# GEMM K-loops: hipcc per-phase s_setprio flips removed, one static s_setprio 1 for the lagging stagger group (waves 4-7) per gemm call, reset at exit (stacked on v12)
# speedup vs baseline: 1.0084x; 1.0064x over previous
; DI int mk_tid(int wv) { int w = wv; asm volatile("" : "+s"(w)); int l = __builtin_amdgcn_mbcnt_hi(~0u, __builtin_amdgcn_mbcnt_lo(~0u, 0u)); asm volatile("" : "+v"(l)); return w * 64 + l; }
; DI int opaque_bid() { int b = blockIdx.x; asm volatile("" : "+s"(b)); return b; }
; #define PG8_STAGE(bufoff, gbase, voff) do { _Pragma("unroll") for (int _i = 0; _i < 2; ++_i) \
;         __builtin_amdgcn_global_load_lds((const unsigned*)((const char*)(gbase) + (voff)[_i]), (LAS unsigned*)(lds + (bufoff) + ldsw + _i * 8192), 16, 0, 0); } while (0)
; #define PG8_BAR __builtin_amdgcn_s_barrier()
; template <class Epi>
; DI void gemm_phase(int wv, LAS unsigned char* lds, const GemmD g, const Epi& E) {
;     const int tid = mk_tid(wv), wid = __builtin_amdgcn_readfirstlane(tid >> 6), lane = tid & 63, wr = wid >> 2, wc = wid & 3, fr = lane & 15, fq = lane >> 4;
;     const int K = g.K, nt = K / BK;
;     const int ldbe = g.ldb * g.dil;
;     unsigned voffA[2], voffB[2];
; #pragma unroll
;     for (int i = 0; i < 2; ++i) { int R, C; stage_rc(tid * 16 + i * 8192, R, C); const int Rb = Epi::PERM ? ((R & ~31) + perm32(R & 31)) : R;
;         voffA[i] = (unsigned)(R * g.lda + C) * 2u; voffB[i] = (unsigned)(Rb * ldbe + C) * 2u; }
;     const size_t kstep = (size_t)(BK * 2);
;     const size_t hstepA = (size_t)HALF * g.lda * 2, hstepB = (size_t)HALF * ldbe * 2;
;     const unsigned ldsw = (unsigned)wid * 1024u;
;     const int aoff = lds_byte(wr * 64 + fr, fq * 8), boff = lds_byte(wc * 32 + fr, fq * 8);
;     ...
;     StaticOrder S; S.init(g.nM, g.nN, (int)gridDim.x, opaque_bid());
;     Unit cur, nxt; int ui = 0;
;     if (!S.next(0, cur)) return;
;     f32x4 acc[2][2][4][2];
; #pragma unroll
;     for (int a = 0; a < 2; ++a)
; #pragma unroll
;         for (int b = 0; b < 2; ++b)
; #pragma unroll
;             for (int m = 0; m < 4; ++m)
; #pragma unroll
;                 for (int n = 0; n < 2; ++n) acc[a][b][m][n] = (f32x4){0.f, 0.f, 0.f, 0.f};
;     bf16x8 At[4][2], B0[2][2], B1[2][2];
;     ...
;     const char* cA = (const char*)g.A + (size_t)cur.pm * 256 * g.lda * 2; const char* cB = (const char*)g.Bt + PG8_BROW(cur.pn) * (size_t)g.ldb * 2;
;     PG8_STAGE(PG8_SB(0, 0), cB, voffB); PG8_STAGE(PG8_SA(0, 0), cA, voffA); PG8_STAGE(PG8_SB(0, 1), cB + hstepB, voffB); PG8_STAGE(PG8_SA(0, 1), cA + hstepA, voffA);
;     if (wr == 1) PG8_BAR;
.LBB0_90:
	s_mov_b32 s1, s68
	v_mov_b32_e32 v3, v232
	s_mov_b32 s13, s55
	v_lshl_add_u32 v0, s1, 6, v3
	s_mul_i32 s56, s0, s30
	s_cmp_ge_i32 s13, s56
	v_readfirstlane_b32 s35, v0
	s_cbranch_scc1 .LBB0_84
	v_lshlrev_b32_e32 v6, 4, v0
	v_add_u32_e32 v4, 0x2000, v6
	v_ashrrev_i32_e32 v2, 31, v4
	v_lshrrev_b32_e32 v2, 22, v2
	v_add_u32_e32 v2, v4, v2
	v_ashrrev_i32_e32 v2, 10, v2
	s_waitcnt lgkmcnt(0)
	v_mul_i32_i24_e32 v5, 0x400, v2
	v_sub_u32_e32 v4, v4, v5
	v_lshrrev_b32_e32 v5, 4, v4
	v_bitop3_b32 v5, v5, v4, 32 bitop3:0x6c
	v_ashrrev_i32_e32 v4, 31, v5
	v_lshrrev_b32_e32 v4, 26, v4
	v_add_u32_e32 v7, v5, v4
	v_lshlrev_b32_e32 v8, 3, v2
	v_ashrrev_i32_e32 v4, 6, v7
	v_and_b32_e32 v8, -16, v8
	v_add_u32_e32 v8, v4, v8
	v_and_b32_e32 v9, 3, v4
	s_mov_b32 s2, 0x3fffe0
	v_lshrrev_b32_e32 v10, 2, v8
	v_lshlrev_b32_e32 v11, 1, v8
	v_and_b32_e32 v7, 0xc0, v7
	v_and_or_b32 v9, v8, s2, v9
	v_and_b32_e32 v10, 4, v10
	v_and_b32_e32 v11, 24, v11
	v_sub_u32_e32 v5, v5, v7
	v_or3_b32 v9, v9, v10, v11
	v_lshlrev_b32_e32 v10, 5, v2
	v_ashrrev_i16_sdwa v5, v244, sext(v5) dst_sel:DWORD dst_unused:UNUSED_PAD src0_sel:DWORD src1_sel:BYTE_0
	s_lshl_b32 s1, s31, 10
	v_and_b32_e32 v10, 32, v10
	v_bfe_i32 v5, v5, 0, 16
	v_mul_u32_u24_e32 v9, s1, v9
	v_add_u32_e32 v7, v10, v5
	v_lshlrev_b32_e32 v8, 11, v8
	v_add_lshl_u32 v130, v9, v7, 1
	v_lshl_add_u32 v132, v7, 1, v8
	v_bfe_i32 v7, v0, 27, 1
	v_lshrrev_b32_e32 v7, 22, v7
	v_add_u32_e32 v7, v6, v7
	v_and_b32_e32 v7, 0xfffffc00, v7
	v_sub_u32_e32 v6, v6, v7
	v_lshrrev_b32_e32 v7, 4, v6
	v_bitop3_b32 v8, v7, v6, 32 bitop3:0x6c
	v_ashrrev_i32_e32 v7, 31, v0
	v_lshrrev_b32_e32 v7, 26, v7
	v_ashrrev_i32_e32 v6, 31, v8
	v_add_u32_e32 v0, v0, v7
	v_lshrrev_b32_e32 v6, 26, v6
	v_ashrrev_i32_e32 v7, 6, v0
	v_add_u32_e32 v9, v8, v6
	v_lshlrev_b32_e32 v0, 3, v7
	v_ashrrev_i32_e32 v6, 6, v9
	v_and_b32_e32 v0, -16, v0
	v_add_u32_e32 v10, v6, v0
	v_and_b32_e32 v0, 3, v6
	v_lshrrev_b32_e32 v11, 2, v10
	v_lshlrev_b32_e32 v12, 1, v10
	v_and_or_b32 v0, v10, s2, v0
	v_and_b32_e32 v11, 4, v11
	v_and_b32_e32 v12, 24, v12
	v_or3_b32 v0, v0, v11, v12
	s_ashr_i32 s39, s13, 31
	v_mul_u32_u24_e32 v0, s1, v0
	s_lshr_b32 s1, s39, 29
	s_add_i32 s1, s13, s1
	s_ashr_i32 s4, s35, 6
	s_lshr_b32 s38, s56, 3
	s_ashr_i32 s14, s1, 3
	s_and_b32 s1, s1, -8
	s_ashr_i32 s5, s35, 8
	s_lshl_b32 s36, s31, 18
	s_lshl_b32 s37, s4, 10
	v_and_b32_e32 v9, 0xc0, v9
	s_sub_i32 s1, s13, s1
	s_or_b32 s40, s38, 1
	v_sub_u32_e32 v8, v8, v9
	s_cmp_lt_i32 s1, 0
	v_lshlrev_b32_e32 v11, 5, v7
	v_ashrrev_i16_sdwa v8, v244, sext(v8) dst_sel:DWORD dst_unused:UNUSED_PAD src0_sel:DWORD src1_sel:BYTE_0
	s_cselect_b32 s15, s40, s38
	s_lshl_b32 s41, s0, 3
	v_and_b32_e32 v11, 32, v11
	v_bfe_i32 v8, v8, 0, 16
	s_abs_i32 s42, s41
	v_add_u32_e32 v9, v11, v8
	v_cvt_f32_u32_e32 v11, s42
	v_lshlrev_b32_e32 v10, 11, v10
	v_add_lshl_u32 v0, v0, v9, 1
	v_lshl_add_u32 v134, v9, 1, v10
	v_rcp_iflag_f32_e32 v9, v11
	s_mul_i32 s1, s15, s1
	s_sub_i32 s15, 0, s42
	s_add_i32 s1, s1, s14
	v_mul_f32_e32 v9, 0x4f7ffffe, v9
	v_cvt_u32_f32_e32 v9, v9
	s_ashr_i32 s14, s1, 31
	s_bfe_i32 s43, s0, 0x1001c
	s_xor_b32 s0, s14, s43
	v_readfirstlane_b32 s44, v9
	s_mul_i32 s15, s15, s44
	s_mul_hi_u32 s15, s44, s15
	s_abs_i32 s14, s1
	s_add_i32 s44, s44, s15
	s_mul_hi_u32 s15, s14, s44
	s_mul_i32 s16, s15, s42
	s_sub_i32 s14, s14, s16
	s_add_i32 s16, s15, 1
	s_sub_i32 s17, s14, s42
	s_cmp_ge_u32 s14, s42
	s_cselect_b32 s15, s16, s15
	s_cselect_b32 s14, s17, s14
	s_add_i32 s16, s15, 1
	s_cmp_ge_u32 s14, s42
	s_cselect_b32 s14, s16, s15
	s_xor_b32 s14, s14, s0
	s_sub_i32 s0, s14, s0
	s_lshl_b32 s14, s0, 3
	s_sub_i32 s15, s30, s14
	s_min_i32 s15, s15, 8
	v_cvt_f32_i32_e32 v9, s15
	s_mul_i32 s0, s0, s41
	s_sub_i32 s16, s1, s0
	v_cvt_f32_i32_e32 v10, s16
	v_rcp_iflag_f32_e32 v11, v9
	s_xor_b32 s0, s16, s15
	s_ashr_i32 s0, s0, 30
	s_or_b32 s17, s0, 1
	v_mul_f32_e32 v11, v10, v11
	v_trunc_f32_e32 v11, v11
	v_fma_f32 v10, -v11, v9, v10
	v_cvt_i32_f32_e32 v11, v11
	v_cmp_ge_f32_e64 s[0:1], |v10|, |v9|
	s_and_b64 s[0:1], s[0:1], exec
	s_cselect_b32 s0, s17, 0
	v_readfirstlane_b32 s1, v11
	s_add_i32 s0, s1, s0
	v_cvt_f32_u32_e32 v10, s34
	s_sext_i32_i16 s55, s0
	s_lshl_b32 s18, s55, 8
	s_and_b32 s19, s18, 0xf00
	v_cvt_f32_u32_e32 v11, s19
	v_rcp_iflag_f32_e32 v9, v10
	s_mul_i32 s0, s0, s15
	s_sub_i32 s0, s16, s0
	s_sext_i32_i16 s0, s0
	v_mul_f32_e32 v12, v11, v9
	v_trunc_f32_e32 v12, v12
	v_cvt_u32_f32_e32 v13, v12
	s_add_i32 s14, s14, s0
	s_ashr_i32 s15, s14, 31
	v_fma_f32 v11, -v12, v10, v11
	s_lshl_b64 s[0:1], s[14:15], 19
	v_cmp_ge_f32_e64 s[16:17], |v11|, v10
	v_readfirstlane_b32 s15, v13
	s_cmp_lg_u64 s[16:17], 0
	s_addc_u32 s15, s15, 0
	s_and_b32 s15, s15, 0xffff
	s_mul_i32 s16, s34, s15
	s_sub_i32 s16, s19, s16
	s_and_b32 s17, s18, 0xfffff000
	s_mul_i32 s16, s16, s31
	s_or_b32 s15, s17, s15
	s_add_i32 s16, s15, s16
	s_ashr_i32 s17, s16, 31
	s_lshl_b64 s[16:17], s[16:17], 11
	s_add_u32 s22, s8, s16
	s_addc_u32 s23, s9, s17
	s_add_i32 s15, s37, 0
	s_add_i32 m0, s15, 0x10000
	s_nop 0
	global_load_lds_dwordx4 v0, s[22:23]
	s_add_i32 m0, s15, 0x12000
	s_add_u32 s24, s6, s0
	global_load_lds_dwordx4 v130, s[22:23]
	s_addc_u32 s25, s7, s1
	s_mov_b32 m0, s15
	s_add_i32 s45, s15, 0x2000
	global_load_lds_dwordx4 v134, s[24:25]
	s_mov_b32 m0, s45
	s_add_u32 s0, s22, s36
	global_load_lds_dwordx4 v132, s[24:25]
	s_addc_u32 s1, s23, 0
	s_add_i32 m0, s15, 0x14000
	s_nop 0
	global_load_lds_dwordx4 v0, s[0:1]
	s_add_i32 m0, s15, 0x16000
	s_add_u32 s16, s24, 0x40000
	s_addc_u32 s17, s25, 0
	s_add_i32 s82, s15, 0x4000
	global_load_lds_dwordx4 v130, s[0:1]
	s_mov_b32 m0, s82
	s_add_i32 s83, s15, 0x6000
	global_load_lds_dwordx4 v134, s[16:17]
	s_mov_b32 m0, s83
	s_cmp_lg_u32 s5, 1
	global_load_lds_dwordx4 v132, s[16:17]
	s_cbranch_scc1 .LBB0_93
	s_setprio 1
	s_barrier

; #define PG8_STAGE(bufoff, gbase, voff) do { _Pragma("unroll") for (int _i = 0; _i < 2; ++_i) \
;         __builtin_amdgcn_global_load_lds((const unsigned*)((const char*)(gbase) + (voff)[_i]), (LAS unsigned*)(lds + (bufoff) + ldsw + _i * 8192), 16, 0, 0); } while (0)
; #define PG8_LDA(dst, b, h) do { _Pragma("unroll") for (int m = 0; m < 4; ++m) _Pragma("unroll") for (int k = 0; k < 2; ++k) dst[m][k] = *(const LAS bf16x8*)(lds + PG8_SA(b, h) + aoff + m * 2048 + k * 1024); } while (0)
; #define PG8_LDB(dst, b, h) do { _Pragma("unroll") for (int n = 0; n < 2; ++n) _Pragma("unroll") for (int k = 0; k < 2; ++k) dst[n][k] = *(const LAS bf16x8*)(lds + PG8_SB(b, h) + boff + n * 2048 + k * 1024); } while (0)
; #define PG8_MMA(ai, bj, At, Bt) do { __builtin_amdgcn_s_setprio(1); _Pragma("unroll") for (int m = 0; m < 4; ++m) _Pragma("unroll") for (int n = 0; n < 2; ++n) _Pragma("unroll") for (int k = 0; k < 2; ++k) \
;         acc[ai][bj][m][n] = __builtin_amdgcn_mfma_f32_16x16x32_bf16(Bt[n][k], At[m][k], acc[ai][bj][m][n], 0, 0, 0); __builtin_amdgcn_s_setprio(0); } while (0)
; #define PG8_WAIT_L(n) asm volatile("s_waitcnt lgkmcnt(" #n ")" ::: "memory")
; template <class Epi>
; DI void gemm_phase(int wv, LAS unsigned char* lds, const GemmD g, const Epi& E) {
;     ...
;         const bool has_next = S.next(ui + 1, nxt);
;         const char* nA = has_next ? (const char*)g.A + (size_t)nxt.pm * 256 * g.lda * 2 : cA; const char* nB = has_next ? (const char*)g.Bt + PG8_BROW(nxt.pn) * (size_t)g.ldb * 2 : cB;
;         for (int t = 0; t < nt; t += 2) {
;             const bool last = (t == nt - 2);
;             const char* a1 = cA + (size_t)(t + 1) * kstep;
;             const char* a2 = last ? nA : cA + (size_t)(t + 2) * kstep; const char* b2 = last ? nB : cB + (size_t)(t + 2) * kstep;
;             const char* a3 = a2 + kstep; const char* b3 = b2 + kstep;
;             PG8_LDB(B0, 0, 0); PG8_SCHED; PG8_LDA(At, 0, 0); PG8_STAGE(PG8_SA(1, 1), a1 + hstepA, voffA);
;             PG8_WAIT_L(8); PG8_BAR; PG8_WAIT_L(0); PG8_MMA(0, 0, At, B0); PG8_BAR; PG8_SCHED;
;             PG8_LDB(B1, 0, 1); PG8_STAGE(PG8_SB(0, 0), b2, voffB);
;             PG8_BAR; PG8_WAIT_L(0); PG8_MMA(0, 1, At, B1); PG8_BAR;
;             PG8_LDA(At, 0, 1); PG8_STAGE(PG8_SA(0, 0), a2, voffA);
;             PG8_BAR; PG8_WAIT_L(0); PG8_MMA(1, 0, At, B0); PG8_BAR; PG8_SCHED;
.LBB0_98:
	s_ashr_i32 s17, s16, 31
	s_lshl_b64 s[20:21], s[16:17], 19
	s_add_u32 s20, s6, s20
	s_addc_u32 s21, s7, s21
	s_and_b64 s[4:5], s[4:5], exec
	s_cselect_b32 s17, s21, s25
	s_cselect_b32 vcc_lo, s20, s24
	s_add_u32 s4, s24, 0x40080
	s_addc_u32 s5, s25, 0
	s_add_u32 vcc_hi, s22, 0x100
	s_addc_u32 s75, s23, 0
	s_mov_b32 s95, -2
	s_add_u32 s22, s4, 0xfffc0080
	s_addc_u32 s23, s5, -1
	s_add_i32 s3, 0, 0x10000
	v_add_u32_e32 v156, s3, v141
	ds_read_b128 v[144:147], v156
	ds_read_b128 v[148:151], v156 offset:1024
	ds_read_b128 v[152:155], v156 offset:2048
	ds_read_b128 v[156:159], v156 offset:3072
	s_cmp_eq_u32 s95, 12
	s_cselect_b32 s23, s17, s23
	s_cselect_b32 s22, vcc_lo, s22
	s_cselect_b32 s25, s19, s75
	s_cselect_b32 s24, s18, vcc_hi
	v_lshl_add_u64 v[164:165], s[4:5], 0, v[136:137]
	s_add_i32 m0, s15, 0xc000
	ds_read_b128 v[160:163], v143
	ds_read_b128 v[176:179], v143 offset:1024
	ds_read_b128 v[180:183], v143 offset:2048
	ds_read_b128 v[184:187], v143 offset:3072
	ds_read_b128 v[188:191], v143 offset:4096
	ds_read_b128 v[192:195], v143 offset:5120
	ds_read_b128 v[196:199], v143 offset:6144
	ds_read_b128 v[200:203], v143 offset:7168
	global_load_lds_dwordx4 v[164:165], off
	v_lshl_add_u64 v[164:165], s[4:5], 0, v[138:139]
	s_add_i32 m0, s15, 0xe000
	s_nop 0
	global_load_lds_dwordx4 v[164:165], off
	s_waitcnt lgkmcnt(8)
	s_barrier
	s_waitcnt lgkmcnt(0)
	s_waitcnt lgkmcnt(0)
	v_mfma_f32_16x16x32_bf16 v[126:129], v[144:147], v[160:163], 0
	v_mfma_f32_16x16x32_bf16 v[122:125], v[152:155], v[160:163], 0
	v_mfma_f32_16x16x32_bf16 v[118:121], v[144:147], v[180:183], 0
	v_mfma_f32_16x16x32_bf16 v[114:117], v[152:155], v[180:183], 0
	v_mfma_f32_16x16x32_bf16 v[102:105], v[144:147], v[188:191], 0
	v_mfma_f32_16x16x32_bf16 v[98:101], v[152:155], v[188:191], 0
	v_mfma_f32_16x16x32_bf16 v[86:89], v[144:147], v[196:199], 0
	v_mfma_f32_16x16x32_bf16 v[82:85], v[152:155], v[196:199], 0
	v_mfma_f32_16x16x32_bf16 v[126:129], v[148:151], v[176:179], v[126:129]
	v_mfma_f32_16x16x32_bf16 v[122:125], v[156:159], v[176:179], v[122:125]
	v_mfma_f32_16x16x32_bf16 v[118:121], v[148:151], v[184:187], v[118:121]
	v_mfma_f32_16x16x32_bf16 v[114:117], v[156:159], v[184:187], v[114:117]
	v_mfma_f32_16x16x32_bf16 v[102:105], v[148:151], v[192:195], v[102:105]
	v_mfma_f32_16x16x32_bf16 v[98:101], v[156:159], v[192:195], v[98:101]
	v_mfma_f32_16x16x32_bf16 v[86:89], v[148:151], v[200:203], v[86:89]
	v_mfma_f32_16x16x32_bf16 v[82:85], v[156:159], v[200:203], v[82:85]
	s_barrier
	s_add_i32 s2, 0, 0x14000
	v_add_u32_e32 v164, s2, v141
	s_add_i32 s3, s3, s37
	ds_read_b128 v[204:207], v164
	ds_read_b128 v[208:211], v164 offset:1024
	ds_read_b128 v[212:215], v164 offset:2048
	ds_read_b128 v[216:219], v164 offset:3072
	v_lshl_add_u64 v[164:165], s[24:25], 0, v[0:1]
	s_mov_b32 m0, s3
	v_lshl_add_u64 v[168:169], s[24:25], 0, v[130:131]
	global_load_lds_dwordx4 v[164:165], off
	s_add_i32 m0, s3, 0x2000
	s_nop 0
	global_load_lds_dwordx4 v[168:169], off
	s_barrier
	s_waitcnt lgkmcnt(0)
	s_waitcnt lgkmcnt(0)
	v_mfma_f32_16x16x32_bf16 v[110:113], v[204:207], v[160:163], 0
	v_mfma_f32_16x16x32_bf16 v[106:109], v[212:215], v[160:163], 0
	v_mfma_f32_16x16x32_bf16 v[94:97], v[204:207], v[180:183], 0
	v_mfma_f32_16x16x32_bf16 v[90:93], v[212:215], v[180:183], 0
	v_mfma_f32_16x16x32_bf16 v[78:81], v[204:207], v[188:191], 0
	v_mfma_f32_16x16x32_bf16 v[74:77], v[212:215], v[188:191], 0
	v_mfma_f32_16x16x32_bf16 v[70:73], v[204:207], v[196:199], 0
	v_mfma_f32_16x16x32_bf16 v[66:69], v[212:215], v[196:199], 0
	v_mfma_f32_16x16x32_bf16 v[110:113], v[208:211], v[176:179], v[110:113]
	v_mfma_f32_16x16x32_bf16 v[106:109], v[216:219], v[176:179], v[106:109]
	v_mfma_f32_16x16x32_bf16 v[94:97], v[208:211], v[184:187], v[94:97]
	v_mfma_f32_16x16x32_bf16 v[90:93], v[216:219], v[184:187], v[90:93]
	v_mfma_f32_16x16x32_bf16 v[78:81], v[208:211], v[192:195], v[78:81]
	v_mfma_f32_16x16x32_bf16 v[74:77], v[216:219], v[192:195], v[74:77]
	v_mfma_f32_16x16x32_bf16 v[70:73], v[208:211], v[200:203], v[70:73]
	v_mfma_f32_16x16x32_bf16 v[66:69], v[216:219], v[200:203], v[66:69]
	s_mov_b32 m0, s15
	v_lshl_add_u64 v[170:171], s[22:23], 0, v[134:135]
	s_barrier
	ds_read_b128 v[160:163], v143 offset:16384
	ds_read_b128 v[176:179], v143 offset:17408
	ds_read_b128 v[180:183], v143 offset:18432
	ds_read_b128 v[184:187], v143 offset:19456
	ds_read_b128 v[188:191], v143 offset:20480
	ds_read_b128 v[192:195], v143 offset:21504
	ds_read_b128 v[196:199], v143 offset:22528
	ds_read_b128 v[200:203], v143 offset:23552
	global_load_lds_dwordx4 v[170:171], off
	v_lshl_add_u64 v[220:221], s[22:23], 0, v[132:133]
	s_mov_b32 m0, s45
	s_nop 0
	global_load_lds_dwordx4 v[220:221], off
	s_barrier
	s_waitcnt lgkmcnt(0)
	s_waitcnt lgkmcnt(0)
	v_mfma_f32_16x16x32_bf16 v[62:65], v[144:147], v[160:163], 0
	v_mfma_f32_16x16x32_bf16 v[58:61], v[152:155], v[160:163], 0
	v_mfma_f32_16x16x32_bf16 v[54:57], v[144:147], v[180:183], 0
	v_mfma_f32_16x16x32_bf16 v[50:53], v[152:155], v[180:183], 0
	v_mfma_f32_16x16x32_bf16 v[38:41], v[144:147], v[188:191], 0
	v_mfma_f32_16x16x32_bf16 v[34:37], v[152:155], v[188:191], 0
	v_mfma_f32_16x16x32_bf16 v[22:25], v[144:147], v[196:199], 0
	v_mfma_f32_16x16x32_bf16 v[18:21], v[152:155], v[196:199], 0
	v_mfma_f32_16x16x32_bf16 v[62:65], v[148:151], v[176:179], v[62:65]
	v_mfma_f32_16x16x32_bf16 v[58:61], v[156:159], v[176:179], v[58:61]
	v_mfma_f32_16x16x32_bf16 v[54:57], v[148:151], v[184:187], v[54:57]
	v_mfma_f32_16x16x32_bf16 v[50:53], v[156:159], v[184:187], v[50:53]
	v_mfma_f32_16x16x32_bf16 v[38:41], v[148:151], v[192:195], v[38:41]
	v_mfma_f32_16x16x32_bf16 v[34:37], v[156:159], v[192:195], v[34:37]
	v_mfma_f32_16x16x32_bf16 v[22:25], v[148:151], v[200:203], v[22:25]
	v_mfma_f32_16x16x32_bf16 v[18:21], v[156:159], v[200:203], v[18:21]
	s_barrier
; #define PG8_STAGE(bufoff, gbase, voff) do { _Pragma("unroll") for (int _i = 0; _i < 2; ++_i) \
;         __builtin_amdgcn_global_load_lds((const unsigned*)((const char*)(gbase) + (voff)[_i]), (LAS unsigned*)(lds + (bufoff) + ldsw + _i * 8192), 16, 0, 0); } while (0)
; #define PG8_LDA(dst, b, h) do { _Pragma("unroll") for (int m = 0; m < 4; ++m) _Pragma("unroll") for (int k = 0; k < 2; ++k) dst[m][k] = *(const LAS bf16x8*)(lds + PG8_SA(b, h) + aoff + m * 2048 + k * 1024); } while (0)
; #define PG8_LDB(dst, b, h) do { _Pragma("unroll") for (int n = 0; n < 2; ++n) _Pragma("unroll") for (int k = 0; k < 2; ++k) dst[n][k] = *(const LAS bf16x8*)(lds + PG8_SB(b, h) + boff + n * 2048 + k * 1024); } while (0)
; #define PG8_MMA(ai, bj, At, Bt) do { __builtin_amdgcn_s_setprio(1); _Pragma("unroll") for (int m = 0; m < 4; ++m) _Pragma("unroll") for (int n = 0; n < 2; ++n) _Pragma("unroll") for (int k = 0; k < 2; ++k) \
;         acc[ai][bj][m][n] = __builtin_amdgcn_mfma_f32_16x16x32_bf16(Bt[n][k], At[m][k], acc[ai][bj][m][n], 0, 0, 0); __builtin_amdgcn_s_setprio(0); } while (0)
; #define PG8_WAIT_V(n) asm volatile("s_waitcnt vmcnt(" #n ")" ::: "memory")
; #define PG8_WAIT_L(n) asm volatile("s_waitcnt lgkmcnt(" #n ")" ::: "memory")
; #define PG8_BAR __builtin_amdgcn_s_barrier()
; #define PG8_SCHED __builtin_amdgcn_sched_barrier(0)
; template <class Epi>
; DI void gemm_phase(int wv, LAS unsigned char* lds, const GemmD g, const Epi& E) {
;     ...
;             PG8_STAGE(PG8_SB(0, 1), b2 + hstepB, voffB);
;             PG8_WAIT_V(6); PG8_BAR; PG8_MMA(1, 1, At, B1); PG8_BAR;
;             PG8_LDB(B0, 1, 0); PG8_SCHED; PG8_LDA(At, 1, 0); PG8_STAGE(PG8_SA(0, 1), a2 + hstepA, voffA);
;             PG8_WAIT_L(8); PG8_BAR; PG8_WAIT_L(0); PG8_MMA(0, 0, At, B0); PG8_BAR; PG8_SCHED;
;             PG8_LDB(B1, 1, 1); PG8_STAGE(PG8_SB(1, 0), b3, voffB);
;             PG8_BAR; PG8_WAIT_L(0); PG8_MMA(0, 1, At, B1); PG8_BAR;
;             PG8_LDA(At, 1, 1); PG8_STAGE(PG8_SA(1, 0), a3, voffA);
	s_add_u32 s24, s24, s36
	s_addc_u32 s25, s25, 0
	s_add_i32 s2, s2, s37
	v_lshl_add_u64 v[222:223], s[24:25], 0, v[0:1]
	s_mov_b32 m0, s2
	v_lshl_add_u64 v[224:225], s[24:25], 0, v[130:131]
	global_load_lds_dwordx4 v[222:223], off
	s_add_i32 m0, s2, 0x2000
	s_nop 0
	global_load_lds_dwordx4 v[224:225], off
	s_waitcnt vmcnt(6)
	s_barrier
	v_mfma_f32_16x16x32_bf16 v[46:49], v[204:207], v[160:163], 0
	v_mfma_f32_16x16x32_bf16 v[42:45], v[212:215], v[160:163], 0
	v_mfma_f32_16x16x32_bf16 v[30:33], v[204:207], v[180:183], 0
	v_mfma_f32_16x16x32_bf16 v[26:29], v[212:215], v[180:183], 0
	v_mfma_f32_16x16x32_bf16 v[14:17], v[204:207], v[188:191], 0
	v_mfma_f32_16x16x32_bf16 v[10:13], v[212:215], v[188:191], 0
	v_mfma_f32_16x16x32_bf16 v[6:9], v[204:207], v[196:199], 0
	v_mfma_f32_16x16x32_bf16 v[2:5], v[212:215], v[196:199], 0
	v_mfma_f32_16x16x32_bf16 v[46:49], v[208:211], v[176:179], v[46:49]
	v_mfma_f32_16x16x32_bf16 v[42:45], v[216:219], v[176:179], v[42:45]
	v_mfma_f32_16x16x32_bf16 v[30:33], v[208:211], v[184:187], v[30:33]
	v_mfma_f32_16x16x32_bf16 v[26:29], v[216:219], v[184:187], v[26:29]
	v_mfma_f32_16x16x32_bf16 v[14:17], v[208:211], v[192:195], v[14:17]
	v_mfma_f32_16x16x32_bf16 v[10:13], v[216:219], v[192:195], v[10:13]
	v_mfma_f32_16x16x32_bf16 v[6:9], v[208:211], v[200:203], v[6:9]
	v_mfma_f32_16x16x32_bf16 v[2:5], v[216:219], v[200:203], v[2:5]
	s_add_i32 s2, 0, 0x18000
	v_add_u32_e32 v156, s2, v141
	s_barrier
	ds_read_b128 v[144:147], v156
	ds_read_b128 v[148:151], v156 offset:1024
	ds_read_b128 v[152:155], v156 offset:2048
	ds_read_b128 v[156:159], v156 offset:3072
	s_add_u32 s22, s22, 0x40000
	s_addc_u32 s23, s23, 0
	s_mov_b32 m0, s82
	v_lshl_add_u64 v[204:205], s[22:23], 0, v[134:135]
	ds_read_b128 v[160:163], v143 offset:32768
	ds_read_b128 v[176:179], v143 offset:33792
	ds_read_b128 v[180:183], v143 offset:34816
	ds_read_b128 v[184:187], v143 offset:35840
	ds_read_b128 v[188:191], v143 offset:36864
	ds_read_b128 v[192:195], v143 offset:37888
	ds_read_b128 v[196:199], v143 offset:38912
	ds_read_b128 v[200:203], v143 offset:39936
	global_load_lds_dwordx4 v[204:205], off
	v_lshl_add_u64 v[204:205], s[22:23], 0, v[132:133]
	s_mov_b32 m0, s83
	s_nop 0
	global_load_lds_dwordx4 v[204:205], off
	s_waitcnt lgkmcnt(8)
	s_barrier
	s_waitcnt lgkmcnt(0)
	s_waitcnt lgkmcnt(0)
	v_mfma_f32_16x16x32_bf16 v[126:129], v[144:147], v[160:163], v[126:129]
	v_mfma_f32_16x16x32_bf16 v[122:125], v[152:155], v[160:163], v[122:125]
	v_mfma_f32_16x16x32_bf16 v[118:121], v[144:147], v[180:183], v[118:121]
	v_mfma_f32_16x16x32_bf16 v[114:117], v[152:155], v[180:183], v[114:117]
	v_mfma_f32_16x16x32_bf16 v[102:105], v[144:147], v[188:191], v[102:105]
	v_mfma_f32_16x16x32_bf16 v[98:101], v[152:155], v[188:191], v[98:101]
	v_mfma_f32_16x16x32_bf16 v[86:89], v[144:147], v[196:199], v[86:89]
	v_mfma_f32_16x16x32_bf16 v[82:85], v[152:155], v[196:199], v[82:85]
	v_mfma_f32_16x16x32_bf16 v[126:129], v[148:151], v[176:179], v[126:129]
	v_mfma_f32_16x16x32_bf16 v[122:125], v[156:159], v[176:179], v[122:125]
	v_mfma_f32_16x16x32_bf16 v[118:121], v[148:151], v[184:187], v[118:121]
	v_mfma_f32_16x16x32_bf16 v[114:117], v[156:159], v[184:187], v[114:117]
	v_mfma_f32_16x16x32_bf16 v[102:105], v[148:151], v[192:195], v[102:105]
	v_mfma_f32_16x16x32_bf16 v[98:101], v[156:159], v[192:195], v[98:101]
	v_mfma_f32_16x16x32_bf16 v[86:89], v[148:151], v[200:203], v[86:89]
	v_mfma_f32_16x16x32_bf16 v[82:85], v[156:159], v[200:203], v[82:85]
	s_barrier
	s_add_i32 s3, 0, 0x1c000
	s_add_i32 s2, s2, s37
	v_add_u32_e32 v216, s3, v141
	v_lshl_add_u64 v[164:165], v[164:165], 0, s[58:59]
	s_mov_b32 m0, s2
	ds_read_b128 v[204:207], v216
	ds_read_b128 v[208:211], v216 offset:1024
	ds_read_b128 v[212:215], v216 offset:2048
	ds_read_b128 v[216:219], v216 offset:3072
	global_load_lds_dwordx4 v[164:165], off
	v_lshl_add_u64 v[164:165], v[168:169], 0, s[58:59]
	s_add_i32 m0, s2, 0x2000
	s_nop 0
	global_load_lds_dwordx4 v[164:165], off
	s_barrier
	s_waitcnt lgkmcnt(0)
	s_waitcnt lgkmcnt(0)
	v_mfma_f32_16x16x32_bf16 v[110:113], v[204:207], v[160:163], v[110:113]
	v_mfma_f32_16x16x32_bf16 v[106:109], v[212:215], v[160:163], v[106:109]
	v_mfma_f32_16x16x32_bf16 v[94:97], v[204:207], v[180:183], v[94:97]
	v_mfma_f32_16x16x32_bf16 v[90:93], v[212:215], v[180:183], v[90:93]
	v_mfma_f32_16x16x32_bf16 v[78:81], v[204:207], v[188:191], v[78:81]
	v_mfma_f32_16x16x32_bf16 v[74:77], v[212:215], v[188:191], v[74:77]
	v_mfma_f32_16x16x32_bf16 v[70:73], v[204:207], v[196:199], v[70:73]
	v_mfma_f32_16x16x32_bf16 v[66:69], v[212:215], v[196:199], v[66:69]
	v_mfma_f32_16x16x32_bf16 v[110:113], v[208:211], v[176:179], v[110:113]
	v_mfma_f32_16x16x32_bf16 v[106:109], v[216:219], v[176:179], v[106:109]
	v_mfma_f32_16x16x32_bf16 v[94:97], v[208:211], v[184:187], v[94:97]
	v_mfma_f32_16x16x32_bf16 v[90:93], v[216:219], v[184:187], v[90:93]
	v_mfma_f32_16x16x32_bf16 v[78:81], v[208:211], v[192:195], v[78:81]
	v_mfma_f32_16x16x32_bf16 v[74:77], v[216:219], v[192:195], v[74:77]
	v_mfma_f32_16x16x32_bf16 v[70:73], v[208:211], v[200:203], v[70:73]
	v_mfma_f32_16x16x32_bf16 v[66:69], v[216:219], v[200:203], v[66:69]
	s_mov_b32 m0, s84
	v_lshl_add_u64 v[164:165], v[170:171], 0, s[58:59]
	s_barrier
	ds_read_b128 v[160:163], v143 offset:49152
	ds_read_b128 v[176:179], v143 offset:50176
	ds_read_b128 v[180:183], v143 offset:51200
	ds_read_b128 v[184:187], v143 offset:52224
	ds_read_b128 v[188:191], v143 offset:53248
	ds_read_b128 v[192:195], v143 offset:54272
	ds_read_b128 v[196:199], v143 offset:55296
	ds_read_b128 v[200:203], v143 offset:56320
	global_load_lds_dwordx4 v[164:165], off
	v_lshl_add_u64 v[164:165], v[220:221], 0, s[58:59]
	s_mov_b32 m0, s85
	s_nop 0
	global_load_lds_dwordx4 v[164:165], off
	s_barrier
; #define PG8_STAGE(bufoff, gbase, voff) do { _Pragma("unroll") for (int _i = 0; _i < 2; ++_i) \
;         __builtin_amdgcn_global_load_lds((const unsigned*)((const char*)(gbase) + (voff)[_i]), (LAS unsigned*)(lds + (bufoff) + ldsw + _i * 8192), 16, 0, 0); } while (0)
; #define PG8_LDA(dst, b, h) do { _Pragma("unroll") for (int m = 0; m < 4; ++m) _Pragma("unroll") for (int k = 0; k < 2; ++k) dst[m][k] = *(const LAS bf16x8*)(lds + PG8_SA(b, h) + aoff + m * 2048 + k * 1024); } while (0)
; #define PG8_LDB(dst, b, h) do { _Pragma("unroll") for (int n = 0; n < 2; ++n) _Pragma("unroll") for (int k = 0; k < 2; ++k) dst[n][k] = *(const LAS bf16x8*)(lds + PG8_SB(b, h) + boff + n * 2048 + k * 1024); } while (0)
; #define PG8_MMA(ai, bj, At, Bt) do { __builtin_amdgcn_s_setprio(1); _Pragma("unroll") for (int m = 0; m < 4; ++m) _Pragma("unroll") for (int n = 0; n < 2; ++n) _Pragma("unroll") for (int k = 0; k < 2; ++k) \
;         acc[ai][bj][m][n] = __builtin_amdgcn_mfma_f32_16x16x32_bf16(Bt[n][k], At[m][k], acc[ai][bj][m][n], 0, 0, 0); __builtin_amdgcn_s_setprio(0); } while (0)
; #define PG8_WAIT_V(n) asm volatile("s_waitcnt vmcnt(" #n ")" ::: "memory")
; #define PG8_WAIT_L(n) asm volatile("s_waitcnt lgkmcnt(" #n ")" ::: "memory")
; #define PG8_BAR __builtin_amdgcn_s_barrier()
; #define PG8_SCHED __builtin_amdgcn_sched_barrier(0)
; template <class Epi>
; DI void gemm_phase(int wv, LAS unsigned char* lds, const GemmD g, const Epi& E) {
;     ...
;         for (int t = 0; t < nt; t += 2) {
;             const bool last = (t == nt - 2);
;             const char* a1 = cA + (size_t)(t + 1) * kstep;
;             const char* a2 = last ? nA : cA + (size_t)(t + 2) * kstep; const char* b2 = last ? nB : cB + (size_t)(t + 2) * kstep;
;             const char* a3 = a2 + kstep; const char* b3 = b2 + kstep;
;             PG8_LDB(B0, 0, 0); PG8_SCHED; PG8_LDA(At, 0, 0); PG8_STAGE(PG8_SA(1, 1), a1 + hstepA, voffA);
;             PG8_WAIT_L(8); PG8_BAR; PG8_WAIT_L(0); PG8_MMA(0, 0, At, B0); PG8_BAR; PG8_SCHED;
;     ...
;             PG8_BAR; PG8_WAIT_L(0); PG8_MMA(1, 0, At, B0); PG8_BAR; PG8_SCHED;
;             PG8_STAGE(PG8_SB(1, 1), b3 + hstepB, voffB);
;             PG8_WAIT_V(6); PG8_BAR; PG8_MMA(1, 1, At, B1); PG8_BAR;
	s_waitcnt lgkmcnt(0)
	s_waitcnt lgkmcnt(0)
	v_mfma_f32_16x16x32_bf16 v[62:65], v[144:147], v[160:163], v[62:65]
	v_mfma_f32_16x16x32_bf16 v[58:61], v[152:155], v[160:163], v[58:61]
	v_mfma_f32_16x16x32_bf16 v[54:57], v[144:147], v[180:183], v[54:57]
	v_mfma_f32_16x16x32_bf16 v[50:53], v[152:155], v[180:183], v[50:53]
	v_mfma_f32_16x16x32_bf16 v[38:41], v[144:147], v[188:191], v[38:41]
	v_mfma_f32_16x16x32_bf16 v[34:37], v[152:155], v[188:191], v[34:37]
	v_mfma_f32_16x16x32_bf16 v[22:25], v[144:147], v[196:199], v[22:25]
	v_mfma_f32_16x16x32_bf16 v[18:21], v[152:155], v[196:199], v[18:21]
	v_mfma_f32_16x16x32_bf16 v[62:65], v[148:151], v[176:179], v[62:65]
	v_mfma_f32_16x16x32_bf16 v[58:61], v[156:159], v[176:179], v[58:61]
	v_mfma_f32_16x16x32_bf16 v[54:57], v[148:151], v[184:187], v[54:57]
	v_mfma_f32_16x16x32_bf16 v[50:53], v[156:159], v[184:187], v[50:53]
	v_mfma_f32_16x16x32_bf16 v[38:41], v[148:151], v[192:195], v[38:41]
	v_mfma_f32_16x16x32_bf16 v[34:37], v[156:159], v[192:195], v[34:37]
	v_mfma_f32_16x16x32_bf16 v[22:25], v[148:151], v[200:203], v[22:25]
	v_mfma_f32_16x16x32_bf16 v[18:21], v[156:159], v[200:203], v[18:21]
	s_barrier
	s_add_i32 s2, s3, s37
	v_lshl_add_u64 v[144:145], v[222:223], 0, s[58:59]
	s_mov_b32 m0, s2
	s_nop 0
	global_load_lds_dwordx4 v[144:145], off
	v_lshl_add_u64 v[144:145], v[224:225], 0, s[58:59]
	s_add_i32 m0, s2, 0x2000
	s_nop 0
	global_load_lds_dwordx4 v[144:145], off
	s_waitcnt vmcnt(6)
	s_barrier
	v_mfma_f32_16x16x32_bf16 v[46:49], v[204:207], v[160:163], v[46:49]
	v_mfma_f32_16x16x32_bf16 v[42:45], v[212:215], v[160:163], v[42:45]
	v_mfma_f32_16x16x32_bf16 v[30:33], v[204:207], v[180:183], v[30:33]
	v_mfma_f32_16x16x32_bf16 v[26:29], v[212:215], v[180:183], v[26:29]
	v_mfma_f32_16x16x32_bf16 v[14:17], v[204:207], v[188:191], v[14:17]
	v_mfma_f32_16x16x32_bf16 v[10:13], v[212:215], v[188:191], v[10:13]
	v_mfma_f32_16x16x32_bf16 v[6:9], v[204:207], v[196:199], v[6:9]
	v_mfma_f32_16x16x32_bf16 v[2:5], v[212:215], v[196:199], v[2:5]
	v_mfma_f32_16x16x32_bf16 v[46:49], v[208:211], v[176:179], v[46:49]
	v_mfma_f32_16x16x32_bf16 v[42:45], v[216:219], v[176:179], v[42:45]
	v_mfma_f32_16x16x32_bf16 v[30:33], v[208:211], v[184:187], v[30:33]
	v_mfma_f32_16x16x32_bf16 v[26:29], v[216:219], v[184:187], v[26:29]
	v_mfma_f32_16x16x32_bf16 v[14:17], v[208:211], v[192:195], v[14:17]
	v_mfma_f32_16x16x32_bf16 v[10:13], v[216:219], v[192:195], v[10:13]
	v_mfma_f32_16x16x32_bf16 v[6:9], v[208:211], v[200:203], v[6:9]
	v_mfma_f32_16x16x32_bf16 v[2:5], v[216:219], v[200:203], v[2:5]
	s_add_i32 s95, s95, 2
	s_add_u32 s4, s4, 0x100
	s_addc_u32 s5, s5, 0
	s_add_u32 vcc_hi, vcc_hi, 0x100
	s_addc_u32 s75, s75, 0
	s_cmp_gt_u32 s95, 13
	s_barrier
	s_cbranch_scc0 .LBB0_99
	s_branch .Lgemm_epi_a
.LBB0_99:
	s_add_u32 s22, s4, 0xfffc0080
	s_addc_u32 s23, s5, -1
	s_add_i32 s3, 0, 0x10000
	v_add_u32_e32 v156, s3, v141
	ds_read_b128 v[144:147], v156
	ds_read_b128 v[148:151], v156 offset:1024
	ds_read_b128 v[152:155], v156 offset:2048
	ds_read_b128 v[156:159], v156 offset:3072
	s_cmp_eq_u32 s95, 12
	s_cselect_b32 s23, s17, s23
	s_cselect_b32 s22, vcc_lo, s22
	s_cselect_b32 s25, s19, s75
	s_cselect_b32 s24, s18, vcc_hi
	v_lshl_add_u64 v[164:165], s[4:5], 0, v[136:137]
	s_add_i32 m0, s15, 0xc000
	ds_read_b128 v[160:163], v143
	ds_read_b128 v[176:179], v143 offset:1024
	ds_read_b128 v[180:183], v143 offset:2048
	ds_read_b128 v[184:187], v143 offset:3072
	ds_read_b128 v[188:191], v143 offset:4096
	ds_read_b128 v[192:195], v143 offset:5120
	ds_read_b128 v[196:199], v143 offset:6144
	ds_read_b128 v[200:203], v143 offset:7168
	global_load_lds_dwordx4 v[164:165], off
	v_lshl_add_u64 v[164:165], s[4:5], 0, v[138:139]
	s_add_i32 m0, s15, 0xe000
	s_nop 0
	global_load_lds_dwordx4 v[164:165], off
	s_waitcnt lgkmcnt(8)
	s_barrier
	s_waitcnt lgkmcnt(0)
	s_waitcnt lgkmcnt(0)
	v_mfma_f32_16x16x32_bf16 v[126:129], v[144:147], v[160:163], v[126:129]
	v_mfma_f32_16x16x32_bf16 v[122:125], v[152:155], v[160:163], v[122:125]
	v_mfma_f32_16x16x32_bf16 v[118:121], v[144:147], v[180:183], v[118:121]
	v_mfma_f32_16x16x32_bf16 v[114:117], v[152:155], v[180:183], v[114:117]
	v_mfma_f32_16x16x32_bf16 v[102:105], v[144:147], v[188:191], v[102:105]
	v_mfma_f32_16x16x32_bf16 v[98:101], v[152:155], v[188:191], v[98:101]
	v_mfma_f32_16x16x32_bf16 v[86:89], v[144:147], v[196:199], v[86:89]
	v_mfma_f32_16x16x32_bf16 v[82:85], v[152:155], v[196:199], v[82:85]
	v_mfma_f32_16x16x32_bf16 v[126:129], v[148:151], v[176:179], v[126:129]
	v_mfma_f32_16x16x32_bf16 v[122:125], v[156:159], v[176:179], v[122:125]
	v_mfma_f32_16x16x32_bf16 v[118:121], v[148:151], v[184:187], v[118:121]
	v_mfma_f32_16x16x32_bf16 v[114:117], v[156:159], v[184:187], v[114:117]
	v_mfma_f32_16x16x32_bf16 v[102:105], v[148:151], v[192:195], v[102:105]
	v_mfma_f32_16x16x32_bf16 v[98:101], v[156:159], v[192:195], v[98:101]
	v_mfma_f32_16x16x32_bf16 v[86:89], v[148:151], v[200:203], v[86:89]
	v_mfma_f32_16x16x32_bf16 v[82:85], v[156:159], v[200:203], v[82:85]
	s_barrier
	s_add_i32 s2, 0, 0x14000
	v_add_u32_e32 v164, s2, v141
	s_add_i32 s3, s3, s37
	ds_read_b128 v[204:207], v164
	ds_read_b128 v[208:211], v164 offset:1024
	ds_read_b128 v[212:215], v164 offset:2048
	ds_read_b128 v[216:219], v164 offset:3072
	v_lshl_add_u64 v[164:165], s[24:25], 0, v[0:1]
	s_mov_b32 m0, s3
	v_lshl_add_u64 v[168:169], s[24:25], 0, v[130:131]
	global_load_lds_dwordx4 v[164:165], off
	s_add_i32 m0, s3, 0x2000
	s_nop 0
	global_load_lds_dwordx4 v[168:169], off
	s_barrier
; #define PG8_STAGE(bufoff, gbase, voff) do { _Pragma("unroll") for (int _i = 0; _i < 2; ++_i) \
;         __builtin_amdgcn_global_load_lds((const unsigned*)((const char*)(gbase) + (voff)[_i]), (LAS unsigned*)(lds + (bufoff) + ldsw + _i * 8192), 16, 0, 0); } while (0)
; #define PG8_LDA(dst, b, h) do { _Pragma("unroll") for (int m = 0; m < 4; ++m) _Pragma("unroll") for (int k = 0; k < 2; ++k) dst[m][k] = *(const LAS bf16x8*)(lds + PG8_SA(b, h) + aoff + m * 2048 + k * 1024); } while (0)
; #define PG8_LDB(dst, b, h) do { _Pragma("unroll") for (int n = 0; n < 2; ++n) _Pragma("unroll") for (int k = 0; k < 2; ++k) dst[n][k] = *(const LAS bf16x8*)(lds + PG8_SB(b, h) + boff + n * 2048 + k * 1024); } while (0)
; #define PG8_MMA(ai, bj, At, Bt) do { __builtin_amdgcn_s_setprio(1); _Pragma("unroll") for (int m = 0; m < 4; ++m) _Pragma("unroll") for (int n = 0; n < 2; ++n) _Pragma("unroll") for (int k = 0; k < 2; ++k) \
;         acc[ai][bj][m][n] = __builtin_amdgcn_mfma_f32_16x16x32_bf16(Bt[n][k], At[m][k], acc[ai][bj][m][n], 0, 0, 0); __builtin_amdgcn_s_setprio(0); } while (0)
; #define PG8_WAIT_V(n) asm volatile("s_waitcnt vmcnt(" #n ")" ::: "memory")
; #define PG8_WAIT_L(n) asm volatile("s_waitcnt lgkmcnt(" #n ")" ::: "memory")
; #define PG8_BAR __builtin_amdgcn_s_barrier()
; #define PG8_SCHED __builtin_amdgcn_sched_barrier(0)
; template <class Epi>
; DI void gemm_phase(int wv, LAS unsigned char* lds, const GemmD g, const Epi& E) {
;     ...
;             PG8_WAIT_L(8); PG8_BAR; PG8_WAIT_L(0); PG8_MMA(0, 0, At, B0); PG8_BAR; PG8_SCHED;
;             PG8_LDB(B1, 0, 1); PG8_STAGE(PG8_SB(0, 0), b2, voffB);
;             PG8_BAR; PG8_WAIT_L(0); PG8_MMA(0, 1, At, B1); PG8_BAR;
;             PG8_LDA(At, 0, 1); PG8_STAGE(PG8_SA(0, 0), a2, voffA);
;             PG8_BAR; PG8_WAIT_L(0); PG8_MMA(1, 0, At, B0); PG8_BAR; PG8_SCHED;
;             PG8_STAGE(PG8_SB(0, 1), b2 + hstepB, voffB);
;             PG8_WAIT_V(6); PG8_BAR; PG8_MMA(1, 1, At, B1); PG8_BAR;
;             PG8_LDB(B0, 1, 0); PG8_SCHED; PG8_LDA(At, 1, 0); PG8_STAGE(PG8_SA(0, 1), a2 + hstepA, voffA);
;             PG8_WAIT_L(8); PG8_BAR; PG8_WAIT_L(0); PG8_MMA(0, 0, At, B0); PG8_BAR; PG8_SCHED;
	s_waitcnt lgkmcnt(0)
	s_waitcnt lgkmcnt(0)
	v_mfma_f32_16x16x32_bf16 v[110:113], v[204:207], v[160:163], v[110:113]
	v_mfma_f32_16x16x32_bf16 v[106:109], v[212:215], v[160:163], v[106:109]
	v_mfma_f32_16x16x32_bf16 v[94:97], v[204:207], v[180:183], v[94:97]
	v_mfma_f32_16x16x32_bf16 v[90:93], v[212:215], v[180:183], v[90:93]
	v_mfma_f32_16x16x32_bf16 v[78:81], v[204:207], v[188:191], v[78:81]
	v_mfma_f32_16x16x32_bf16 v[74:77], v[212:215], v[188:191], v[74:77]
	v_mfma_f32_16x16x32_bf16 v[70:73], v[204:207], v[196:199], v[70:73]
	v_mfma_f32_16x16x32_bf16 v[66:69], v[212:215], v[196:199], v[66:69]
	v_mfma_f32_16x16x32_bf16 v[110:113], v[208:211], v[176:179], v[110:113]
	v_mfma_f32_16x16x32_bf16 v[106:109], v[216:219], v[176:179], v[106:109]
	v_mfma_f32_16x16x32_bf16 v[94:97], v[208:211], v[184:187], v[94:97]
	v_mfma_f32_16x16x32_bf16 v[90:93], v[216:219], v[184:187], v[90:93]
	v_mfma_f32_16x16x32_bf16 v[78:81], v[208:211], v[192:195], v[78:81]
	v_mfma_f32_16x16x32_bf16 v[74:77], v[216:219], v[192:195], v[74:77]
	v_mfma_f32_16x16x32_bf16 v[70:73], v[208:211], v[200:203], v[70:73]
	v_mfma_f32_16x16x32_bf16 v[66:69], v[216:219], v[200:203], v[66:69]
	s_mov_b32 m0, s15
	v_lshl_add_u64 v[170:171], s[22:23], 0, v[134:135]
	s_barrier
	ds_read_b128 v[160:163], v143 offset:16384
	ds_read_b128 v[176:179], v143 offset:17408
	ds_read_b128 v[180:183], v143 offset:18432
	ds_read_b128 v[184:187], v143 offset:19456
	ds_read_b128 v[188:191], v143 offset:20480
	ds_read_b128 v[192:195], v143 offset:21504
	ds_read_b128 v[196:199], v143 offset:22528
	ds_read_b128 v[200:203], v143 offset:23552
	global_load_lds_dwordx4 v[170:171], off
	v_lshl_add_u64 v[220:221], s[22:23], 0, v[132:133]
	s_mov_b32 m0, s45
	s_nop 0
	global_load_lds_dwordx4 v[220:221], off
	s_barrier
	s_waitcnt lgkmcnt(0)
	s_waitcnt lgkmcnt(0)
	v_mfma_f32_16x16x32_bf16 v[62:65], v[144:147], v[160:163], v[62:65]
	v_mfma_f32_16x16x32_bf16 v[58:61], v[152:155], v[160:163], v[58:61]
	v_mfma_f32_16x16x32_bf16 v[54:57], v[144:147], v[180:183], v[54:57]
	v_mfma_f32_16x16x32_bf16 v[50:53], v[152:155], v[180:183], v[50:53]
	v_mfma_f32_16x16x32_bf16 v[38:41], v[144:147], v[188:191], v[38:41]
	v_mfma_f32_16x16x32_bf16 v[34:37], v[152:155], v[188:191], v[34:37]
	v_mfma_f32_16x16x32_bf16 v[22:25], v[144:147], v[196:199], v[22:25]
	v_mfma_f32_16x16x32_bf16 v[18:21], v[152:155], v[196:199], v[18:21]
	v_mfma_f32_16x16x32_bf16 v[62:65], v[148:151], v[176:179], v[62:65]
	v_mfma_f32_16x16x32_bf16 v[58:61], v[156:159], v[176:179], v[58:61]
	v_mfma_f32_16x16x32_bf16 v[54:57], v[148:151], v[184:187], v[54:57]
	v_mfma_f32_16x16x32_bf16 v[50:53], v[156:159], v[184:187], v[50:53]
	v_mfma_f32_16x16x32_bf16 v[38:41], v[148:151], v[192:195], v[38:41]
	v_mfma_f32_16x16x32_bf16 v[34:37], v[156:159], v[192:195], v[34:37]
	v_mfma_f32_16x16x32_bf16 v[22:25], v[148:151], v[200:203], v[22:25]
	v_mfma_f32_16x16x32_bf16 v[18:21], v[156:159], v[200:203], v[18:21]
	s_barrier
	s_add_u32 s24, s24, s36
	s_addc_u32 s25, s25, 0
	s_add_i32 s2, s2, s37
	v_lshl_add_u64 v[222:223], s[24:25], 0, v[0:1]
	s_mov_b32 m0, s2
	v_lshl_add_u64 v[224:225], s[24:25], 0, v[130:131]
	global_load_lds_dwordx4 v[222:223], off
	s_add_i32 m0, s2, 0x2000
	s_nop 0
	global_load_lds_dwordx4 v[224:225], off
	s_waitcnt vmcnt(6)
	s_barrier
	v_mfma_f32_16x16x32_bf16 v[46:49], v[204:207], v[160:163], v[46:49]
	v_mfma_f32_16x16x32_bf16 v[42:45], v[212:215], v[160:163], v[42:45]
	v_mfma_f32_16x16x32_bf16 v[30:33], v[204:207], v[180:183], v[30:33]
	v_mfma_f32_16x16x32_bf16 v[26:29], v[212:215], v[180:183], v[26:29]
	v_mfma_f32_16x16x32_bf16 v[14:17], v[204:207], v[188:191], v[14:17]
	v_mfma_f32_16x16x32_bf16 v[10:13], v[212:215], v[188:191], v[10:13]
	v_mfma_f32_16x16x32_bf16 v[6:9], v[204:207], v[196:199], v[6:9]
	v_mfma_f32_16x16x32_bf16 v[2:5], v[212:215], v[196:199], v[2:5]
	v_mfma_f32_16x16x32_bf16 v[46:49], v[208:211], v[176:179], v[46:49]
	v_mfma_f32_16x16x32_bf16 v[42:45], v[216:219], v[176:179], v[42:45]
	v_mfma_f32_16x16x32_bf16 v[30:33], v[208:211], v[184:187], v[30:33]
	v_mfma_f32_16x16x32_bf16 v[26:29], v[216:219], v[184:187], v[26:29]
	v_mfma_f32_16x16x32_bf16 v[14:17], v[208:211], v[192:195], v[14:17]
	v_mfma_f32_16x16x32_bf16 v[10:13], v[216:219], v[192:195], v[10:13]
	v_mfma_f32_16x16x32_bf16 v[6:9], v[208:211], v[200:203], v[6:9]
	v_mfma_f32_16x16x32_bf16 v[2:5], v[216:219], v[200:203], v[2:5]
	s_add_i32 s2, 0, 0x18000
	v_add_u32_e32 v156, s2, v141
	s_barrier
	ds_read_b128 v[144:147], v156
	ds_read_b128 v[148:151], v156 offset:1024
	ds_read_b128 v[152:155], v156 offset:2048
	ds_read_b128 v[156:159], v156 offset:3072
	s_add_u32 s22, s22, 0x40000
	s_addc_u32 s23, s23, 0
	s_mov_b32 m0, s82
	v_lshl_add_u64 v[204:205], s[22:23], 0, v[134:135]
	ds_read_b128 v[160:163], v143 offset:32768
	ds_read_b128 v[176:179], v143 offset:33792
	ds_read_b128 v[180:183], v143 offset:34816
	ds_read_b128 v[184:187], v143 offset:35840
	ds_read_b128 v[188:191], v143 offset:36864
	ds_read_b128 v[192:195], v143 offset:37888
	ds_read_b128 v[196:199], v143 offset:38912
	ds_read_b128 v[200:203], v143 offset:39936
	global_load_lds_dwordx4 v[204:205], off
	v_lshl_add_u64 v[204:205], s[22:23], 0, v[132:133]
	s_mov_b32 m0, s83
	s_nop 0
	global_load_lds_dwordx4 v[204:205], off
	s_waitcnt lgkmcnt(8)
	s_barrier
; #define PG8_STAGE(bufoff, gbase, voff) do { _Pragma("unroll") for (int _i = 0; _i < 2; ++_i) \
;         __builtin_amdgcn_global_load_lds((const unsigned*)((const char*)(gbase) + (voff)[_i]), (LAS unsigned*)(lds + (bufoff) + ldsw + _i * 8192), 16, 0, 0); } while (0)
; #define PG8_LDA(dst, b, h) do { _Pragma("unroll") for (int m = 0; m < 4; ++m) _Pragma("unroll") for (int k = 0; k < 2; ++k) dst[m][k] = *(const LAS bf16x8*)(lds + PG8_SA(b, h) + aoff + m * 2048 + k * 1024); } while (0)
; #define PG8_LDB(dst, b, h) do { _Pragma("unroll") for (int n = 0; n < 2; ++n) _Pragma("unroll") for (int k = 0; k < 2; ++k) dst[n][k] = *(const LAS bf16x8*)(lds + PG8_SB(b, h) + boff + n * 2048 + k * 1024); } while (0)
; #define PG8_MMA(ai, bj, At, Bt) do { __builtin_amdgcn_s_setprio(1); _Pragma("unroll") for (int m = 0; m < 4; ++m) _Pragma("unroll") for (int n = 0; n < 2; ++n) _Pragma("unroll") for (int k = 0; k < 2; ++k) \
;         acc[ai][bj][m][n] = __builtin_amdgcn_mfma_f32_16x16x32_bf16(Bt[n][k], At[m][k], acc[ai][bj][m][n], 0, 0, 0); __builtin_amdgcn_s_setprio(0); } while (0)
; #define PG8_WAIT_V(n) asm volatile("s_waitcnt vmcnt(" #n ")" ::: "memory")
; #define PG8_WAIT_L(n) asm volatile("s_waitcnt lgkmcnt(" #n ")" ::: "memory")
; #define PG8_BAR __builtin_amdgcn_s_barrier()
; #define PG8_SCHED __builtin_amdgcn_sched_barrier(0)
; template <class Epi>
; DI void gemm_phase(int wv, LAS unsigned char* lds, const GemmD g, const Epi& E) {
;     ...
;             PG8_WAIT_L(8); PG8_BAR; PG8_WAIT_L(0); PG8_MMA(0, 0, At, B0); PG8_BAR; PG8_SCHED;
;             PG8_LDB(B1, 1, 1); PG8_STAGE(PG8_SB(1, 0), b3, voffB);
;             PG8_BAR; PG8_WAIT_L(0); PG8_MMA(0, 1, At, B1); PG8_BAR;
;             PG8_LDA(At, 1, 1); PG8_STAGE(PG8_SA(1, 0), a3, voffA);
;             PG8_BAR; PG8_WAIT_L(0); PG8_MMA(1, 0, At, B0); PG8_BAR; PG8_SCHED;
;             PG8_STAGE(PG8_SB(1, 1), b3 + hstepB, voffB);
;             PG8_WAIT_V(6); PG8_BAR; PG8_MMA(1, 1, At, B1); PG8_BAR;
;         }
	s_waitcnt lgkmcnt(0)
	s_waitcnt lgkmcnt(0)
	v_mfma_f32_16x16x32_bf16 v[126:129], v[144:147], v[160:163], v[126:129]
	v_mfma_f32_16x16x32_bf16 v[122:125], v[152:155], v[160:163], v[122:125]
	v_mfma_f32_16x16x32_bf16 v[118:121], v[144:147], v[180:183], v[118:121]
	v_mfma_f32_16x16x32_bf16 v[114:117], v[152:155], v[180:183], v[114:117]
	v_mfma_f32_16x16x32_bf16 v[102:105], v[144:147], v[188:191], v[102:105]
	v_mfma_f32_16x16x32_bf16 v[98:101], v[152:155], v[188:191], v[98:101]
	v_mfma_f32_16x16x32_bf16 v[86:89], v[144:147], v[196:199], v[86:89]
	v_mfma_f32_16x16x32_bf16 v[82:85], v[152:155], v[196:199], v[82:85]
	v_mfma_f32_16x16x32_bf16 v[126:129], v[148:151], v[176:179], v[126:129]
	v_mfma_f32_16x16x32_bf16 v[122:125], v[156:159], v[176:179], v[122:125]
	v_mfma_f32_16x16x32_bf16 v[118:121], v[148:151], v[184:187], v[118:121]
	v_mfma_f32_16x16x32_bf16 v[114:117], v[156:159], v[184:187], v[114:117]
	v_mfma_f32_16x16x32_bf16 v[102:105], v[148:151], v[192:195], v[102:105]
	v_mfma_f32_16x16x32_bf16 v[98:101], v[156:159], v[192:195], v[98:101]
	v_mfma_f32_16x16x32_bf16 v[86:89], v[148:151], v[200:203], v[86:89]
	v_mfma_f32_16x16x32_bf16 v[82:85], v[156:159], v[200:203], v[82:85]
	s_barrier
	s_add_i32 s3, 0, 0x1c000
	s_add_i32 s2, s2, s37
	v_add_u32_e32 v216, s3, v141
	v_lshl_add_u64 v[164:165], v[164:165], 0, s[58:59]
	s_mov_b32 m0, s2
	ds_read_b128 v[204:207], v216
	ds_read_b128 v[208:211], v216 offset:1024
	ds_read_b128 v[212:215], v216 offset:2048
	ds_read_b128 v[216:219], v216 offset:3072
	global_load_lds_dwordx4 v[164:165], off
	v_lshl_add_u64 v[164:165], v[168:169], 0, s[58:59]
	s_add_i32 m0, s2, 0x2000
	s_nop 0
	global_load_lds_dwordx4 v[164:165], off
	s_barrier
	s_waitcnt lgkmcnt(0)
	s_waitcnt lgkmcnt(0)
	v_mfma_f32_16x16x32_bf16 v[110:113], v[204:207], v[160:163], v[110:113]
	v_mfma_f32_16x16x32_bf16 v[106:109], v[212:215], v[160:163], v[106:109]
	v_mfma_f32_16x16x32_bf16 v[94:97], v[204:207], v[180:183], v[94:97]
	v_mfma_f32_16x16x32_bf16 v[90:93], v[212:215], v[180:183], v[90:93]
	v_mfma_f32_16x16x32_bf16 v[78:81], v[204:207], v[188:191], v[78:81]
	v_mfma_f32_16x16x32_bf16 v[74:77], v[212:215], v[188:191], v[74:77]
	v_mfma_f32_16x16x32_bf16 v[70:73], v[204:207], v[196:199], v[70:73]
	v_mfma_f32_16x16x32_bf16 v[66:69], v[212:215], v[196:199], v[66:69]
	v_mfma_f32_16x16x32_bf16 v[110:113], v[208:211], v[176:179], v[110:113]
	v_mfma_f32_16x16x32_bf16 v[106:109], v[216:219], v[176:179], v[106:109]
	v_mfma_f32_16x16x32_bf16 v[94:97], v[208:211], v[184:187], v[94:97]
	v_mfma_f32_16x16x32_bf16 v[90:93], v[216:219], v[184:187], v[90:93]
	v_mfma_f32_16x16x32_bf16 v[78:81], v[208:211], v[192:195], v[78:81]
	v_mfma_f32_16x16x32_bf16 v[74:77], v[216:219], v[192:195], v[74:77]
	v_mfma_f32_16x16x32_bf16 v[70:73], v[208:211], v[200:203], v[70:73]
	v_mfma_f32_16x16x32_bf16 v[66:69], v[216:219], v[200:203], v[66:69]
	s_mov_b32 m0, s84
	v_lshl_add_u64 v[164:165], v[170:171], 0, s[58:59]
	s_barrier
	ds_read_b128 v[160:163], v143 offset:49152
	ds_read_b128 v[176:179], v143 offset:50176
	ds_read_b128 v[180:183], v143 offset:51200
	ds_read_b128 v[184:187], v143 offset:52224
	ds_read_b128 v[188:191], v143 offset:53248
	ds_read_b128 v[192:195], v143 offset:54272
	ds_read_b128 v[196:199], v143 offset:55296
	ds_read_b128 v[200:203], v143 offset:56320
	global_load_lds_dwordx4 v[164:165], off
	v_lshl_add_u64 v[164:165], v[220:221], 0, s[58:59]
	s_mov_b32 m0, s85
	s_nop 0
	global_load_lds_dwordx4 v[164:165], off
	s_barrier
	s_waitcnt lgkmcnt(0)
	s_waitcnt lgkmcnt(0)
	v_mfma_f32_16x16x32_bf16 v[62:65], v[144:147], v[160:163], v[62:65]
	v_mfma_f32_16x16x32_bf16 v[58:61], v[152:155], v[160:163], v[58:61]
	v_mfma_f32_16x16x32_bf16 v[54:57], v[144:147], v[180:183], v[54:57]
	v_mfma_f32_16x16x32_bf16 v[50:53], v[152:155], v[180:183], v[50:53]
	v_mfma_f32_16x16x32_bf16 v[38:41], v[144:147], v[188:191], v[38:41]
	v_mfma_f32_16x16x32_bf16 v[34:37], v[152:155], v[188:191], v[34:37]
	v_mfma_f32_16x16x32_bf16 v[22:25], v[144:147], v[196:199], v[22:25]
	v_mfma_f32_16x16x32_bf16 v[18:21], v[152:155], v[196:199], v[18:21]
	v_mfma_f32_16x16x32_bf16 v[62:65], v[148:151], v[176:179], v[62:65]
	v_mfma_f32_16x16x32_bf16 v[58:61], v[156:159], v[176:179], v[58:61]
	v_mfma_f32_16x16x32_bf16 v[54:57], v[148:151], v[184:187], v[54:57]
	v_mfma_f32_16x16x32_bf16 v[50:53], v[156:159], v[184:187], v[50:53]
	v_mfma_f32_16x16x32_bf16 v[38:41], v[148:151], v[192:195], v[38:41]
	v_mfma_f32_16x16x32_bf16 v[34:37], v[156:159], v[192:195], v[34:37]
	v_mfma_f32_16x16x32_bf16 v[22:25], v[148:151], v[200:203], v[22:25]
	v_mfma_f32_16x16x32_bf16 v[18:21], v[156:159], v[200:203], v[18:21]
	s_barrier
	s_add_i32 s2, s3, s37
	v_lshl_add_u64 v[144:145], v[222:223], 0, s[58:59]
	s_mov_b32 m0, s2
	s_nop 0
	global_load_lds_dwordx4 v[144:145], off
	v_lshl_add_u64 v[144:145], v[224:225], 0, s[58:59]
	s_add_i32 m0, s2, 0x2000
	s_nop 0
	global_load_lds_dwordx4 v[144:145], off
	s_waitcnt vmcnt(6)
	s_barrier
	v_mfma_f32_16x16x32_bf16 v[46:49], v[204:207], v[160:163], v[46:49]
	v_mfma_f32_16x16x32_bf16 v[42:45], v[212:215], v[160:163], v[42:45]
	v_mfma_f32_16x16x32_bf16 v[30:33], v[204:207], v[180:183], v[30:33]
	v_mfma_f32_16x16x32_bf16 v[26:29], v[212:215], v[180:183], v[26:29]
	v_mfma_f32_16x16x32_bf16 v[14:17], v[204:207], v[188:191], v[14:17]
	v_mfma_f32_16x16x32_bf16 v[10:13], v[212:215], v[188:191], v[10:13]
	v_mfma_f32_16x16x32_bf16 v[6:9], v[204:207], v[196:199], v[6:9]
	v_mfma_f32_16x16x32_bf16 v[2:5], v[212:215], v[196:199], v[2:5]
	v_mfma_f32_16x16x32_bf16 v[46:49], v[208:211], v[176:179], v[46:49]
	v_mfma_f32_16x16x32_bf16 v[42:45], v[216:219], v[176:179], v[42:45]
	v_mfma_f32_16x16x32_bf16 v[30:33], v[208:211], v[184:187], v[30:33]
	v_mfma_f32_16x16x32_bf16 v[26:29], v[216:219], v[184:187], v[26:29]
	v_mfma_f32_16x16x32_bf16 v[14:17], v[208:211], v[192:195], v[14:17]
	v_mfma_f32_16x16x32_bf16 v[10:13], v[216:219], v[192:195], v[10:13]
	v_mfma_f32_16x16x32_bf16 v[6:9], v[208:211], v[200:203], v[6:9]
	v_mfma_f32_16x16x32_bf16 v[2:5], v[216:219], v[200:203], v[2:5]
	s_add_i32 s95, s95, 2
	s_add_u32 s4, s4, 0x100
	s_addc_u32 s5, s5, 0
	s_add_u32 vcc_hi, vcc_hi, 0x100
	s_addc_u32 s75, s75, 0
	s_cmp_gt_u32 s95, 13
	s_barrier
	s_cbranch_scc0 .LBB0_99
; DI unsigned pk2(float lo, float hi) { f32x2 f = {lo, hi}; bf2_t v = __builtin_convertvector(f, bf2_t); return __builtin_bit_cast(unsigned, v); }
; #define PG8_WAIT_V(n) asm volatile("s_waitcnt vmcnt(" #n ")" ::: "memory")
; #define PG8_BAR __builtin_amdgcn_s_barrier()
;     DI void operator()(const f32x4 (&acc)[2][2][4][2], const Unit& u, int wr, int wc, int fr, int fq) const {
;         const int row0 = u.pm * BM + wr * 64 + fr; const int col0 = u.pn * BM + wc * 32 + 8 * fq;
; #pragma unroll
;         for (int ai = 0; ai < 2; ++ai)
; #pragma unroll
;             for (int m = 0; m < 4; ++m) { bf16_t* rowp = O + (size_t)(row0 + ai * HALF + m * 16) * ldc + col0;
; #pragma unroll
;                 for (int bj = 0; bj < 2; ++bj) { f32x4 v0 = acc[ai][bj][m][0], v1 = acc[ai][bj][m][1];
;                     if (ACT == 1) {
; #pragma unroll
;                         for (int j = 0; j < 4; ++j) { float a = fmaxf(v0[j], 0.f), b = fmaxf(v1[j], 0.f); v0[j] = a * a; v1[j] = b * b; } }
;                     u32x4 w; w.x = pk2(v0[0], v0[1]); w.y = pk2(v0[2], v0[3]); w.z = pk2(v1[0], v1[1]); w.w = pk2(v1[2], v1[3]);
;                     *(u32x4*)(rowp + bj * HALF) = w; } }
; template <class Epi>
; DI void gemm_phase(int wv, LAS unsigned char* lds, const GemmD g, const Epi& E) {
;     ...
;         E(acc, cur, wr, wc, fr, fq);
;         if (!has_next) break;
; #pragma unroll
;         for (int a = 0; a < 2; ++a)
; #pragma unroll
;             for (int b = 0; b < 2; ++b)
; #pragma unroll
;                 for (int m = 0; m < 4; ++m)
; #pragma unroll
;                     for (int n = 0; n < 2; ++n) acc[a][b][m][n] = (f32x4){0.f, 0.f, 0.f, 0.f};
;         cur = nxt; cA = nA; cB = nB; ++ui;
;     }
;     PG8_WAIT_V(0);
;     if (wr == 0) PG8_BAR;
;     PG8_BAR;
.Lgemm_epi_a:
	v_lshl_add_u32 v148, s14, 8, v140
	v_lshl_or_b32 v144, s55, 8, v142
	v_ashrrev_i32_e32 v145, 31, v144
	v_mad_i64_i32 v[146:147], s[4:5], s12, v148, 0
	v_cvt_pk_bf16_f32 v110, v110, v111
	v_cvt_pk_bf16_f32 v111, v112, v113
	v_cvt_pk_bf16_f32 v112, v106, v107
	v_or_b32_e32 v106, 16, v148
	v_lshl_add_u64 v[146:147], v[146:147], 1, s[10:11]
	v_lshlrev_b64 v[144:145], 1, v[144:145]
	v_mad_i64_i32 v[106:107], s[4:5], s12, v106, 0
	v_cvt_pk_bf16_f32 v94, v94, v95
	v_cvt_pk_bf16_f32 v95, v96, v97
	v_cvt_pk_bf16_f32 v96, v90, v91
	v_or_b32_e32 v90, 32, v148
	v_lshl_add_u64 v[146:147], v[146:147], 0, v[144:145]
	v_cvt_pk_bf16_f32 v113, v108, v109
	v_lshl_add_u64 v[106:107], v[106:107], 1, s[10:11]
	v_mad_i64_i32 v[90:91], s[4:5], s12, v90, 0
	v_cvt_pk_bf16_f32 v78, v78, v79
	v_cvt_pk_bf16_f32 v79, v80, v81
	v_cvt_pk_bf16_f32 v80, v74, v75
	v_or_b32_e32 v74, 48, v148
	v_cvt_pk_bf16_f32 v70, v70, v71
	v_cvt_pk_bf16_f32 v71, v72, v73
	v_cvt_pk_bf16_f32 v72, v66, v67
	v_add_u32_e32 v66, 0x80, v148
	v_cvt_pk_bf16_f32 v126, v126, v127
	v_cvt_pk_bf16_f32 v127, v128, v129
	v_cvt_pk_bf16_f32 v128, v122, v123
	v_cvt_pk_bf16_f32 v129, v124, v125
	global_store_dwordx4 v[146:147], v[110:113], off offset:256
	v_cvt_pk_bf16_f32 v97, v92, v93
	v_lshl_add_u64 v[90:91], v[90:91], 1, s[10:11]
	v_lshl_add_u64 v[110:111], v[106:107], 0, v[144:145]
	v_mad_i64_i32 v[74:75], s[4:5], s12, v74, 0
	v_mad_i64_i32 v[66:67], s[4:5], s12, v66, 0
	v_cvt_pk_bf16_f32 v46, v46, v47
	v_cvt_pk_bf16_f32 v47, v48, v49
	v_cvt_pk_bf16_f32 v48, v42, v43
	v_add_u32_e32 v42, 0x90, v148
	global_store_dwordx4 v[146:147], v[126:129], off
	v_cvt_pk_bf16_f32 v106, v118, v119
	v_cvt_pk_bf16_f32 v107, v120, v121
	v_cvt_pk_bf16_f32 v108, v114, v115
	v_cvt_pk_bf16_f32 v109, v116, v117
	global_store_dwordx4 v[110:111], v[94:97], off offset:256
	v_cvt_pk_bf16_f32 v81, v76, v77
	v_lshl_add_u64 v[74:75], v[74:75], 1, s[10:11]
	v_lshl_add_u64 v[94:95], v[90:91], 0, v[144:145]
	v_lshl_add_u64 v[66:67], v[66:67], 1, s[10:11]
	v_mad_i64_i32 v[42:43], s[4:5], s12, v42, 0
	v_cvt_pk_bf16_f32 v30, v30, v31
	v_cvt_pk_bf16_f32 v31, v32, v33
	v_cvt_pk_bf16_f32 v32, v26, v27
	v_add_u32_e32 v26, 0xa0, v148
	global_store_dwordx4 v[110:111], v[106:109], off
	v_cvt_pk_bf16_f32 v90, v102, v103
	v_cvt_pk_bf16_f32 v91, v104, v105
	v_cvt_pk_bf16_f32 v92, v98, v99
	v_cvt_pk_bf16_f32 v93, v100, v101
	global_store_dwordx4 v[94:95], v[78:81], off offset:256
	v_cvt_pk_bf16_f32 v76, v82, v83
	v_cvt_pk_bf16_f32 v77, v84, v85
	v_lshl_add_u64 v[78:79], v[74:75], 0, v[144:145]
	v_cvt_pk_bf16_f32 v74, v86, v87
	v_cvt_pk_bf16_f32 v75, v88, v89
	v_cvt_pk_bf16_f32 v73, v68, v69
	v_lshl_add_u64 v[66:67], v[66:67], 0, v[144:145]
	v_cvt_pk_bf16_f32 v49, v44, v45
	v_lshl_add_u64 v[42:43], v[42:43], 1, s[10:11]
	v_mad_i64_i32 v[26:27], s[4:5], s12, v26, 0
	v_cvt_pk_bf16_f32 v14, v14, v15
	v_cvt_pk_bf16_f32 v15, v16, v17
	v_cvt_pk_bf16_f32 v16, v10, v11
	v_add_u32_e32 v10, 0xb0, v148
	global_store_dwordx4 v[94:95], v[90:93], off
	global_store_dwordx4 v[78:79], v[74:77], off
	global_store_dwordx4 v[78:79], v[70:73], off offset:256
	v_cvt_pk_bf16_f32 v62, v62, v63
	v_cvt_pk_bf16_f32 v63, v64, v65
	v_cvt_pk_bf16_f32 v64, v58, v59
	v_cvt_pk_bf16_f32 v65, v60, v61
	global_store_dwordx4 v[66:67], v[46:49], off offset:256
	v_cvt_pk_bf16_f32 v33, v28, v29
	v_lshl_add_u64 v[26:27], v[26:27], 1, s[10:11]
	v_lshl_add_u64 v[46:47], v[42:43], 0, v[144:145]
	v_mad_i64_i32 v[10:11], s[4:5], s12, v10, 0
	global_store_dwordx4 v[66:67], v[62:65], off
	v_cvt_pk_bf16_f32 v42, v54, v55
	v_cvt_pk_bf16_f32 v43, v56, v57
	v_cvt_pk_bf16_f32 v44, v50, v51
	v_cvt_pk_bf16_f32 v45, v52, v53
	global_store_dwordx4 v[46:47], v[30:33], off offset:256
	v_cvt_pk_bf16_f32 v17, v12, v13
	v_lshl_add_u64 v[10:11], v[10:11], 1, s[10:11]
	v_lshl_add_u64 v[30:31], v[26:27], 0, v[144:145]
	global_store_dwordx4 v[46:47], v[42:45], off
	v_cvt_pk_bf16_f32 v26, v38, v39
	v_cvt_pk_bf16_f32 v27, v40, v41
	v_cvt_pk_bf16_f32 v28, v34, v35
	v_cvt_pk_bf16_f32 v29, v36, v37
	global_store_dwordx4 v[30:31], v[14:17], off offset:256
	v_cvt_pk_bf16_f32 v12, v18, v19
	v_cvt_pk_bf16_f32 v13, v20, v21
	v_lshl_add_u64 v[14:15], v[10:11], 0, v[144:145]
	v_cvt_pk_bf16_f32 v10, v22, v23
	v_cvt_pk_bf16_f32 v11, v24, v25
	v_cvt_pk_bf16_f32 v6, v6, v7
	v_cvt_pk_bf16_f32 v7, v8, v9
	v_cvt_pk_bf16_f32 v8, v2, v3
	v_cvt_pk_bf16_f32 v9, v4, v5
	s_and_b64 vcc, exec, s[0:1]
	s_mov_b32 s55, s68
	s_mov_b32 s14, s16
	s_mov_b64 s[22:23], s[18:19]
	s_mov_b64 s[24:25], s[20:21]
	global_store_dwordx4 v[30:31], v[26:29], off
	global_store_dwordx4 v[14:15], v[10:13], off
	global_store_dwordx4 v[14:15], v[6:9], off offset:256
	s_cbranch_vccz .LBB0_94
	s_waitcnt vmcnt(0)
	s_setprio 0
	s_cmpk_gt_u32 s35, 0xff
	v_readlane_b32 s68, v253, 13
	s_cbranch_scc1 .LBB0_83
	s_barrier
	s_branch .LBB0_83

; DI int mk_tid(int wv) { int w = wv; asm volatile("" : "+s"(w)); int l = __builtin_amdgcn_mbcnt_hi(~0u, __builtin_amdgcn_mbcnt_lo(~0u, 0u)); asm volatile("" : "+v"(l)); return w * 64 + l; }
; DI int opaque_bid() { int b = blockIdx.x; asm volatile("" : "+s"(b)); return b; }
; #define PG8_STAGE(bufoff, gbase, voff) do { _Pragma("unroll") for (int _i = 0; _i < 2; ++_i) \
;         __builtin_amdgcn_global_load_lds((const unsigned*)((const char*)(gbase) + (voff)[_i]), (LAS unsigned*)(lds + (bufoff) + ldsw + _i * 8192), 16, 0, 0); } while (0)
; #define PG8_BAR __builtin_amdgcn_s_barrier()
; template <class Epi>
; DI void gemm_phase(int wv, LAS unsigned char* lds, const GemmD g, const Epi& E) {
;     const int tid = mk_tid(wv), wid = __builtin_amdgcn_readfirstlane(tid >> 6), lane = tid & 63, wr = wid >> 2, wc = wid & 3, fr = lane & 15, fq = lane >> 4;
;     const int K = g.K, nt = K / BK;
;     const int ldbe = g.ldb * g.dil;
;     unsigned voffA[2], voffB[2];
; #pragma unroll
;     for (int i = 0; i < 2; ++i) { int R, C; stage_rc(tid * 16 + i * 8192, R, C); const int Rb = Epi::PERM ? ((R & ~31) + perm32(R & 31)) : R;
;         voffA[i] = (unsigned)(R * g.lda + C) * 2u; voffB[i] = (unsigned)(Rb * ldbe + C) * 2u; }
;     const size_t kstep = (size_t)(BK * 2);
;     const size_t hstepA = (size_t)HALF * g.lda * 2, hstepB = (size_t)HALF * ldbe * 2;
;     const unsigned ldsw = (unsigned)wid * 1024u;
;     const int aoff = lds_byte(wr * 64 + fr, fq * 8), boff = lds_byte(wc * 32 + fr, fq * 8);
;     ...
;     StaticOrder S; S.init(g.nM, g.nN, (int)gridDim.x, opaque_bid());
;     Unit cur, nxt; int ui = 0;
;     if (!S.next(0, cur)) return;
;     f32x4 acc[2][2][4][2];
; #pragma unroll
;     for (int a = 0; a < 2; ++a)
; #pragma unroll
;         for (int b = 0; b < 2; ++b)
; #pragma unroll
;             for (int m = 0; m < 4; ++m)
; #pragma unroll
;                 for (int n = 0; n < 2; ++n) acc[a][b][m][n] = (f32x4){0.f, 0.f, 0.f, 0.f};
;     bf16x8 At[4][2], B0[2][2], B1[2][2];
;     ...
;     const char* cA = (const char*)g.A + (size_t)cur.pm * 256 * g.lda * 2; const char* cB = (const char*)g.Bt + PG8_BROW(cur.pn) * (size_t)g.ldb * 2;
;     PG8_STAGE(PG8_SB(0, 0), cB, voffB); PG8_STAGE(PG8_SA(0, 0), cA, voffA); PG8_STAGE(PG8_SB(0, 1), cB + hstepB, voffB); PG8_STAGE(PG8_SA(0, 1), cA + hstepA, voffA);
;     if (wr == 1) PG8_BAR;
.LBB0_480:
	v_ashrrev_i32_e32 v2, 31, v0
	v_lshrrev_b32_e32 v2, 26, v2
	s_waitcnt lgkmcnt(0)
	v_lshlrev_b32_e32 v5, 4, v0
	v_add_u32_e32 v2, v0, v2
	v_bfe_i32 v0, v0, 27, 1
	v_lshrrev_b32_e32 v0, 22, v0
	v_add_u32_e32 v0, v5, v0
	v_and_b32_e32 v0, 0xfffffc00, v0
	v_sub_u32_e32 v0, v5, v0
	v_ashrrev_i32_e32 v2, 6, v2
	v_lshrrev_b32_e32 v3, 4, v0
	v_bitop3_b32 v0, v3, v0, 32 bitop3:0x6c
	v_lshlrev_b32_e32 v3, 3, v2
	v_and_b32_e32 v4, -16, v3
	v_ashrrev_i32_e32 v3, 31, v0
	v_lshrrev_b32_e32 v3, 26, v3
	v_add_u32_e32 v6, v0, v3
	v_ashrrev_i32_e32 v3, 6, v6
	v_add_u32_e32 v7, v3, v4
	v_lshlrev_b32_e32 v4, 5, v2
	v_and_b32_e32 v9, 32, v4
	v_and_b32_e32 v4, 0xc0, v6
	v_sub_u32_e32 v0, v0, v4
	s_add_u32 s76, s48, s0
	v_ashrrev_i16_sdwa v0, v244, sext(v0) dst_sel:DWORD dst_unused:UNUSED_PAD src0_sel:DWORD src1_sel:BYTE_0
	s_addc_u32 s78, s49, s1
	v_bfe_i32 v4, v0, 0, 16
	v_lshlrev_b32_e32 v0, 1, v7
	v_lshrrev_b32_e32 v6, 2, v7
	v_and_b32_e32 v10, 3, v3
	s_mov_b32 s1, 0x1fffe0
	v_and_b32_e32 v0, 24, v0
	v_and_b32_e32 v6, 4, v6
	v_and_or_b32 v10, v7, s1, v10
	v_or3_b32 v0, v10, v6, v0
	v_add_lshl_u32 v6, v9, v4, 1
	v_lshl_add_u32 v130, v7, 11, v6
	v_lshl_add_u32 v0, v0, 11, v6
	v_add_u32_e32 v6, 0x2000, v5
	v_ashrrev_i32_e32 v5, 31, v6
	s_add_i32 s2, s8, s6
	v_lshrrev_b32_e32 v5, 22, v5
	s_ashr_i32 s3, s2, 31
	v_add_u32_e32 v5, v6, v5
	s_lshr_b32 s3, s3, 25
	v_ashrrev_i32_e32 v5, 10, v5
	s_add_i32 s3, s2, s3
	v_mul_i32_i24_e32 v7, 0x400, v5
	s_ashr_i32 s6, s3, 7
	s_and_b32 s3, s3, 0xff80
	v_sub_u32_e32 v6, v6, v7
	s_sub_i32 s2, s2, s3
	v_lshrrev_b32_e32 v7, 4, v6
	s_bfe_i32 s3, s2, 0x80000
	v_bitop3_b32 v7, v7, v6, 32 bitop3:0x6c
	v_lshlrev_b32_e32 v6, 3, v5
	s_bfe_u32 s3, s3, 0x3000c
	v_and_b32_e32 v9, -16, v6
	v_ashrrev_i32_e32 v6, 31, v7
	s_add_i32 s3, s2, s3
	v_lshrrev_b32_e32 v6, 26, v6
	s_bfe_i32 s7, s3, 0x80000
	s_and_b32 s3, s3, 0xf8
	v_add_u32_e32 v10, v7, v6
	s_sext_i32_i16 s7, s7
	s_sub_i32 s2, s2, s3
	v_ashrrev_i32_e32 v6, 6, v10
	s_lshl_b32 s6, s6, 3
	s_sext_i32_i8 s2, s2
	s_ashr_i32 s12, s7, 3
	v_add_u32_e32 v9, v6, v9
	v_and_b32_e32 v13, 3, v6
	s_add_i32 s24, s6, s2
	s_lshl_b32 s8, s12, 8
	v_and_or_b32 v13, v9, s1, v13
	s_ashr_i32 s1, s35, 6
	s_ashr_i32 s25, s24, 31
	s_ashr_i32 s9, s8, 31
	s_ashr_i32 s0, s35, 8
	v_and_b32_e32 v10, 0xc0, v10
	s_lshl_b32 s79, s1, 10
	s_lshl_b64 s[6:7], s[24:25], 19
	s_lshl_b64 s[8:9], s[8:9], 11
	v_sub_u32_e32 v7, v7, v10
	s_add_u32 s28, s39, s8
	v_lshlrev_b32_e32 v11, 5, v5
	v_ashrrev_i16_sdwa v7, v244, sext(v7) dst_sel:DWORD dst_unused:UNUSED_PAD src0_sel:DWORD src1_sel:BYTE_0
	v_lshlrev_b32_e32 v10, 1, v9
	v_lshrrev_b32_e32 v12, 2, v9
	s_addc_u32 s29, s40, s9
	s_add_i32 s25, s79, 0
	v_and_b32_e32 v11, 32, v11
	v_bfe_i32 v7, v7, 0, 16
	v_and_b32_e32 v10, 24, v10
	v_and_b32_e32 v12, 4, v12
	s_add_i32 m0, s25, 0x10000
	v_or3_b32 v10, v13, v12, v10
	v_add_lshl_u32 v11, v11, v7, 1
	global_load_lds_dwordx4 v0, s[28:29]
	s_add_i32 m0, s25, 0x12000
	v_lshl_add_u32 v134, v10, 11, v11
	s_add_u32 s26, s76, s6
	global_load_lds_dwordx4 v134, s[28:29]
	s_addc_u32 s27, s78, s7
	s_mov_b32 m0, s25
	s_add_i32 s80, s25, 0x2000
	v_lshl_add_u32 v132, v9, 11, v11
	global_load_lds_dwordx4 v130, s[26:27]
	s_mov_b32 m0, s80
	s_add_u32 s6, s28, 0x40000
	global_load_lds_dwordx4 v132, s[26:27]
	s_addc_u32 s7, s29, 0
	s_add_i32 m0, s25, 0x14000
	s_nop 0
	global_load_lds_dwordx4 v0, s[6:7]
	s_add_i32 m0, s25, 0x16000
	s_nop 0
	global_load_lds_dwordx4 v134, s[6:7]
	s_add_u32 s6, s26, 0x40000
	s_addc_u32 s7, s27, 0
	s_add_i32 s81, s25, 0x4000
	s_mov_b32 m0, s81
	s_add_i32 s82, s25, 0x6000
	global_load_lds_dwordx4 v130, s[6:7]
	s_mov_b32 m0, s82
	s_cmp_lg_u32 s0, 1
	global_load_lds_dwordx4 v132, s[6:7]
	s_cbranch_scc1 .LBB0_482
	s_setprio 1
	s_barrier

; #define PG8_STAGE(bufoff, gbase, voff) do { _Pragma("unroll") for (int _i = 0; _i < 2; ++_i) \
;         __builtin_amdgcn_global_load_lds((const unsigned*)((const char*)(gbase) + (voff)[_i]), (LAS unsigned*)(lds + (bufoff) + ldsw + _i * 8192), 16, 0, 0); } while (0)
; #define PG8_LDA(dst, b, h) do { _Pragma("unroll") for (int m = 0; m < 4; ++m) _Pragma("unroll") for (int k = 0; k < 2; ++k) dst[m][k] = *(const LAS bf16x8*)(lds + PG8_SA(b, h) + aoff + m * 2048 + k * 1024); } while (0)
; #define PG8_LDB(dst, b, h) do { _Pragma("unroll") for (int n = 0; n < 2; ++n) _Pragma("unroll") for (int k = 0; k < 2; ++k) dst[n][k] = *(const LAS bf16x8*)(lds + PG8_SB(b, h) + boff + n * 2048 + k * 1024); } while (0)
; #define PG8_MMA(ai, bj, At, Bt) do { __builtin_amdgcn_s_setprio(1); _Pragma("unroll") for (int m = 0; m < 4; ++m) _Pragma("unroll") for (int n = 0; n < 2; ++n) _Pragma("unroll") for (int k = 0; k < 2; ++k) \
;         acc[ai][bj][m][n] = __builtin_amdgcn_mfma_f32_16x16x32_bf16(Bt[n][k], At[m][k], acc[ai][bj][m][n], 0, 0, 0); __builtin_amdgcn_s_setprio(0); } while (0)
; #define PG8_WAIT_L(n) asm volatile("s_waitcnt lgkmcnt(" #n ")" ::: "memory")
; template <class Epi>
; DI void gemm_phase(int wv, LAS unsigned char* lds, const GemmD g, const Epi& E) {
;     ...
;         const bool has_next = S.next(ui + 1, nxt);
;         const char* nA = has_next ? (const char*)g.A + (size_t)nxt.pm * 256 * g.lda * 2 : cA; const char* nB = has_next ? (const char*)g.Bt + PG8_BROW(nxt.pn) * (size_t)g.ldb * 2 : cB;
;         for (int t = 0; t < nt; t += 2) {
;             const bool last = (t == nt - 2);
;             const char* a1 = cA + (size_t)(t + 1) * kstep;
;             const char* a2 = last ? nA : cA + (size_t)(t + 2) * kstep; const char* b2 = last ? nB : cB + (size_t)(t + 2) * kstep;
;             const char* a3 = a2 + kstep; const char* b3 = b2 + kstep;
;             PG8_LDB(B0, 0, 0); PG8_SCHED; PG8_LDA(At, 0, 0); PG8_STAGE(PG8_SA(1, 1), a1 + hstepA, voffA);
;             PG8_WAIT_L(8); PG8_BAR; PG8_WAIT_L(0); PG8_MMA(0, 0, At, B0); PG8_BAR; PG8_SCHED;
;             PG8_LDB(B1, 0, 1); PG8_STAGE(PG8_SB(0, 0), b2, voffB);
;             PG8_BAR; PG8_WAIT_L(0); PG8_MMA(0, 1, At, B1); PG8_BAR;
;             PG8_LDA(At, 0, 1); PG8_STAGE(PG8_SA(0, 0), a2, voffA);
;             PG8_BAR; PG8_WAIT_L(0); PG8_MMA(1, 0, At, B0); PG8_BAR; PG8_SCHED;
.LBB0_489:
	s_ashr_i32 s7, s6, 31
	v_cmp_lt_i64_e32 vcc, s[8:9], v[228:229]
	s_lshl_b64 s[8:9], s[6:7], 19
	s_add_u32 s8, s76, s8
	s_addc_u32 s9, s78, s9
	s_and_b64 s[16:17], vcc, exec
	s_cselect_b32 s7, s9, s27
	s_cselect_b32 s13, s8, s26
	s_lshl_b32 s16, s86, 8
	s_ashr_i32 s17, s16, 31
	s_lshl_b64 s[16:17], s[16:17], 11
	s_add_u32 s22, s39, s16
	s_addc_u32 s23, s40, s17
	s_and_b64 s[16:17], vcc, exec
	s_cselect_b32 s16, s23, s29
	s_cselect_b32 s17, s22, s28
	s_add_u32 s26, s26, 0x40080
	s_addc_u32 s27, s27, 0
	s_add_u32 s36, s28, 0x100
	s_addc_u32 s38, s29, 0
	s_mov_b32 s41, -2
	s_add_u32 s2, s26, 0xfffc0080
	s_addc_u32 s3, s27, -1
	s_add_i32 s18, 0, 0x10000
	v_add_u32_e32 v140, s18, v144
	ds_read_b128 v[148:151], v140
	ds_read_b128 v[152:155], v140 offset:1024
	ds_read_b128 v[156:159], v140 offset:2048
	ds_read_b128 v[160:163], v140 offset:3072
	s_cmp_eq_u32 s41, 12
	s_cselect_b32 s31, s7, s3
	s_cselect_b32 s30, s13, s2
	s_cselect_b32 s29, s16, s38
	s_cselect_b32 s28, s17, s36
	v_lshl_add_u64 v[140:141], s[26:27], 0, v[136:137]
	s_add_i32 m0, s25, 0xc000
	ds_read_b128 v[168:171], v146
	ds_read_b128 v[176:179], v146 offset:1024
	ds_read_b128 v[180:183], v146 offset:2048
	ds_read_b128 v[184:187], v146 offset:3072
	ds_read_b128 v[188:191], v146 offset:4096
	ds_read_b128 v[192:195], v146 offset:5120
	ds_read_b128 v[196:199], v146 offset:6144
	ds_read_b128 v[200:203], v146 offset:7168
	global_load_lds_dwordx4 v[140:141], off
	v_lshl_add_u64 v[140:141], s[26:27], 0, v[138:139]
	s_add_i32 m0, s25, 0xe000
	s_nop 0
	global_load_lds_dwordx4 v[140:141], off
	s_waitcnt lgkmcnt(8)
	s_barrier
	s_waitcnt lgkmcnt(0)
	s_waitcnt lgkmcnt(0)
	v_mfma_f32_16x16x32_bf16 v[126:129], v[148:151], v[168:171], 0
	v_mfma_f32_16x16x32_bf16 v[122:125], v[156:159], v[168:171], 0
	v_mfma_f32_16x16x32_bf16 v[110:113], v[148:151], v[180:183], 0
	v_mfma_f32_16x16x32_bf16 v[106:109], v[156:159], v[180:183], 0
	v_mfma_f32_16x16x32_bf16 v[94:97], v[148:151], v[188:191], 0
	v_mfma_f32_16x16x32_bf16 v[90:93], v[156:159], v[188:191], 0
	v_mfma_f32_16x16x32_bf16 v[78:81], v[148:151], v[196:199], 0
	v_mfma_f32_16x16x32_bf16 v[74:77], v[156:159], v[196:199], 0
	v_mfma_f32_16x16x32_bf16 v[126:129], v[152:155], v[176:179], v[126:129]
	v_mfma_f32_16x16x32_bf16 v[122:125], v[160:163], v[176:179], v[122:125]
	v_mfma_f32_16x16x32_bf16 v[110:113], v[152:155], v[184:187], v[110:113]
	v_mfma_f32_16x16x32_bf16 v[106:109], v[160:163], v[184:187], v[106:109]
	v_mfma_f32_16x16x32_bf16 v[94:97], v[152:155], v[192:195], v[94:97]
	v_mfma_f32_16x16x32_bf16 v[90:93], v[160:163], v[192:195], v[90:93]
	v_mfma_f32_16x16x32_bf16 v[78:81], v[152:155], v[200:203], v[78:81]
	v_mfma_f32_16x16x32_bf16 v[74:77], v[160:163], v[200:203], v[74:77]
	s_barrier
	s_add_i32 s2, 0, 0x14000
	v_add_u32_e32 v140, s2, v144
	s_add_i32 s3, s18, s79
	ds_read_b128 v[204:207], v140
	ds_read_b128 v[208:211], v140 offset:1024
	ds_read_b128 v[212:215], v140 offset:2048
	ds_read_b128 v[216:219], v140 offset:3072
	v_lshl_add_u64 v[140:141], s[28:29], 0, v[0:1]
	s_mov_b32 m0, s3
	v_lshl_add_u64 v[164:165], s[28:29], 0, v[134:135]
	global_load_lds_dwordx4 v[140:141], off
	s_add_i32 m0, s3, 0x2000
	s_nop 0
	global_load_lds_dwordx4 v[164:165], off
	s_barrier
	s_waitcnt lgkmcnt(0)
	s_waitcnt lgkmcnt(0)
	v_mfma_f32_16x16x32_bf16 v[118:121], v[204:207], v[168:171], 0
	v_mfma_f32_16x16x32_bf16 v[114:117], v[212:215], v[168:171], 0
	v_mfma_f32_16x16x32_bf16 v[102:105], v[204:207], v[180:183], 0
	v_mfma_f32_16x16x32_bf16 v[98:101], v[212:215], v[180:183], 0
	v_mfma_f32_16x16x32_bf16 v[86:89], v[204:207], v[188:191], 0
	v_mfma_f32_16x16x32_bf16 v[82:85], v[212:215], v[188:191], 0
	v_mfma_f32_16x16x32_bf16 v[70:73], v[204:207], v[196:199], 0
	v_mfma_f32_16x16x32_bf16 v[66:69], v[212:215], v[196:199], 0
	v_mfma_f32_16x16x32_bf16 v[118:121], v[208:211], v[176:179], v[118:121]
	v_mfma_f32_16x16x32_bf16 v[114:117], v[216:219], v[176:179], v[114:117]
	v_mfma_f32_16x16x32_bf16 v[102:105], v[208:211], v[184:187], v[102:105]
	v_mfma_f32_16x16x32_bf16 v[98:101], v[216:219], v[184:187], v[98:101]
	v_mfma_f32_16x16x32_bf16 v[86:89], v[208:211], v[192:195], v[86:89]
	v_mfma_f32_16x16x32_bf16 v[82:85], v[216:219], v[192:195], v[82:85]
	v_mfma_f32_16x16x32_bf16 v[70:73], v[208:211], v[200:203], v[70:73]
	v_mfma_f32_16x16x32_bf16 v[66:69], v[216:219], v[200:203], v[66:69]
	s_mov_b32 m0, s25
	v_lshl_add_u64 v[220:221], s[30:31], 0, v[130:131]
	s_barrier
	ds_read_b128 v[168:171], v146 offset:16384
	ds_read_b128 v[176:179], v146 offset:17408
	ds_read_b128 v[180:183], v146 offset:18432
	ds_read_b128 v[184:187], v146 offset:19456
	ds_read_b128 v[188:191], v146 offset:20480
	ds_read_b128 v[192:195], v146 offset:21504
	ds_read_b128 v[196:199], v146 offset:22528
	ds_read_b128 v[200:203], v146 offset:23552
	global_load_lds_dwordx4 v[220:221], off
	v_lshl_add_u64 v[222:223], s[30:31], 0, v[132:133]
	s_mov_b32 m0, s80
	s_nop 0
	global_load_lds_dwordx4 v[222:223], off
	s_barrier
	s_waitcnt lgkmcnt(0)
	s_waitcnt lgkmcnt(0)
	v_mfma_f32_16x16x32_bf16 v[62:65], v[148:151], v[168:171], 0
	v_mfma_f32_16x16x32_bf16 v[58:61], v[156:159], v[168:171], 0
	v_mfma_f32_16x16x32_bf16 v[46:49], v[148:151], v[180:183], 0
	v_mfma_f32_16x16x32_bf16 v[42:45], v[156:159], v[180:183], 0
	v_mfma_f32_16x16x32_bf16 v[30:33], v[148:151], v[188:191], 0
	v_mfma_f32_16x16x32_bf16 v[26:29], v[156:159], v[188:191], 0
	v_mfma_f32_16x16x32_bf16 v[14:17], v[148:151], v[196:199], 0
	v_mfma_f32_16x16x32_bf16 v[10:13], v[156:159], v[196:199], 0
	v_mfma_f32_16x16x32_bf16 v[62:65], v[152:155], v[176:179], v[62:65]
	v_mfma_f32_16x16x32_bf16 v[58:61], v[160:163], v[176:179], v[58:61]
	v_mfma_f32_16x16x32_bf16 v[46:49], v[152:155], v[184:187], v[46:49]
	v_mfma_f32_16x16x32_bf16 v[42:45], v[160:163], v[184:187], v[42:45]
	v_mfma_f32_16x16x32_bf16 v[30:33], v[152:155], v[192:195], v[30:33]
	v_mfma_f32_16x16x32_bf16 v[26:29], v[160:163], v[192:195], v[26:29]
	v_mfma_f32_16x16x32_bf16 v[14:17], v[152:155], v[200:203], v[14:17]
	v_mfma_f32_16x16x32_bf16 v[10:13], v[160:163], v[200:203], v[10:13]
	s_barrier
; #define PG8_STAGE(bufoff, gbase, voff) do { _Pragma("unroll") for (int _i = 0; _i < 2; ++_i) \
;         __builtin_amdgcn_global_load_lds((const unsigned*)((const char*)(gbase) + (voff)[_i]), (LAS unsigned*)(lds + (bufoff) + ldsw + _i * 8192), 16, 0, 0); } while (0)
; #define PG8_LDA(dst, b, h) do { _Pragma("unroll") for (int m = 0; m < 4; ++m) _Pragma("unroll") for (int k = 0; k < 2; ++k) dst[m][k] = *(const LAS bf16x8*)(lds + PG8_SA(b, h) + aoff + m * 2048 + k * 1024); } while (0)
; #define PG8_LDB(dst, b, h) do { _Pragma("unroll") for (int n = 0; n < 2; ++n) _Pragma("unroll") for (int k = 0; k < 2; ++k) dst[n][k] = *(const LAS bf16x8*)(lds + PG8_SB(b, h) + boff + n * 2048 + k * 1024); } while (0)
; #define PG8_MMA(ai, bj, At, Bt) do { __builtin_amdgcn_s_setprio(1); _Pragma("unroll") for (int m = 0; m < 4; ++m) _Pragma("unroll") for (int n = 0; n < 2; ++n) _Pragma("unroll") for (int k = 0; k < 2; ++k) \
;         acc[ai][bj][m][n] = __builtin_amdgcn_mfma_f32_16x16x32_bf16(Bt[n][k], At[m][k], acc[ai][bj][m][n], 0, 0, 0); __builtin_amdgcn_s_setprio(0); } while (0)
; #define PG8_WAIT_V(n) asm volatile("s_waitcnt vmcnt(" #n ")" ::: "memory")
; #define PG8_WAIT_L(n) asm volatile("s_waitcnt lgkmcnt(" #n ")" ::: "memory")
; #define PG8_BAR __builtin_amdgcn_s_barrier()
; #define PG8_SCHED __builtin_amdgcn_sched_barrier(0)
; template <class Epi>
; DI void gemm_phase(int wv, LAS unsigned char* lds, const GemmD g, const Epi& E) {
;     ...
;             PG8_BAR; PG8_WAIT_L(0); PG8_MMA(1, 0, At, B0); PG8_BAR; PG8_SCHED;
;             PG8_STAGE(PG8_SB(0, 1), b2 + hstepB, voffB);
;             PG8_WAIT_V(6); PG8_BAR; PG8_MMA(1, 1, At, B1); PG8_BAR;
;             PG8_LDB(B0, 1, 0); PG8_SCHED; PG8_LDA(At, 1, 0); PG8_STAGE(PG8_SA(0, 1), a2 + hstepA, voffA);
;             PG8_WAIT_L(8); PG8_BAR; PG8_WAIT_L(0); PG8_MMA(0, 0, At, B0); PG8_BAR; PG8_SCHED;
;             PG8_LDB(B1, 1, 1); PG8_STAGE(PG8_SB(1, 0), b3, voffB);
;             PG8_BAR; PG8_WAIT_L(0); PG8_MMA(0, 1, At, B1); PG8_BAR;
;             PG8_LDA(At, 1, 1); PG8_STAGE(PG8_SA(1, 0), a3, voffA);
;             PG8_BAR; PG8_WAIT_L(0); PG8_MMA(1, 0, At, B0); PG8_BAR; PG8_SCHED;
	s_add_u32 s18, s28, 0x40000
	s_addc_u32 s19, s29, 0
	s_add_i32 s2, s2, s79
	v_lshl_add_u64 v[148:149], s[18:19], 0, v[0:1]
	s_mov_b32 m0, s2
	s_nop 0
	global_load_lds_dwordx4 v[148:149], off
	v_lshl_add_u64 v[148:149], s[18:19], 0, v[134:135]
	s_add_i32 m0, s2, 0x2000
	s_nop 0
	global_load_lds_dwordx4 v[148:149], off
	s_waitcnt vmcnt(6)
	s_barrier
	v_mfma_f32_16x16x32_bf16 v[54:57], v[204:207], v[168:171], 0
	v_mfma_f32_16x16x32_bf16 v[50:53], v[212:215], v[168:171], 0
	v_mfma_f32_16x16x32_bf16 v[38:41], v[204:207], v[180:183], 0
	v_mfma_f32_16x16x32_bf16 v[34:37], v[212:215], v[180:183], 0
	v_mfma_f32_16x16x32_bf16 v[22:25], v[204:207], v[188:191], 0
	v_mfma_f32_16x16x32_bf16 v[18:21], v[212:215], v[188:191], 0
	v_mfma_f32_16x16x32_bf16 v[6:9], v[204:207], v[196:199], 0
	v_mfma_f32_16x16x32_bf16 v[2:5], v[212:215], v[196:199], 0
	v_mfma_f32_16x16x32_bf16 v[54:57], v[208:211], v[176:179], v[54:57]
	v_mfma_f32_16x16x32_bf16 v[50:53], v[216:219], v[176:179], v[50:53]
	v_mfma_f32_16x16x32_bf16 v[38:41], v[208:211], v[184:187], v[38:41]
	v_mfma_f32_16x16x32_bf16 v[34:37], v[216:219], v[184:187], v[34:37]
	v_mfma_f32_16x16x32_bf16 v[22:25], v[208:211], v[192:195], v[22:25]
	v_mfma_f32_16x16x32_bf16 v[18:21], v[216:219], v[192:195], v[18:21]
	v_mfma_f32_16x16x32_bf16 v[6:9], v[208:211], v[200:203], v[6:9]
	v_mfma_f32_16x16x32_bf16 v[2:5], v[216:219], v[200:203], v[2:5]
	s_add_i32 s2, 0, 0x18000
	v_add_u32_e32 v147, s2, v144
	s_barrier
	ds_read_b128 v[148:151], v147
	ds_read_b128 v[152:155], v147 offset:1024
	ds_read_b128 v[156:159], v147 offset:2048
	ds_read_b128 v[160:163], v147 offset:3072
	s_add_u32 s18, s30, 0x40000
	s_addc_u32 s19, s31, 0
	s_mov_b32 m0, s81
	v_lshl_add_u64 v[204:205], s[18:19], 0, v[130:131]
	ds_read_b128 v[168:171], v146 offset:32768
	ds_read_b128 v[176:179], v146 offset:33792
	ds_read_b128 v[180:183], v146 offset:34816
	ds_read_b128 v[184:187], v146 offset:35840
	ds_read_b128 v[188:191], v146 offset:36864
	ds_read_b128 v[192:195], v146 offset:37888
	ds_read_b128 v[196:199], v146 offset:38912
	ds_read_b128 v[200:203], v146 offset:39936
	global_load_lds_dwordx4 v[204:205], off
	v_lshl_add_u64 v[204:205], s[18:19], 0, v[132:133]
	s_mov_b32 m0, s82
	s_nop 0
	global_load_lds_dwordx4 v[204:205], off
	s_waitcnt lgkmcnt(8)
	s_barrier
	s_waitcnt lgkmcnt(0)
	s_waitcnt lgkmcnt(0)
	v_mfma_f32_16x16x32_bf16 v[126:129], v[148:151], v[168:171], v[126:129]
	v_mfma_f32_16x16x32_bf16 v[122:125], v[156:159], v[168:171], v[122:125]
	v_mfma_f32_16x16x32_bf16 v[110:113], v[148:151], v[180:183], v[110:113]
	v_mfma_f32_16x16x32_bf16 v[106:109], v[156:159], v[180:183], v[106:109]
	v_mfma_f32_16x16x32_bf16 v[94:97], v[148:151], v[188:191], v[94:97]
	v_mfma_f32_16x16x32_bf16 v[90:93], v[156:159], v[188:191], v[90:93]
	v_mfma_f32_16x16x32_bf16 v[78:81], v[148:151], v[196:199], v[78:81]
	v_mfma_f32_16x16x32_bf16 v[74:77], v[156:159], v[196:199], v[74:77]
	v_mfma_f32_16x16x32_bf16 v[126:129], v[152:155], v[176:179], v[126:129]
	v_mfma_f32_16x16x32_bf16 v[122:125], v[160:163], v[176:179], v[122:125]
	v_mfma_f32_16x16x32_bf16 v[110:113], v[152:155], v[184:187], v[110:113]
	v_mfma_f32_16x16x32_bf16 v[106:109], v[160:163], v[184:187], v[106:109]
	v_mfma_f32_16x16x32_bf16 v[94:97], v[152:155], v[192:195], v[94:97]
	v_mfma_f32_16x16x32_bf16 v[90:93], v[160:163], v[192:195], v[90:93]
	v_mfma_f32_16x16x32_bf16 v[78:81], v[152:155], v[200:203], v[78:81]
	v_mfma_f32_16x16x32_bf16 v[74:77], v[160:163], v[200:203], v[74:77]
	s_barrier
	s_add_i32 s3, 0, 0x1c000
	s_add_i32 s2, s2, s79
	v_add_u32_e32 v147, s3, v144
	v_lshl_add_u64 v[140:141], v[140:141], 0, s[58:59]
	s_mov_b32 m0, s2
	ds_read_b128 v[204:207], v147
	ds_read_b128 v[208:211], v147 offset:1024
	ds_read_b128 v[212:215], v147 offset:2048
	ds_read_b128 v[216:219], v147 offset:3072
	global_load_lds_dwordx4 v[140:141], off
	v_lshl_add_u64 v[140:141], v[164:165], 0, s[58:59]
	s_add_i32 m0, s2, 0x2000
	s_nop 0
	global_load_lds_dwordx4 v[140:141], off
	s_barrier
	s_waitcnt lgkmcnt(0)
	s_waitcnt lgkmcnt(0)
	v_mfma_f32_16x16x32_bf16 v[118:121], v[204:207], v[168:171], v[118:121]
	v_mfma_f32_16x16x32_bf16 v[114:117], v[212:215], v[168:171], v[114:117]
	v_mfma_f32_16x16x32_bf16 v[102:105], v[204:207], v[180:183], v[102:105]
	v_mfma_f32_16x16x32_bf16 v[98:101], v[212:215], v[180:183], v[98:101]
	v_mfma_f32_16x16x32_bf16 v[86:89], v[204:207], v[188:191], v[86:89]
	v_mfma_f32_16x16x32_bf16 v[82:85], v[212:215], v[188:191], v[82:85]
	v_mfma_f32_16x16x32_bf16 v[70:73], v[204:207], v[196:199], v[70:73]
	v_mfma_f32_16x16x32_bf16 v[66:69], v[212:215], v[196:199], v[66:69]
	v_mfma_f32_16x16x32_bf16 v[118:121], v[208:211], v[176:179], v[118:121]
	v_mfma_f32_16x16x32_bf16 v[114:117], v[216:219], v[176:179], v[114:117]
	v_mfma_f32_16x16x32_bf16 v[102:105], v[208:211], v[184:187], v[102:105]
	v_mfma_f32_16x16x32_bf16 v[98:101], v[216:219], v[184:187], v[98:101]
	v_mfma_f32_16x16x32_bf16 v[86:89], v[208:211], v[192:195], v[86:89]
	v_mfma_f32_16x16x32_bf16 v[82:85], v[216:219], v[192:195], v[82:85]
	v_mfma_f32_16x16x32_bf16 v[70:73], v[208:211], v[200:203], v[70:73]
	v_mfma_f32_16x16x32_bf16 v[66:69], v[216:219], v[200:203], v[66:69]
	s_mov_b32 m0, s83
	v_lshl_add_u64 v[140:141], v[220:221], 0, s[58:59]
	s_barrier
	ds_read_b128 v[168:171], v146 offset:49152
	ds_read_b128 v[176:179], v146 offset:50176
	ds_read_b128 v[180:183], v146 offset:51200
	ds_read_b128 v[184:187], v146 offset:52224
	ds_read_b128 v[188:191], v146 offset:53248
	ds_read_b128 v[192:195], v146 offset:54272
	ds_read_b128 v[196:199], v146 offset:55296
	ds_read_b128 v[200:203], v146 offset:56320
	global_load_lds_dwordx4 v[140:141], off
	v_lshl_add_u64 v[140:141], v[222:223], 0, s[58:59]
	s_mov_b32 m0, s84
	s_nop 0
	global_load_lds_dwordx4 v[140:141], off
	s_barrier
; #define PG8_STAGE(bufoff, gbase, voff) do { _Pragma("unroll") for (int _i = 0; _i < 2; ++_i) \
;         __builtin_amdgcn_global_load_lds((const unsigned*)((const char*)(gbase) + (voff)[_i]), (LAS unsigned*)(lds + (bufoff) + ldsw + _i * 8192), 16, 0, 0); } while (0)
; #define PG8_LDA(dst, b, h) do { _Pragma("unroll") for (int m = 0; m < 4; ++m) _Pragma("unroll") for (int k = 0; k < 2; ++k) dst[m][k] = *(const LAS bf16x8*)(lds + PG8_SA(b, h) + aoff + m * 2048 + k * 1024); } while (0)
; #define PG8_LDB(dst, b, h) do { _Pragma("unroll") for (int n = 0; n < 2; ++n) _Pragma("unroll") for (int k = 0; k < 2; ++k) dst[n][k] = *(const LAS bf16x8*)(lds + PG8_SB(b, h) + boff + n * 2048 + k * 1024); } while (0)
; #define PG8_MMA(ai, bj, At, Bt) do { __builtin_amdgcn_s_setprio(1); _Pragma("unroll") for (int m = 0; m < 4; ++m) _Pragma("unroll") for (int n = 0; n < 2; ++n) _Pragma("unroll") for (int k = 0; k < 2; ++k) \
;         acc[ai][bj][m][n] = __builtin_amdgcn_mfma_f32_16x16x32_bf16(Bt[n][k], At[m][k], acc[ai][bj][m][n], 0, 0, 0); __builtin_amdgcn_s_setprio(0); } while (0)
; #define PG8_WAIT_V(n) asm volatile("s_waitcnt vmcnt(" #n ")" ::: "memory")
; #define PG8_WAIT_L(n) asm volatile("s_waitcnt lgkmcnt(" #n ")" ::: "memory")
; #define PG8_BAR __builtin_amdgcn_s_barrier()
; #define PG8_SCHED __builtin_amdgcn_sched_barrier(0)
; template <class Epi>
; DI void gemm_phase(int wv, LAS unsigned char* lds, const GemmD g, const Epi& E) {
;     ...
;             PG8_LDB(B0, 0, 0); PG8_SCHED; PG8_LDA(At, 0, 0); PG8_STAGE(PG8_SA(1, 1), a1 + hstepA, voffA);
;             PG8_WAIT_L(8); PG8_BAR; PG8_WAIT_L(0); PG8_MMA(0, 0, At, B0); PG8_BAR; PG8_SCHED;
;     ...
;             PG8_BAR; PG8_WAIT_L(0); PG8_MMA(0, 1, At, B1); PG8_BAR;
;             PG8_LDA(At, 1, 1); PG8_STAGE(PG8_SA(1, 0), a3, voffA);
;             PG8_BAR; PG8_WAIT_L(0); PG8_MMA(1, 0, At, B0); PG8_BAR; PG8_SCHED;
;             PG8_STAGE(PG8_SB(1, 1), b3 + hstepB, voffB);
;             PG8_WAIT_V(6); PG8_BAR; PG8_MMA(1, 1, At, B1); PG8_BAR;
;         }
	s_waitcnt lgkmcnt(0)
	s_waitcnt lgkmcnt(0)
	v_mfma_f32_16x16x32_bf16 v[62:65], v[148:151], v[168:171], v[62:65]
	v_mfma_f32_16x16x32_bf16 v[58:61], v[156:159], v[168:171], v[58:61]
	v_mfma_f32_16x16x32_bf16 v[46:49], v[148:151], v[180:183], v[46:49]
	v_mfma_f32_16x16x32_bf16 v[42:45], v[156:159], v[180:183], v[42:45]
	v_mfma_f32_16x16x32_bf16 v[30:33], v[148:151], v[188:191], v[30:33]
	v_mfma_f32_16x16x32_bf16 v[26:29], v[156:159], v[188:191], v[26:29]
	v_mfma_f32_16x16x32_bf16 v[14:17], v[148:151], v[196:199], v[14:17]
	v_mfma_f32_16x16x32_bf16 v[10:13], v[156:159], v[196:199], v[10:13]
	v_mfma_f32_16x16x32_bf16 v[62:65], v[152:155], v[176:179], v[62:65]
	v_mfma_f32_16x16x32_bf16 v[58:61], v[160:163], v[176:179], v[58:61]
	v_mfma_f32_16x16x32_bf16 v[46:49], v[152:155], v[184:187], v[46:49]
	v_mfma_f32_16x16x32_bf16 v[42:45], v[160:163], v[184:187], v[42:45]
	v_mfma_f32_16x16x32_bf16 v[30:33], v[152:155], v[192:195], v[30:33]
	v_mfma_f32_16x16x32_bf16 v[26:29], v[160:163], v[192:195], v[26:29]
	v_mfma_f32_16x16x32_bf16 v[14:17], v[152:155], v[200:203], v[14:17]
	v_mfma_f32_16x16x32_bf16 v[10:13], v[160:163], v[200:203], v[10:13]
	s_barrier
	s_add_u32 s18, s28, 0x40080
	s_addc_u32 s19, s29, 0
	s_add_i32 s2, s3, s79
	v_lshl_add_u64 v[140:141], s[18:19], 0, v[0:1]
	s_mov_b32 m0, s2
	s_nop 0
	global_load_lds_dwordx4 v[140:141], off
	v_lshl_add_u64 v[140:141], s[18:19], 0, v[134:135]
	s_add_i32 m0, s2, 0x2000
	s_nop 0
	global_load_lds_dwordx4 v[140:141], off
	s_waitcnt vmcnt(6)
	s_barrier
	v_mfma_f32_16x16x32_bf16 v[54:57], v[204:207], v[168:171], v[54:57]
	v_mfma_f32_16x16x32_bf16 v[50:53], v[212:215], v[168:171], v[50:53]
	v_mfma_f32_16x16x32_bf16 v[38:41], v[204:207], v[180:183], v[38:41]
	v_mfma_f32_16x16x32_bf16 v[34:37], v[212:215], v[180:183], v[34:37]
	v_mfma_f32_16x16x32_bf16 v[22:25], v[204:207], v[188:191], v[22:25]
	v_mfma_f32_16x16x32_bf16 v[18:21], v[212:215], v[188:191], v[18:21]
	v_mfma_f32_16x16x32_bf16 v[6:9], v[204:207], v[196:199], v[6:9]
	v_mfma_f32_16x16x32_bf16 v[2:5], v[212:215], v[196:199], v[2:5]
	v_mfma_f32_16x16x32_bf16 v[54:57], v[208:211], v[176:179], v[54:57]
	v_mfma_f32_16x16x32_bf16 v[50:53], v[216:219], v[176:179], v[50:53]
	v_mfma_f32_16x16x32_bf16 v[38:41], v[208:211], v[184:187], v[38:41]
	v_mfma_f32_16x16x32_bf16 v[34:37], v[216:219], v[184:187], v[34:37]
	v_mfma_f32_16x16x32_bf16 v[22:25], v[208:211], v[192:195], v[22:25]
	v_mfma_f32_16x16x32_bf16 v[18:21], v[216:219], v[192:195], v[18:21]
	v_mfma_f32_16x16x32_bf16 v[6:9], v[208:211], v[200:203], v[6:9]
	v_mfma_f32_16x16x32_bf16 v[2:5], v[216:219], v[200:203], v[2:5]
	s_add_i32 s41, s41, 2
	s_add_u32 s26, s26, 0x100
	s_addc_u32 s27, s27, 0
	s_add_u32 s36, s36, 0x100
	s_addc_u32 s38, s38, 0
	s_cmp_gt_u32 s41, 13
	s_barrier
	s_cbranch_scc0 .LBB0_490
	s_branch .Lgemm_epi_b
.LBB0_490:
	s_add_u32 s2, s26, 0xfffc0080
	s_addc_u32 s3, s27, -1
	s_add_i32 s18, 0, 0x10000
	v_add_u32_e32 v140, s18, v144
	ds_read_b128 v[148:151], v140
	ds_read_b128 v[152:155], v140 offset:1024
	ds_read_b128 v[156:159], v140 offset:2048
	ds_read_b128 v[160:163], v140 offset:3072
	s_cmp_eq_u32 s41, 12
	s_cselect_b32 s31, s7, s3
	s_cselect_b32 s30, s13, s2
	s_cselect_b32 s29, s16, s38
	s_cselect_b32 s28, s17, s36
	v_lshl_add_u64 v[140:141], s[26:27], 0, v[136:137]
	s_add_i32 m0, s25, 0xc000
	ds_read_b128 v[168:171], v146
	ds_read_b128 v[176:179], v146 offset:1024
	ds_read_b128 v[180:183], v146 offset:2048
	ds_read_b128 v[184:187], v146 offset:3072
	ds_read_b128 v[188:191], v146 offset:4096
	ds_read_b128 v[192:195], v146 offset:5120
	ds_read_b128 v[196:199], v146 offset:6144
	ds_read_b128 v[200:203], v146 offset:7168
	global_load_lds_dwordx4 v[140:141], off
	v_lshl_add_u64 v[140:141], s[26:27], 0, v[138:139]
	s_add_i32 m0, s25, 0xe000
	s_nop 0
	global_load_lds_dwordx4 v[140:141], off
	s_waitcnt lgkmcnt(8)
	s_barrier
	s_waitcnt lgkmcnt(0)
	s_waitcnt lgkmcnt(0)
	v_mfma_f32_16x16x32_bf16 v[126:129], v[148:151], v[168:171], v[126:129]
	v_mfma_f32_16x16x32_bf16 v[122:125], v[156:159], v[168:171], v[122:125]
	v_mfma_f32_16x16x32_bf16 v[110:113], v[148:151], v[180:183], v[110:113]
	v_mfma_f32_16x16x32_bf16 v[106:109], v[156:159], v[180:183], v[106:109]
	v_mfma_f32_16x16x32_bf16 v[94:97], v[148:151], v[188:191], v[94:97]
	v_mfma_f32_16x16x32_bf16 v[90:93], v[156:159], v[188:191], v[90:93]
	v_mfma_f32_16x16x32_bf16 v[78:81], v[148:151], v[196:199], v[78:81]
	v_mfma_f32_16x16x32_bf16 v[74:77], v[156:159], v[196:199], v[74:77]
	v_mfma_f32_16x16x32_bf16 v[126:129], v[152:155], v[176:179], v[126:129]
	v_mfma_f32_16x16x32_bf16 v[122:125], v[160:163], v[176:179], v[122:125]
	v_mfma_f32_16x16x32_bf16 v[110:113], v[152:155], v[184:187], v[110:113]
	v_mfma_f32_16x16x32_bf16 v[106:109], v[160:163], v[184:187], v[106:109]
	v_mfma_f32_16x16x32_bf16 v[94:97], v[152:155], v[192:195], v[94:97]
	v_mfma_f32_16x16x32_bf16 v[90:93], v[160:163], v[192:195], v[90:93]
	v_mfma_f32_16x16x32_bf16 v[78:81], v[152:155], v[200:203], v[78:81]
	v_mfma_f32_16x16x32_bf16 v[74:77], v[160:163], v[200:203], v[74:77]
	s_barrier
	s_add_i32 s2, 0, 0x14000
	v_add_u32_e32 v140, s2, v144
	s_add_i32 s3, s18, s79
	ds_read_b128 v[204:207], v140
	ds_read_b128 v[208:211], v140 offset:1024
	ds_read_b128 v[212:215], v140 offset:2048
	ds_read_b128 v[216:219], v140 offset:3072
	v_lshl_add_u64 v[140:141], s[28:29], 0, v[0:1]
	s_mov_b32 m0, s3
	v_lshl_add_u64 v[164:165], s[28:29], 0, v[134:135]
	global_load_lds_dwordx4 v[140:141], off
	s_add_i32 m0, s3, 0x2000
	s_nop 0
	global_load_lds_dwordx4 v[164:165], off
	s_barrier
; #define PG8_STAGE(bufoff, gbase, voff) do { _Pragma("unroll") for (int _i = 0; _i < 2; ++_i) \
;         __builtin_amdgcn_global_load_lds((const unsigned*)((const char*)(gbase) + (voff)[_i]), (LAS unsigned*)(lds + (bufoff) + ldsw + _i * 8192), 16, 0, 0); } while (0)
; #define PG8_LDA(dst, b, h) do { _Pragma("unroll") for (int m = 0; m < 4; ++m) _Pragma("unroll") for (int k = 0; k < 2; ++k) dst[m][k] = *(const LAS bf16x8*)(lds + PG8_SA(b, h) + aoff + m * 2048 + k * 1024); } while (0)
; #define PG8_LDB(dst, b, h) do { _Pragma("unroll") for (int n = 0; n < 2; ++n) _Pragma("unroll") for (int k = 0; k < 2; ++k) dst[n][k] = *(const LAS bf16x8*)(lds + PG8_SB(b, h) + boff + n * 2048 + k * 1024); } while (0)
; #define PG8_MMA(ai, bj, At, Bt) do { __builtin_amdgcn_s_setprio(1); _Pragma("unroll") for (int m = 0; m < 4; ++m) _Pragma("unroll") for (int n = 0; n < 2; ++n) _Pragma("unroll") for (int k = 0; k < 2; ++k) \
;         acc[ai][bj][m][n] = __builtin_amdgcn_mfma_f32_16x16x32_bf16(Bt[n][k], At[m][k], acc[ai][bj][m][n], 0, 0, 0); __builtin_amdgcn_s_setprio(0); } while (0)
; #define PG8_WAIT_V(n) asm volatile("s_waitcnt vmcnt(" #n ")" ::: "memory")
; #define PG8_WAIT_L(n) asm volatile("s_waitcnt lgkmcnt(" #n ")" ::: "memory")
; #define PG8_BAR __builtin_amdgcn_s_barrier()
; #define PG8_SCHED __builtin_amdgcn_sched_barrier(0)
; template <class Epi>
; DI void gemm_phase(int wv, LAS unsigned char* lds, const GemmD g, const Epi& E) {
;     ...
;             PG8_WAIT_L(8); PG8_BAR; PG8_WAIT_L(0); PG8_MMA(0, 0, At, B0); PG8_BAR; PG8_SCHED;
;             PG8_LDB(B1, 0, 1); PG8_STAGE(PG8_SB(0, 0), b2, voffB);
;             PG8_BAR; PG8_WAIT_L(0); PG8_MMA(0, 1, At, B1); PG8_BAR;
;             PG8_LDA(At, 0, 1); PG8_STAGE(PG8_SA(0, 0), a2, voffA);
;             PG8_BAR; PG8_WAIT_L(0); PG8_MMA(1, 0, At, B0); PG8_BAR; PG8_SCHED;
;             PG8_STAGE(PG8_SB(0, 1), b2 + hstepB, voffB);
;             PG8_WAIT_V(6); PG8_BAR; PG8_MMA(1, 1, At, B1); PG8_BAR;
;             PG8_LDB(B0, 1, 0); PG8_SCHED; PG8_LDA(At, 1, 0); PG8_STAGE(PG8_SA(0, 1), a2 + hstepA, voffA);
;             PG8_WAIT_L(8); PG8_BAR; PG8_WAIT_L(0); PG8_MMA(0, 0, At, B0); PG8_BAR; PG8_SCHED;
;             PG8_LDB(B1, 1, 1); PG8_STAGE(PG8_SB(1, 0), b3, voffB);
	s_waitcnt lgkmcnt(0)
	s_waitcnt lgkmcnt(0)
	v_mfma_f32_16x16x32_bf16 v[118:121], v[204:207], v[168:171], v[118:121]
	v_mfma_f32_16x16x32_bf16 v[114:117], v[212:215], v[168:171], v[114:117]
	v_mfma_f32_16x16x32_bf16 v[102:105], v[204:207], v[180:183], v[102:105]
	v_mfma_f32_16x16x32_bf16 v[98:101], v[212:215], v[180:183], v[98:101]
	v_mfma_f32_16x16x32_bf16 v[86:89], v[204:207], v[188:191], v[86:89]
	v_mfma_f32_16x16x32_bf16 v[82:85], v[212:215], v[188:191], v[82:85]
	v_mfma_f32_16x16x32_bf16 v[70:73], v[204:207], v[196:199], v[70:73]
	v_mfma_f32_16x16x32_bf16 v[66:69], v[212:215], v[196:199], v[66:69]
	v_mfma_f32_16x16x32_bf16 v[118:121], v[208:211], v[176:179], v[118:121]
	v_mfma_f32_16x16x32_bf16 v[114:117], v[216:219], v[176:179], v[114:117]
	v_mfma_f32_16x16x32_bf16 v[102:105], v[208:211], v[184:187], v[102:105]
	v_mfma_f32_16x16x32_bf16 v[98:101], v[216:219], v[184:187], v[98:101]
	v_mfma_f32_16x16x32_bf16 v[86:89], v[208:211], v[192:195], v[86:89]
	v_mfma_f32_16x16x32_bf16 v[82:85], v[216:219], v[192:195], v[82:85]
	v_mfma_f32_16x16x32_bf16 v[70:73], v[208:211], v[200:203], v[70:73]
	v_mfma_f32_16x16x32_bf16 v[66:69], v[216:219], v[200:203], v[66:69]
	s_mov_b32 m0, s25
	v_lshl_add_u64 v[220:221], s[30:31], 0, v[130:131]
	s_barrier
	ds_read_b128 v[168:171], v146 offset:16384
	ds_read_b128 v[176:179], v146 offset:17408
	ds_read_b128 v[180:183], v146 offset:18432
	ds_read_b128 v[184:187], v146 offset:19456
	ds_read_b128 v[188:191], v146 offset:20480
	ds_read_b128 v[192:195], v146 offset:21504
	ds_read_b128 v[196:199], v146 offset:22528
	ds_read_b128 v[200:203], v146 offset:23552
	global_load_lds_dwordx4 v[220:221], off
	v_lshl_add_u64 v[222:223], s[30:31], 0, v[132:133]
	s_mov_b32 m0, s80
	s_nop 0
	global_load_lds_dwordx4 v[222:223], off
	s_barrier
	s_waitcnt lgkmcnt(0)
	s_waitcnt lgkmcnt(0)
	v_mfma_f32_16x16x32_bf16 v[62:65], v[148:151], v[168:171], v[62:65]
	v_mfma_f32_16x16x32_bf16 v[58:61], v[156:159], v[168:171], v[58:61]
	v_mfma_f32_16x16x32_bf16 v[46:49], v[148:151], v[180:183], v[46:49]
	v_mfma_f32_16x16x32_bf16 v[42:45], v[156:159], v[180:183], v[42:45]
	v_mfma_f32_16x16x32_bf16 v[30:33], v[148:151], v[188:191], v[30:33]
	v_mfma_f32_16x16x32_bf16 v[26:29], v[156:159], v[188:191], v[26:29]
	v_mfma_f32_16x16x32_bf16 v[14:17], v[148:151], v[196:199], v[14:17]
	v_mfma_f32_16x16x32_bf16 v[10:13], v[156:159], v[196:199], v[10:13]
	v_mfma_f32_16x16x32_bf16 v[62:65], v[152:155], v[176:179], v[62:65]
	v_mfma_f32_16x16x32_bf16 v[58:61], v[160:163], v[176:179], v[58:61]
	v_mfma_f32_16x16x32_bf16 v[46:49], v[152:155], v[184:187], v[46:49]
	v_mfma_f32_16x16x32_bf16 v[42:45], v[160:163], v[184:187], v[42:45]
	v_mfma_f32_16x16x32_bf16 v[30:33], v[152:155], v[192:195], v[30:33]
	v_mfma_f32_16x16x32_bf16 v[26:29], v[160:163], v[192:195], v[26:29]
	v_mfma_f32_16x16x32_bf16 v[14:17], v[152:155], v[200:203], v[14:17]
	v_mfma_f32_16x16x32_bf16 v[10:13], v[160:163], v[200:203], v[10:13]
	s_barrier
	s_add_u32 s18, s28, 0x40000
	s_addc_u32 s19, s29, 0
	s_add_i32 s2, s2, s79
	v_lshl_add_u64 v[148:149], s[18:19], 0, v[0:1]
	s_mov_b32 m0, s2
	s_nop 0
	global_load_lds_dwordx4 v[148:149], off
	v_lshl_add_u64 v[148:149], s[18:19], 0, v[134:135]
	s_add_i32 m0, s2, 0x2000
	s_nop 0
	global_load_lds_dwordx4 v[148:149], off
	s_waitcnt vmcnt(6)
	s_barrier
	v_mfma_f32_16x16x32_bf16 v[54:57], v[204:207], v[168:171], v[54:57]
	v_mfma_f32_16x16x32_bf16 v[50:53], v[212:215], v[168:171], v[50:53]
	v_mfma_f32_16x16x32_bf16 v[38:41], v[204:207], v[180:183], v[38:41]
	v_mfma_f32_16x16x32_bf16 v[34:37], v[212:215], v[180:183], v[34:37]
	v_mfma_f32_16x16x32_bf16 v[22:25], v[204:207], v[188:191], v[22:25]
	v_mfma_f32_16x16x32_bf16 v[18:21], v[212:215], v[188:191], v[18:21]
	v_mfma_f32_16x16x32_bf16 v[6:9], v[204:207], v[196:199], v[6:9]
	v_mfma_f32_16x16x32_bf16 v[2:5], v[212:215], v[196:199], v[2:5]
	v_mfma_f32_16x16x32_bf16 v[54:57], v[208:211], v[176:179], v[54:57]
	v_mfma_f32_16x16x32_bf16 v[50:53], v[216:219], v[176:179], v[50:53]
	v_mfma_f32_16x16x32_bf16 v[38:41], v[208:211], v[184:187], v[38:41]
	v_mfma_f32_16x16x32_bf16 v[34:37], v[216:219], v[184:187], v[34:37]
	v_mfma_f32_16x16x32_bf16 v[22:25], v[208:211], v[192:195], v[22:25]
	v_mfma_f32_16x16x32_bf16 v[18:21], v[216:219], v[192:195], v[18:21]
	v_mfma_f32_16x16x32_bf16 v[6:9], v[208:211], v[200:203], v[6:9]
	v_mfma_f32_16x16x32_bf16 v[2:5], v[216:219], v[200:203], v[2:5]
	s_add_i32 s2, 0, 0x18000
	v_add_u32_e32 v147, s2, v144
	s_barrier
	ds_read_b128 v[148:151], v147
	ds_read_b128 v[152:155], v147 offset:1024
	ds_read_b128 v[156:159], v147 offset:2048
	ds_read_b128 v[160:163], v147 offset:3072
	s_add_u32 s18, s30, 0x40000
	s_addc_u32 s19, s31, 0
	s_mov_b32 m0, s81
	v_lshl_add_u64 v[204:205], s[18:19], 0, v[130:131]
	ds_read_b128 v[168:171], v146 offset:32768
	ds_read_b128 v[176:179], v146 offset:33792
	ds_read_b128 v[180:183], v146 offset:34816
	ds_read_b128 v[184:187], v146 offset:35840
	ds_read_b128 v[188:191], v146 offset:36864
	ds_read_b128 v[192:195], v146 offset:37888
	ds_read_b128 v[196:199], v146 offset:38912
	ds_read_b128 v[200:203], v146 offset:39936
	global_load_lds_dwordx4 v[204:205], off
	v_lshl_add_u64 v[204:205], s[18:19], 0, v[132:133]
	s_mov_b32 m0, s82
	s_nop 0
	global_load_lds_dwordx4 v[204:205], off
	s_waitcnt lgkmcnt(8)
	s_barrier
; #define PG8_STAGE(bufoff, gbase, voff) do { _Pragma("unroll") for (int _i = 0; _i < 2; ++_i) \
;         __builtin_amdgcn_global_load_lds((const unsigned*)((const char*)(gbase) + (voff)[_i]), (LAS unsigned*)(lds + (bufoff) + ldsw + _i * 8192), 16, 0, 0); } while (0)
; #define PG8_LDA(dst, b, h) do { _Pragma("unroll") for (int m = 0; m < 4; ++m) _Pragma("unroll") for (int k = 0; k < 2; ++k) dst[m][k] = *(const LAS bf16x8*)(lds + PG8_SA(b, h) + aoff + m * 2048 + k * 1024); } while (0)
; #define PG8_LDB(dst, b, h) do { _Pragma("unroll") for (int n = 0; n < 2; ++n) _Pragma("unroll") for (int k = 0; k < 2; ++k) dst[n][k] = *(const LAS bf16x8*)(lds + PG8_SB(b, h) + boff + n * 2048 + k * 1024); } while (0)
; #define PG8_MMA(ai, bj, At, Bt) do { __builtin_amdgcn_s_setprio(1); _Pragma("unroll") for (int m = 0; m < 4; ++m) _Pragma("unroll") for (int n = 0; n < 2; ++n) _Pragma("unroll") for (int k = 0; k < 2; ++k) \
;         acc[ai][bj][m][n] = __builtin_amdgcn_mfma_f32_16x16x32_bf16(Bt[n][k], At[m][k], acc[ai][bj][m][n], 0, 0, 0); __builtin_amdgcn_s_setprio(0); } while (0)
; #define PG8_WAIT_V(n) asm volatile("s_waitcnt vmcnt(" #n ")" ::: "memory")
; #define PG8_WAIT_L(n) asm volatile("s_waitcnt lgkmcnt(" #n ")" ::: "memory")
; #define PG8_BAR __builtin_amdgcn_s_barrier()
; #define PG8_SCHED __builtin_amdgcn_sched_barrier(0)
; template <class Epi>
; DI void gemm_phase(int wv, LAS unsigned char* lds, const GemmD g, const Epi& E) {
;     ...
;             PG8_WAIT_L(8); PG8_BAR; PG8_WAIT_L(0); PG8_MMA(0, 0, At, B0); PG8_BAR; PG8_SCHED;
;             PG8_LDB(B1, 1, 1); PG8_STAGE(PG8_SB(1, 0), b3, voffB);
;             PG8_BAR; PG8_WAIT_L(0); PG8_MMA(0, 1, At, B1); PG8_BAR;
;             PG8_LDA(At, 1, 1); PG8_STAGE(PG8_SA(1, 0), a3, voffA);
;             PG8_BAR; PG8_WAIT_L(0); PG8_MMA(1, 0, At, B0); PG8_BAR; PG8_SCHED;
;             PG8_STAGE(PG8_SB(1, 1), b3 + hstepB, voffB);
;             PG8_WAIT_V(6); PG8_BAR; PG8_MMA(1, 1, At, B1); PG8_BAR;
;         }
	s_waitcnt lgkmcnt(0)
	s_waitcnt lgkmcnt(0)
	v_mfma_f32_16x16x32_bf16 v[126:129], v[148:151], v[168:171], v[126:129]
	v_mfma_f32_16x16x32_bf16 v[122:125], v[156:159], v[168:171], v[122:125]
	v_mfma_f32_16x16x32_bf16 v[110:113], v[148:151], v[180:183], v[110:113]
	v_mfma_f32_16x16x32_bf16 v[106:109], v[156:159], v[180:183], v[106:109]
	v_mfma_f32_16x16x32_bf16 v[94:97], v[148:151], v[188:191], v[94:97]
	v_mfma_f32_16x16x32_bf16 v[90:93], v[156:159], v[188:191], v[90:93]
	v_mfma_f32_16x16x32_bf16 v[78:81], v[148:151], v[196:199], v[78:81]
	v_mfma_f32_16x16x32_bf16 v[74:77], v[156:159], v[196:199], v[74:77]
	v_mfma_f32_16x16x32_bf16 v[126:129], v[152:155], v[176:179], v[126:129]
	v_mfma_f32_16x16x32_bf16 v[122:125], v[160:163], v[176:179], v[122:125]
	v_mfma_f32_16x16x32_bf16 v[110:113], v[152:155], v[184:187], v[110:113]
	v_mfma_f32_16x16x32_bf16 v[106:109], v[160:163], v[184:187], v[106:109]
	v_mfma_f32_16x16x32_bf16 v[94:97], v[152:155], v[192:195], v[94:97]
	v_mfma_f32_16x16x32_bf16 v[90:93], v[160:163], v[192:195], v[90:93]
	v_mfma_f32_16x16x32_bf16 v[78:81], v[152:155], v[200:203], v[78:81]
	v_mfma_f32_16x16x32_bf16 v[74:77], v[160:163], v[200:203], v[74:77]
	s_barrier
	s_add_i32 s3, 0, 0x1c000
	s_add_i32 s2, s2, s79
	v_add_u32_e32 v147, s3, v144
	v_lshl_add_u64 v[140:141], v[140:141], 0, s[58:59]
	s_mov_b32 m0, s2
	ds_read_b128 v[204:207], v147
	ds_read_b128 v[208:211], v147 offset:1024
	ds_read_b128 v[212:215], v147 offset:2048
	ds_read_b128 v[216:219], v147 offset:3072
	global_load_lds_dwordx4 v[140:141], off
	v_lshl_add_u64 v[140:141], v[164:165], 0, s[58:59]
	s_add_i32 m0, s2, 0x2000
	s_nop 0
	global_load_lds_dwordx4 v[140:141], off
	s_barrier
	s_waitcnt lgkmcnt(0)
	s_waitcnt lgkmcnt(0)
	v_mfma_f32_16x16x32_bf16 v[118:121], v[204:207], v[168:171], v[118:121]
	v_mfma_f32_16x16x32_bf16 v[114:117], v[212:215], v[168:171], v[114:117]
	v_mfma_f32_16x16x32_bf16 v[102:105], v[204:207], v[180:183], v[102:105]
	v_mfma_f32_16x16x32_bf16 v[98:101], v[212:215], v[180:183], v[98:101]
	v_mfma_f32_16x16x32_bf16 v[86:89], v[204:207], v[188:191], v[86:89]
	v_mfma_f32_16x16x32_bf16 v[82:85], v[212:215], v[188:191], v[82:85]
	v_mfma_f32_16x16x32_bf16 v[70:73], v[204:207], v[196:199], v[70:73]
	v_mfma_f32_16x16x32_bf16 v[66:69], v[212:215], v[196:199], v[66:69]
	v_mfma_f32_16x16x32_bf16 v[118:121], v[208:211], v[176:179], v[118:121]
	v_mfma_f32_16x16x32_bf16 v[114:117], v[216:219], v[176:179], v[114:117]
	v_mfma_f32_16x16x32_bf16 v[102:105], v[208:211], v[184:187], v[102:105]
	v_mfma_f32_16x16x32_bf16 v[98:101], v[216:219], v[184:187], v[98:101]
	v_mfma_f32_16x16x32_bf16 v[86:89], v[208:211], v[192:195], v[86:89]
	v_mfma_f32_16x16x32_bf16 v[82:85], v[216:219], v[192:195], v[82:85]
	v_mfma_f32_16x16x32_bf16 v[70:73], v[208:211], v[200:203], v[70:73]
	v_mfma_f32_16x16x32_bf16 v[66:69], v[216:219], v[200:203], v[66:69]
	s_mov_b32 m0, s83
	v_lshl_add_u64 v[140:141], v[220:221], 0, s[58:59]
	s_barrier
	ds_read_b128 v[168:171], v146 offset:49152
	ds_read_b128 v[176:179], v146 offset:50176
	ds_read_b128 v[180:183], v146 offset:51200
	ds_read_b128 v[184:187], v146 offset:52224
	ds_read_b128 v[188:191], v146 offset:53248
	ds_read_b128 v[192:195], v146 offset:54272
	ds_read_b128 v[196:199], v146 offset:55296
	ds_read_b128 v[200:203], v146 offset:56320
	global_load_lds_dwordx4 v[140:141], off
	v_lshl_add_u64 v[140:141], v[222:223], 0, s[58:59]
	s_mov_b32 m0, s84
	s_nop 0
	global_load_lds_dwordx4 v[140:141], off
	s_barrier
	s_waitcnt lgkmcnt(0)
	s_waitcnt lgkmcnt(0)
	v_mfma_f32_16x16x32_bf16 v[62:65], v[148:151], v[168:171], v[62:65]
	v_mfma_f32_16x16x32_bf16 v[58:61], v[156:159], v[168:171], v[58:61]
	v_mfma_f32_16x16x32_bf16 v[46:49], v[148:151], v[180:183], v[46:49]
	v_mfma_f32_16x16x32_bf16 v[42:45], v[156:159], v[180:183], v[42:45]
	v_mfma_f32_16x16x32_bf16 v[30:33], v[148:151], v[188:191], v[30:33]
	v_mfma_f32_16x16x32_bf16 v[26:29], v[156:159], v[188:191], v[26:29]
	v_mfma_f32_16x16x32_bf16 v[14:17], v[148:151], v[196:199], v[14:17]
	v_mfma_f32_16x16x32_bf16 v[10:13], v[156:159], v[196:199], v[10:13]
	v_mfma_f32_16x16x32_bf16 v[62:65], v[152:155], v[176:179], v[62:65]
	v_mfma_f32_16x16x32_bf16 v[58:61], v[160:163], v[176:179], v[58:61]
	v_mfma_f32_16x16x32_bf16 v[46:49], v[152:155], v[184:187], v[46:49]
	v_mfma_f32_16x16x32_bf16 v[42:45], v[160:163], v[184:187], v[42:45]
	v_mfma_f32_16x16x32_bf16 v[30:33], v[152:155], v[192:195], v[30:33]
	v_mfma_f32_16x16x32_bf16 v[26:29], v[160:163], v[192:195], v[26:29]
	v_mfma_f32_16x16x32_bf16 v[14:17], v[152:155], v[200:203], v[14:17]
	v_mfma_f32_16x16x32_bf16 v[10:13], v[160:163], v[200:203], v[10:13]
	s_barrier
	s_add_u32 s18, s28, 0x40080
	s_addc_u32 s19, s29, 0
	s_add_i32 s2, s3, s79
	v_lshl_add_u64 v[140:141], s[18:19], 0, v[0:1]
	s_mov_b32 m0, s2
	s_nop 0
	global_load_lds_dwordx4 v[140:141], off
	v_lshl_add_u64 v[140:141], s[18:19], 0, v[134:135]
	s_add_i32 m0, s2, 0x2000
	s_nop 0
	global_load_lds_dwordx4 v[140:141], off
	s_waitcnt vmcnt(6)
	s_barrier
	v_mfma_f32_16x16x32_bf16 v[54:57], v[204:207], v[168:171], v[54:57]
	v_mfma_f32_16x16x32_bf16 v[50:53], v[212:215], v[168:171], v[50:53]
	v_mfma_f32_16x16x32_bf16 v[38:41], v[204:207], v[180:183], v[38:41]
	v_mfma_f32_16x16x32_bf16 v[34:37], v[212:215], v[180:183], v[34:37]
	v_mfma_f32_16x16x32_bf16 v[22:25], v[204:207], v[188:191], v[22:25]
	v_mfma_f32_16x16x32_bf16 v[18:21], v[212:215], v[188:191], v[18:21]
	v_mfma_f32_16x16x32_bf16 v[6:9], v[204:207], v[196:199], v[6:9]
	v_mfma_f32_16x16x32_bf16 v[2:5], v[212:215], v[196:199], v[2:5]
	v_mfma_f32_16x16x32_bf16 v[54:57], v[208:211], v[176:179], v[54:57]
	v_mfma_f32_16x16x32_bf16 v[50:53], v[216:219], v[176:179], v[50:53]
	v_mfma_f32_16x16x32_bf16 v[38:41], v[208:211], v[184:187], v[38:41]
	v_mfma_f32_16x16x32_bf16 v[34:37], v[216:219], v[184:187], v[34:37]
	v_mfma_f32_16x16x32_bf16 v[22:25], v[208:211], v[192:195], v[22:25]
	v_mfma_f32_16x16x32_bf16 v[18:21], v[216:219], v[192:195], v[18:21]
	v_mfma_f32_16x16x32_bf16 v[6:9], v[208:211], v[200:203], v[6:9]
	v_mfma_f32_16x16x32_bf16 v[2:5], v[216:219], v[200:203], v[2:5]
	s_add_i32 s41, s41, 2
	s_add_u32 s26, s26, 0x100
	s_addc_u32 s27, s27, 0
	s_add_u32 s36, s36, 0x100
	s_addc_u32 s38, s38, 0
	s_cmp_gt_u32 s41, 13
	s_barrier
	s_cbranch_scc0 .LBB0_490
; DI unsigned pk2(float lo, float hi) { f32x2 f = {lo, hi}; bf2_t v = __builtin_convertvector(f, bf2_t); return __builtin_bit_cast(unsigned, v); }
;     DI void operator()(const f32x4 (&acc)[2][2][4][2], const Unit& u, int wr, int wc, int fr, int fq) const {
;         const int row0 = u.pm * BM + wr * 64 + fr; const int col0 = u.pn * BM + wc * 32 + 8 * fq;
; #pragma unroll
;         for (int ai = 0; ai < 2; ++ai)
; #pragma unroll
;             for (int m = 0; m < 4; ++m) { bf16_t* rowp = O + (size_t)(row0 + ai * HALF + m * 16) * ldc + col0;
; #pragma unroll
;                 for (int bj = 0; bj < 2; ++bj) { f32x4 v0 = acc[ai][bj][m][0], v1 = acc[ai][bj][m][1];
;                     if (ACT == 1) {
; #pragma unroll
;                         for (int j = 0; j < 4; ++j) { float a = fmaxf(v0[j], 0.f), b = fmaxf(v1[j], 0.f); v0[j] = a * a; v1[j] = b * b; } }
;                     u32x4 w; w.x = pk2(v0[0], v0[1]); w.y = pk2(v0[2], v0[3]); w.z = pk2(v1[0], v1[1]); w.w = pk2(v1[2], v1[3]);
;                     *(u32x4*)(rowp + bj * HALF) = w; } }
.Lgemm_epi_b:
	v_lshl_add_u32 v148, s24, 8, v143
	v_lshl_or_b32 v140, s12, 8, v145
	v_ashrrev_i32_e32 v149, 31, v148
	v_ashrrev_i32_e32 v141, 31, v140
	v_lshlrev_b64 v[150:151], 13, v[148:149]
	v_max_f32_e32 v122, v122, v122
	v_max_f32_e32 v123, v123, v123
	v_lshl_add_u64 v[150:151], s[10:11], 0, v[150:151]
	v_lshlrev_b64 v[152:153], 1, v[140:141]
	v_max_f32_e32 v122, 0, v122
	v_max_f32_e32 v123, 0, v123
	v_lshl_add_u64 v[140:141], v[150:151], 0, v[152:153]
	v_pk_mul_f32 v[150:151], v[122:123], v[122:123]
	v_max_f32_e32 v123, v124, v124
	v_max_f32_e32 v126, v126, v126
	v_max_f32_e32 v127, v127, v127
	v_max_f32_e32 v122, v128, v128
	v_max_f32_e32 v124, 0, v123
	v_max_f32_e32 v123, v129, v129
	v_max_f32_e32 v125, v125, v125
	v_max_f32_e32 v126, 0, v126
	v_max_f32_e32 v127, 0, v127
	v_max_f32_e32 v122, 0, v122
	v_max_f32_e32 v123, 0, v123
	v_max_f32_e32 v125, 0, v125
	v_pk_mul_f32 v[126:127], v[126:127], v[126:127]
	v_pk_mul_f32 v[128:129], v[122:123], v[122:123]
	v_pk_mul_f32 v[154:155], v[124:125], v[124:125]
	v_max_f32_e32 v114, v114, v114
	v_max_f32_e32 v115, v115, v115
	v_cvt_pk_bf16_f32 v122, v126, v127
	v_cvt_pk_bf16_f32 v123, v128, v129
	v_cvt_pk_bf16_f32 v124, v150, v151
	v_cvt_pk_bf16_f32 v125, v154, v155
	v_max_f32_e32 v114, 0, v114
	v_max_f32_e32 v115, 0, v115
	global_store_dwordx4 v[140:141], v[122:125], off
	v_max_f32_e32 v118, v118, v118
	v_max_f32_e32 v119, v119, v119
	v_pk_mul_f32 v[122:123], v[114:115], v[114:115]
	v_max_f32_e32 v115, v116, v116
	v_max_f32_e32 v114, v120, v120
	v_max_f32_e32 v116, 0, v115
	v_max_f32_e32 v115, v121, v121
	v_max_f32_e32 v117, v117, v117
	v_max_f32_e32 v118, 0, v118
	v_max_f32_e32 v119, 0, v119
	v_max_f32_e32 v114, 0, v114
	v_max_f32_e32 v115, 0, v115
	v_max_f32_e32 v117, 0, v117
	v_pk_mul_f32 v[118:119], v[118:119], v[118:119]
	v_pk_mul_f32 v[120:121], v[114:115], v[114:115]
	v_pk_mul_f32 v[124:125], v[116:117], v[116:117]
	v_max_f32_e32 v106, v106, v106
	v_max_f32_e32 v107, v107, v107
	v_cvt_pk_bf16_f32 v114, v118, v119
	v_cvt_pk_bf16_f32 v115, v120, v121
	v_cvt_pk_bf16_f32 v116, v122, v123
	v_cvt_pk_bf16_f32 v117, v124, v125
	v_max_f32_e32 v106, 0, v106
	v_max_f32_e32 v107, 0, v107
	global_store_dwordx4 v[140:141], v[114:117], off offset:256
	v_max_f32_e32 v110, v110, v110
	v_max_f32_e32 v111, v111, v111
	v_or_b32_e32 v114, 16, v148
	v_pk_mul_f32 v[116:117], v[106:107], v[106:107]
	v_max_f32_e32 v107, v108, v108
	v_ashrrev_i32_e32 v115, 31, v114
	v_max_f32_e32 v106, v112, v112
	v_max_f32_e32 v108, 0, v107
	v_max_f32_e32 v107, v113, v113
	v_max_f32_e32 v109, v109, v109
	v_lshlrev_b64 v[114:115], 13, v[114:115]
	v_max_f32_e32 v110, 0, v110
	v_max_f32_e32 v111, 0, v111
	v_max_f32_e32 v106, 0, v106
	v_max_f32_e32 v107, 0, v107
	v_max_f32_e32 v109, 0, v109
	v_lshl_add_u64 v[114:115], s[10:11], 0, v[114:115]
	v_pk_mul_f32 v[110:111], v[110:111], v[110:111]
	v_pk_mul_f32 v[112:113], v[106:107], v[106:107]
	v_pk_mul_f32 v[118:119], v[108:109], v[108:109]
	v_max_f32_e32 v98, v98, v98
	v_max_f32_e32 v99, v99, v99
	v_lshl_add_u64 v[114:115], v[114:115], 0, v[152:153]
	v_cvt_pk_bf16_f32 v106, v110, v111
	v_cvt_pk_bf16_f32 v107, v112, v113
	v_cvt_pk_bf16_f32 v108, v116, v117
	v_cvt_pk_bf16_f32 v109, v118, v119
	v_max_f32_e32 v98, 0, v98
	v_max_f32_e32 v99, 0, v99
	global_store_dwordx4 v[114:115], v[106:109], off
	v_max_f32_e32 v102, v102, v102
	v_max_f32_e32 v103, v103, v103
	v_pk_mul_f32 v[106:107], v[98:99], v[98:99]
	v_max_f32_e32 v99, v100, v100
	v_max_f32_e32 v98, v104, v104
	v_max_f32_e32 v100, 0, v99
	v_max_f32_e32 v99, v105, v105
	v_max_f32_e32 v101, v101, v101
	v_max_f32_e32 v102, 0, v102
	v_max_f32_e32 v103, 0, v103
	v_max_f32_e32 v98, 0, v98
	v_max_f32_e32 v99, 0, v99
	v_max_f32_e32 v101, 0, v101
	v_pk_mul_f32 v[102:103], v[102:103], v[102:103]
	v_pk_mul_f32 v[104:105], v[98:99], v[98:99]
	v_pk_mul_f32 v[108:109], v[100:101], v[100:101]
	v_max_f32_e32 v90, v90, v90
	v_max_f32_e32 v91, v91, v91
	v_cvt_pk_bf16_f32 v98, v102, v103
	v_cvt_pk_bf16_f32 v99, v104, v105
	v_cvt_pk_bf16_f32 v100, v106, v107
	v_cvt_pk_bf16_f32 v101, v108, v109
	v_max_f32_e32 v90, 0, v90
	v_max_f32_e32 v91, 0, v91
	global_store_dwordx4 v[114:115], v[98:101], off offset:256
	v_max_f32_e32 v94, v94, v94
	v_max_f32_e32 v95, v95, v95
	v_or_b32_e32 v98, 32, v148
	v_pk_mul_f32 v[100:101], v[90:91], v[90:91]
	v_max_f32_e32 v91, v92, v92
	v_ashrrev_i32_e32 v99, 31, v98
	v_max_f32_e32 v90, v96, v96
	v_max_f32_e32 v92, 0, v91
	v_max_f32_e32 v91, v97, v97
	v_max_f32_e32 v93, v93, v93
	v_lshlrev_b64 v[98:99], 13, v[98:99]
	v_max_f32_e32 v94, 0, v94
	v_max_f32_e32 v95, 0, v95
	v_max_f32_e32 v90, 0, v90
	v_max_f32_e32 v91, 0, v91
	v_max_f32_e32 v93, 0, v93
	v_lshl_add_u64 v[98:99], s[10:11], 0, v[98:99]
	v_pk_mul_f32 v[94:95], v[94:95], v[94:95]
	v_pk_mul_f32 v[96:97], v[90:91], v[90:91]
	v_pk_mul_f32 v[102:103], v[92:93], v[92:93]
	v_max_f32_e32 v82, v82, v82
	v_max_f32_e32 v83, v83, v83
	v_lshl_add_u64 v[98:99], v[98:99], 0, v[152:153]
	v_cvt_pk_bf16_f32 v90, v94, v95
	v_cvt_pk_bf16_f32 v91, v96, v97
	v_cvt_pk_bf16_f32 v92, v100, v101
	v_cvt_pk_bf16_f32 v93, v102, v103
	v_max_f32_e32 v82, 0, v82
	v_max_f32_e32 v83, 0, v83
	global_store_dwordx4 v[98:99], v[90:93], off
	v_max_f32_e32 v86, v86, v86
	v_max_f32_e32 v87, v87, v87
	v_pk_mul_f32 v[90:91], v[82:83], v[82:83]
	v_max_f32_e32 v83, v84, v84
	v_max_f32_e32 v82, v88, v88
	v_max_f32_e32 v84, 0, v83
	v_max_f32_e32 v83, v89, v89
	v_max_f32_e32 v85, v85, v85
	v_max_f32_e32 v86, 0, v86
	v_max_f32_e32 v87, 0, v87
	v_max_f32_e32 v82, 0, v82
	v_max_f32_e32 v83, 0, v83
	v_max_f32_e32 v85, 0, v85
	v_pk_mul_f32 v[86:87], v[86:87], v[86:87]
	v_pk_mul_f32 v[88:89], v[82:83], v[82:83]
; DI unsigned pk2(float lo, float hi) { f32x2 f = {lo, hi}; bf2_t v = __builtin_convertvector(f, bf2_t); return __builtin_bit_cast(unsigned, v); }
;     DI void operator()(const f32x4 (&acc)[2][2][4][2], const Unit& u, int wr, int wc, int fr, int fq) const {
;         const int row0 = u.pm * BM + wr * 64 + fr; const int col0 = u.pn * BM + wc * 32 + 8 * fq;
; #pragma unroll
;         for (int ai = 0; ai < 2; ++ai)
; #pragma unroll
;             for (int m = 0; m < 4; ++m) { bf16_t* rowp = O + (size_t)(row0 + ai * HALF + m * 16) * ldc + col0;
; #pragma unroll
;                 for (int bj = 0; bj < 2; ++bj) { f32x4 v0 = acc[ai][bj][m][0], v1 = acc[ai][bj][m][1];
;                     if (ACT == 1) {
; #pragma unroll
;                         for (int j = 0; j < 4; ++j) { float a = fmaxf(v0[j], 0.f), b = fmaxf(v1[j], 0.f); v0[j] = a * a; v1[j] = b * b; } }
;                     u32x4 w; w.x = pk2(v0[0], v0[1]); w.y = pk2(v0[2], v0[3]); w.z = pk2(v1[0], v1[1]); w.w = pk2(v1[2], v1[3]);
;                     *(u32x4*)(rowp + bj * HALF) = w; } }
	v_pk_mul_f32 v[92:93], v[84:85], v[84:85]
	v_max_f32_e32 v74, v74, v74
	v_max_f32_e32 v75, v75, v75
	v_cvt_pk_bf16_f32 v82, v86, v87
	v_cvt_pk_bf16_f32 v83, v88, v89
	v_cvt_pk_bf16_f32 v84, v90, v91
	v_cvt_pk_bf16_f32 v85, v92, v93
	v_max_f32_e32 v74, 0, v74
	v_max_f32_e32 v75, 0, v75
	global_store_dwordx4 v[98:99], v[82:85], off offset:256
	v_max_f32_e32 v78, v78, v78
	v_max_f32_e32 v79, v79, v79
	v_or_b32_e32 v82, 48, v148
	v_pk_mul_f32 v[84:85], v[74:75], v[74:75]
	v_max_f32_e32 v75, v76, v76
	v_ashrrev_i32_e32 v83, 31, v82
	v_max_f32_e32 v74, v80, v80
	v_max_f32_e32 v76, 0, v75
	v_max_f32_e32 v75, v81, v81
	v_max_f32_e32 v77, v77, v77
	v_lshlrev_b64 v[82:83], 13, v[82:83]
	v_max_f32_e32 v78, 0, v78
	v_max_f32_e32 v79, 0, v79
	v_max_f32_e32 v74, 0, v74
	v_max_f32_e32 v75, 0, v75
	v_max_f32_e32 v77, 0, v77
	v_lshl_add_u64 v[82:83], s[10:11], 0, v[82:83]
	v_pk_mul_f32 v[78:79], v[78:79], v[78:79]
	v_pk_mul_f32 v[80:81], v[74:75], v[74:75]
	v_pk_mul_f32 v[86:87], v[76:77], v[76:77]
	v_max_f32_e32 v66, v66, v66
	v_max_f32_e32 v67, v67, v67
	v_lshl_add_u64 v[82:83], v[82:83], 0, v[152:153]
	v_cvt_pk_bf16_f32 v74, v78, v79
	v_cvt_pk_bf16_f32 v75, v80, v81
	v_cvt_pk_bf16_f32 v76, v84, v85
	v_cvt_pk_bf16_f32 v77, v86, v87
	v_max_f32_e32 v66, 0, v66
	v_max_f32_e32 v67, 0, v67
	global_store_dwordx4 v[82:83], v[74:77], off
	v_max_f32_e32 v70, v70, v70
	v_max_f32_e32 v71, v71, v71
	v_pk_mul_f32 v[74:75], v[66:67], v[66:67]
	v_max_f32_e32 v67, v68, v68
	v_max_f32_e32 v66, v72, v72
	v_max_f32_e32 v68, 0, v67
	v_max_f32_e32 v67, v73, v73
	v_max_f32_e32 v69, v69, v69
	v_max_f32_e32 v70, 0, v70
	v_max_f32_e32 v71, 0, v71
	v_max_f32_e32 v66, 0, v66
	v_max_f32_e32 v67, 0, v67
	v_max_f32_e32 v69, 0, v69
	v_pk_mul_f32 v[70:71], v[70:71], v[70:71]
	v_pk_mul_f32 v[72:73], v[66:67], v[66:67]
	v_pk_mul_f32 v[76:77], v[68:69], v[68:69]
	v_max_f32_e32 v58, v58, v58
	v_max_f32_e32 v59, v59, v59
	v_cvt_pk_bf16_f32 v66, v70, v71
	v_cvt_pk_bf16_f32 v67, v72, v73
	v_cvt_pk_bf16_f32 v68, v74, v75
	v_cvt_pk_bf16_f32 v69, v76, v77
	v_max_f32_e32 v58, 0, v58
	v_max_f32_e32 v59, 0, v59
	global_store_dwordx4 v[82:83], v[66:69], off offset:256
	v_max_f32_e32 v62, v62, v62
	v_max_f32_e32 v63, v63, v63
	v_pk_mul_f32 v[68:69], v[58:59], v[58:59]
	v_max_f32_e32 v59, v60, v60
	v_max_f32_e32 v62, 0, v62
	v_max_f32_e32 v63, 0, v63
	v_max_f32_e32 v58, v64, v64
	v_max_f32_e32 v60, 0, v59
	v_max_f32_e32 v59, v65, v65
	v_max_f32_e32 v61, v61, v61
	v_pk_mul_f32 v[62:63], v[62:63], v[62:63]
	v_max_f32_e32 v58, 0, v58
	v_max_f32_e32 v59, 0, v59
	v_max_f32_e32 v61, 0, v61
	v_pk_mul_f32 v[64:65], v[58:59], v[58:59]
	v_pk_mul_f32 v[70:71], v[60:61], v[60:61]
	v_cvt_pk_bf16_f32 v58, v62, v63
	v_add_co_u32_e32 v62, vcc, s74, v140
	v_max_f32_e32 v50, v50, v50
	v_max_f32_e32 v51, v51, v51
	v_cvt_pk_bf16_f32 v59, v64, v65
	v_cvt_pk_bf16_f32 v60, v68, v69
	v_cvt_pk_bf16_f32 v61, v70, v71
	v_addc_co_u32_e32 v63, vcc, 0, v141, vcc
	v_max_f32_e32 v50, 0, v50
	v_max_f32_e32 v51, 0, v51
	global_store_dwordx4 v[62:63], v[58:61], off
	v_max_f32_e32 v54, v54, v54
	v_max_f32_e32 v55, v55, v55
	v_pk_mul_f32 v[58:59], v[50:51], v[50:51]
	v_max_f32_e32 v51, v52, v52
	v_max_f32_e32 v50, v56, v56
	v_max_f32_e32 v52, 0, v51
	v_max_f32_e32 v51, v57, v57
	v_max_f32_e32 v53, v53, v53
	v_max_f32_e32 v54, 0, v54
	v_max_f32_e32 v55, 0, v55
	v_max_f32_e32 v50, 0, v50
	v_max_f32_e32 v51, 0, v51
	v_max_f32_e32 v53, 0, v53
	s_mov_b64 s[12:13], 0x100000
	v_pk_mul_f32 v[54:55], v[54:55], v[54:55]
	v_pk_mul_f32 v[56:57], v[50:51], v[50:51]
	v_pk_mul_f32 v[60:61], v[52:53], v[52:53]
	v_max_f32_e32 v42, v42, v42
	v_max_f32_e32 v43, v43, v43
	v_lshl_add_u64 v[66:67], v[140:141], 0, s[12:13]
	v_cvt_pk_bf16_f32 v50, v54, v55
	v_cvt_pk_bf16_f32 v51, v56, v57
	v_cvt_pk_bf16_f32 v52, v58, v59
	v_cvt_pk_bf16_f32 v53, v60, v61
	v_max_f32_e32 v42, 0, v42
	v_max_f32_e32 v43, 0, v43
	global_store_dwordx4 v[66:67], v[50:53], off offset:256
	v_max_f32_e32 v46, v46, v46
	v_max_f32_e32 v47, v47, v47
	v_pk_mul_f32 v[52:53], v[42:43], v[42:43]
	v_max_f32_e32 v43, v44, v44
	v_max_f32_e32 v46, 0, v46
	v_max_f32_e32 v47, 0, v47
	v_max_f32_e32 v42, v48, v48
	v_max_f32_e32 v44, 0, v43
	v_max_f32_e32 v43, v49, v49
	v_max_f32_e32 v45, v45, v45
	v_pk_mul_f32 v[46:47], v[46:47], v[46:47]
	v_max_f32_e32 v42, 0, v42
	v_max_f32_e32 v43, 0, v43
	v_max_f32_e32 v45, 0, v45
	s_mov_b32 s2, 0x120000
	v_pk_mul_f32 v[48:49], v[42:43], v[42:43]
	v_pk_mul_f32 v[54:55], v[44:45], v[44:45]
	v_cvt_pk_bf16_f32 v42, v46, v47
	v_add_co_u32_e32 v46, vcc, s2, v140
	v_max_f32_e32 v34, v34, v34
	v_max_f32_e32 v35, v35, v35
	v_cvt_pk_bf16_f32 v43, v48, v49
	v_cvt_pk_bf16_f32 v44, v52, v53
	v_cvt_pk_bf16_f32 v45, v54, v55
; DI unsigned pk2(float lo, float hi) { f32x2 f = {lo, hi}; bf2_t v = __builtin_convertvector(f, bf2_t); return __builtin_bit_cast(unsigned, v); }
; #define PG8_WAIT_V(n) asm volatile("s_waitcnt vmcnt(" #n ")" ::: "memory")
; #define PG8_BAR __builtin_amdgcn_s_barrier()
;     DI void operator()(const f32x4 (&acc)[2][2][4][2], const Unit& u, int wr, int wc, int fr, int fq) const {
;         const int row0 = u.pm * BM + wr * 64 + fr; const int col0 = u.pn * BM + wc * 32 + 8 * fq;
; #pragma unroll
;         for (int ai = 0; ai < 2; ++ai)
; #pragma unroll
;             for (int m = 0; m < 4; ++m) { bf16_t* rowp = O + (size_t)(row0 + ai * HALF + m * 16) * ldc + col0;
; #pragma unroll
;                 for (int bj = 0; bj < 2; ++bj) { f32x4 v0 = acc[ai][bj][m][0], v1 = acc[ai][bj][m][1];
;                     if (ACT == 1) {
; #pragma unroll
;                         for (int j = 0; j < 4; ++j) { float a = fmaxf(v0[j], 0.f), b = fmaxf(v1[j], 0.f); v0[j] = a * a; v1[j] = b * b; } }
;                     u32x4 w; w.x = pk2(v0[0], v0[1]); w.y = pk2(v0[2], v0[3]); w.z = pk2(v1[0], v1[1]); w.w = pk2(v1[2], v1[3]);
;                     *(u32x4*)(rowp + bj * HALF) = w; } }
; template <class Epi>
; DI void gemm_phase(int wv, LAS unsigned char* lds, const GemmD g, const Epi& E) {
;     ...
;         E(acc, cur, wr, wc, fr, fq);
;         if (!has_next) break;
; #pragma unroll
;         for (int a = 0; a < 2; ++a)
; #pragma unroll
;             for (int b = 0; b < 2; ++b)
; #pragma unroll
;                 for (int m = 0; m < 4; ++m)
; #pragma unroll
;                     for (int n = 0; n < 2; ++n) acc[a][b][m][n] = (f32x4){0.f, 0.f, 0.f, 0.f};
;         cur = nxt; cA = nA; cB = nB; ++ui;
;     }
;     PG8_WAIT_V(0);
;     if (wr == 0) PG8_BAR;
;     PG8_BAR;
	v_addc_co_u32_e32 v47, vcc, 0, v141, vcc
	v_max_f32_e32 v34, 0, v34
	v_max_f32_e32 v35, 0, v35
	global_store_dwordx4 v[46:47], v[42:45], off
	v_max_f32_e32 v38, v38, v38
	v_max_f32_e32 v39, v39, v39
	v_pk_mul_f32 v[42:43], v[34:35], v[34:35]
	v_max_f32_e32 v35, v36, v36
	v_max_f32_e32 v34, v40, v40
	v_max_f32_e32 v36, 0, v35
	v_max_f32_e32 v35, v41, v41
	v_max_f32_e32 v37, v37, v37
	v_max_f32_e32 v38, 0, v38
	v_max_f32_e32 v39, 0, v39
	v_max_f32_e32 v34, 0, v34
	v_max_f32_e32 v35, 0, v35
	v_max_f32_e32 v37, 0, v37
	s_mov_b64 s[12:13], 0x120000
	v_pk_mul_f32 v[38:39], v[38:39], v[38:39]
	v_pk_mul_f32 v[40:41], v[34:35], v[34:35]
	v_pk_mul_f32 v[44:45], v[36:37], v[36:37]
	v_max_f32_e32 v26, v26, v26
	v_max_f32_e32 v27, v27, v27
	v_lshl_add_u64 v[50:51], v[140:141], 0, s[12:13]
	v_cvt_pk_bf16_f32 v34, v38, v39
	v_cvt_pk_bf16_f32 v35, v40, v41
	v_cvt_pk_bf16_f32 v36, v42, v43
	v_cvt_pk_bf16_f32 v37, v44, v45
	v_max_f32_e32 v26, 0, v26
	v_max_f32_e32 v27, 0, v27
	global_store_dwordx4 v[50:51], v[34:37], off offset:256
	v_max_f32_e32 v30, v30, v30
	v_max_f32_e32 v31, v31, v31
	v_pk_mul_f32 v[36:37], v[26:27], v[26:27]
	v_max_f32_e32 v27, v28, v28
	v_max_f32_e32 v30, 0, v30
	v_max_f32_e32 v31, 0, v31
	v_max_f32_e32 v26, v32, v32
	v_max_f32_e32 v28, 0, v27
	v_max_f32_e32 v27, v33, v33
	v_max_f32_e32 v29, v29, v29
	v_pk_mul_f32 v[30:31], v[30:31], v[30:31]
	v_max_f32_e32 v26, 0, v26
	v_max_f32_e32 v27, 0, v27
	v_max_f32_e32 v29, 0, v29
	s_mov_b32 s2, 0x140000
	v_pk_mul_f32 v[32:33], v[26:27], v[26:27]
	v_pk_mul_f32 v[38:39], v[28:29], v[28:29]
	v_cvt_pk_bf16_f32 v26, v30, v31
	v_add_co_u32_e32 v30, vcc, s2, v140
	v_max_f32_e32 v18, v18, v18
	v_max_f32_e32 v19, v19, v19
	v_cvt_pk_bf16_f32 v27, v32, v33
	v_cvt_pk_bf16_f32 v28, v36, v37
	v_cvt_pk_bf16_f32 v29, v38, v39
	v_addc_co_u32_e32 v31, vcc, 0, v141, vcc
	v_max_f32_e32 v18, 0, v18
	v_max_f32_e32 v19, 0, v19
	global_store_dwordx4 v[30:31], v[26:29], off
	v_max_f32_e32 v22, v22, v22
	v_max_f32_e32 v23, v23, v23
	v_pk_mul_f32 v[26:27], v[18:19], v[18:19]
	v_max_f32_e32 v19, v20, v20
	v_max_f32_e32 v18, v24, v24
	v_max_f32_e32 v20, 0, v19
	v_max_f32_e32 v19, v25, v25
	v_max_f32_e32 v21, v21, v21
	v_max_f32_e32 v22, 0, v22
	v_max_f32_e32 v23, 0, v23
	v_max_f32_e32 v18, 0, v18
	v_max_f32_e32 v19, 0, v19
	v_max_f32_e32 v21, 0, v21
	s_mov_b64 s[12:13], 0x140000
	v_pk_mul_f32 v[22:23], v[22:23], v[22:23]
	v_pk_mul_f32 v[24:25], v[18:19], v[18:19]
	v_pk_mul_f32 v[28:29], v[20:21], v[20:21]
	v_max_f32_e32 v10, v10, v10
	v_max_f32_e32 v11, v11, v11
	v_lshl_add_u64 v[34:35], v[140:141], 0, s[12:13]
	v_cvt_pk_bf16_f32 v18, v22, v23
	v_cvt_pk_bf16_f32 v19, v24, v25
	v_cvt_pk_bf16_f32 v20, v26, v27
	v_cvt_pk_bf16_f32 v21, v28, v29
	v_max_f32_e32 v10, 0, v10
	v_max_f32_e32 v11, 0, v11
	global_store_dwordx4 v[34:35], v[18:21], off offset:256
	v_max_f32_e32 v14, v14, v14
	v_max_f32_e32 v15, v15, v15
	v_pk_mul_f32 v[20:21], v[10:11], v[10:11]
	v_max_f32_e32 v11, v12, v12
	v_max_f32_e32 v14, 0, v14
	v_max_f32_e32 v15, 0, v15
	v_max_f32_e32 v10, v16, v16
	v_max_f32_e32 v12, 0, v11
	v_max_f32_e32 v11, v17, v17
	v_max_f32_e32 v13, v13, v13
	v_pk_mul_f32 v[14:15], v[14:15], v[14:15]
	v_max_f32_e32 v10, 0, v10
	v_max_f32_e32 v11, 0, v11
	v_max_f32_e32 v13, 0, v13
	s_mov_b32 s2, 0x160000
	v_pk_mul_f32 v[16:17], v[10:11], v[10:11]
	v_pk_mul_f32 v[22:23], v[12:13], v[12:13]
	v_cvt_pk_bf16_f32 v10, v14, v15
	v_add_co_u32_e32 v14, vcc, s2, v140
	v_max_f32_e32 v2, v2, v2
	v_max_f32_e32 v3, v3, v3
	v_cvt_pk_bf16_f32 v11, v16, v17
	v_cvt_pk_bf16_f32 v12, v20, v21
	v_cvt_pk_bf16_f32 v13, v22, v23
	v_addc_co_u32_e32 v15, vcc, 0, v141, vcc
	v_max_f32_e32 v2, 0, v2
	v_max_f32_e32 v3, 0, v3
	global_store_dwordx4 v[14:15], v[10:13], off
	v_max_f32_e32 v6, v6, v6
	v_max_f32_e32 v7, v7, v7
	v_pk_mul_f32 v[10:11], v[2:3], v[2:3]
	v_max_f32_e32 v3, v4, v4
	v_max_f32_e32 v2, v8, v8
	v_max_f32_e32 v4, 0, v3
	v_max_f32_e32 v3, v9, v9
	v_max_f32_e32 v5, v5, v5
	v_max_f32_e32 v6, 0, v6
	v_max_f32_e32 v7, 0, v7
	v_max_f32_e32 v2, 0, v2
	v_max_f32_e32 v3, 0, v3
	v_max_f32_e32 v5, 0, v5
	s_mov_b64 s[12:13], 0x160000
	v_pk_mul_f32 v[6:7], v[6:7], v[6:7]
	v_pk_mul_f32 v[8:9], v[2:3], v[2:3]
	v_pk_mul_f32 v[12:13], v[4:5], v[4:5]
	v_lshl_add_u64 v[18:19], v[140:141], 0, s[12:13]
	v_cvt_pk_bf16_f32 v2, v6, v7
	v_cvt_pk_bf16_f32 v3, v8, v9
	v_cvt_pk_bf16_f32 v4, v10, v11
	v_cvt_pk_bf16_f32 v5, v12, v13
	s_and_b64 vcc, exec, s[0:1]
	s_mov_b32 s12, s86
	s_mov_b32 s24, s6
	s_mov_b64 s[28:29], s[22:23]
	s_mov_b64 s[26:27], s[8:9]
	global_store_dwordx4 v[18:19], v[2:5], off offset:256
	s_cbranch_vccz .LBB0_483
	s_waitcnt vmcnt(0)
	s_setprio 0
	s_cmpk_gt_u32 s35, 0xff
	s_cbranch_scc1 .LBB0_494
	s_barrier

; DI int mk_tid(int wv) { int w = wv; asm volatile("" : "+s"(w)); int l = __builtin_amdgcn_mbcnt_hi(~0u, __builtin_amdgcn_mbcnt_lo(~0u, 0u)); asm volatile("" : "+v"(l)); return w * 64 + l; }
; DI int opaque_bid() { int b = blockIdx.x; asm volatile("" : "+s"(b)); return b; }
; #define PG8_WAIT_V(n) asm volatile("s_waitcnt vmcnt(" #n ")" ::: "memory")
; #define PG8_BAR __builtin_amdgcn_s_barrier()
; template <class Epi>
; DI void gemm_phase(int wv, LAS unsigned char* lds, const GemmD g, const Epi& E) {
;     const int tid = mk_tid(wv), wid = __builtin_amdgcn_readfirstlane(tid >> 6), lane = tid & 63, wr = wid >> 2, wc = wid & 3, fr = lane & 15, fq = lane >> 4;
;     const int K = g.K, nt = K / BK;
;     const int ldbe = g.ldb * g.dil;
;     unsigned voffA[2], voffB[2];
; #pragma unroll
;     for (int i = 0; i < 2; ++i) { int R, C; stage_rc(tid * 16 + i * 8192, R, C); const int Rb = Epi::PERM ? ((R & ~31) + perm32(R & 31)) : R;
;         voffA[i] = (unsigned)(R * g.lda + C) * 2u; voffB[i] = (unsigned)(Rb * ldbe + C) * 2u; }
;     const size_t kstep = (size_t)(BK * 2);
;     const size_t hstepA = (size_t)HALF * g.lda * 2, hstepB = (size_t)HALF * ldbe * 2;
;     const unsigned ldsw = (unsigned)wid * 1024u;
;     const int aoff = lds_byte(wr * 64 + fr, fq * 8), boff = lds_byte(wc * 32 + fr, fq * 8);
;     ...
;     StaticOrder S; S.init(g.nM, g.nN, (int)gridDim.x, opaque_bid());
;     Unit cur, nxt; int ui = 0;
;     if (!S.next(0, cur)) return;
;     f32x4 acc[2][2][4][2];
; #pragma unroll
;     for (int a = 0; a < 2; ++a)
; #pragma unroll
;         for (int b = 0; b < 2; ++b)
; #pragma unroll
;             for (int m = 0; m < 4; ++m)
; #pragma unroll
;                 for (int n = 0; n < 2; ++n) acc[a][b][m][n] = (f32x4){0.f, 0.f, 0.f, 0.f};
;     bf16x8 At[4][2], B0[2][2], B1[2][2];
;     ...
;     const char* cA = (const char*)g.A + (size_t)cur.pm * 256 * g.lda * 2; const char* cB = (const char*)g.Bt + PG8_BROW(cur.pn) * (size_t)g.ldb * 2;
;     PG8_STAGE(PG8_SB(0, 0), cB, voffB); PG8_STAGE(PG8_SA(0, 0), cA, voffA); PG8_STAGE(PG8_SB(0, 1), cB + hstepB, voffB); PG8_STAGE(PG8_SA(0, 1), cA + hstepA, voffA);
;     if (wr == 1) PG8_BAR;
;     PG8_WAIT_V(4); PG8_BAR;
;     PG8_STAGE(PG8_SB(1, 0), cB + kstep, voffB); PG8_STAGE(PG8_SA(1, 0), cA + kstep, voffA); PG8_STAGE(PG8_SB(1, 1), cB + hstepB + kstep, voffB);
;     PG8_WAIT_V(6); PG8_BAR;
.LBB0_534:
	v_ashrrev_i32_e32 v3, 31, v0
	v_lshrrev_b32_e32 v3, 26, v3
	v_lshlrev_b32_e32 v2, 4, v0
	v_add_u32_e32 v3, v0, v3
	v_bfe_i32 v0, v0, 27, 1
	v_lshrrev_b32_e32 v0, 22, v0
	v_add_u32_e32 v0, v2, v0
	v_and_b32_e32 v0, 0xfffffc00, v0
	v_sub_u32_e32 v0, v2, v0
	v_lshrrev_b32_e32 v4, 4, v0
	v_bitop3_b32 v0, v4, v0, 32 bitop3:0x6c
	s_waitcnt lgkmcnt(0)
	v_ashrrev_i32_e32 v5, 31, v0
	v_lshrrev_b32_e32 v5, 26, v5
	v_ashrrev_i32_e32 v3, 6, v3
	v_add_u32_e32 v5, v0, v5
	s_and_b64 s[12:13], s[4:5], exec
	v_readlane_b32 s2, v253, 36
	v_lshlrev_b32_e32 v4, 3, v3
	v_ashrrev_i32_e32 v6, 6, v5
	v_and_b32_e32 v5, 0xc0, v5
	v_readlane_b32 s3, v253, 37
	s_cselect_b32 s81, s2, s10
	s_cselect_b32 s2, 0, 0xa00000
	v_and_b32_e32 v4, -16, v4
	v_lshlrev_b32_e32 v3, 5, v3
	v_sub_u32_e32 v0, v0, v5
	s_cselect_b32 s80, s3, s11
	s_cselect_b32 s16, 0x400, s77
	s_add_u32 s82, s15, s2
	v_readlane_b32 s2, v253, 30
	v_add_u32_e32 v4, v6, v4
	v_and_b32_e32 v3, 32, v3
	v_ashrrev_i16_sdwa v0, v244, sext(v0) dst_sel:DWORD dst_unused:UNUSED_PAD src0_sel:DWORD src1_sel:BYTE_0
	s_addc_u32 s83, s2, 0
	s_ashr_i32 s13, s78, 6
	v_add_u32_sdwa v0, v3, sext(v0) dst_sel:DWORD dst_unused:UNUSED_PAD src0_sel:DWORD src1_sel:WORD_0
	v_lshlrev_b32_e32 v3, 1, v4
	v_lshrrev_b32_e32 v5, 2, v4
	v_and_b32_e32 v6, 3, v6
	s_mov_b32 s3, 0x7fffffe0
	v_and_b32_e32 v3, 24, v3
	v_and_b32_e32 v5, 4, v5
	v_and_or_b32 v6, v4, s3, v6
	s_and_b64 s[18:19], s[4:5], exec
	v_or3_b32 v3, v6, v5, v3
	s_cselect_b32 s2, 10, 12
	v_lshlrev_b32_e32 v4, s2, v4
	v_lshlrev_b32_e32 v3, s2, v3
	v_add_u32_e32 v2, 0x2000, v2
	v_add_lshl_u32 v130, v0, v4, 1
	v_add_lshl_u32 v0, v3, v0, 1
	v_ashrrev_i32_e32 v3, 31, v2
	v_lshrrev_b32_e32 v3, 22, v3
	v_add_u32_e32 v3, v2, v3
	v_ashrrev_i32_e32 v3, 10, v3
	v_mul_i32_i24_e32 v4, 0x400, v3
	v_sub_u32_e32 v2, v2, v4
	v_lshrrev_b32_e32 v4, 4, v2
	v_bitop3_b32 v2, v4, v2, 32 bitop3:0x6c
	v_ashrrev_i32_e32 v5, 31, v2
	v_lshrrev_b32_e32 v5, 26, v5
	v_add_u32_e32 v5, v2, v5
	v_lshlrev_b32_e32 v4, 3, v3
	v_ashrrev_i32_e32 v6, 6, v5
	v_and_b32_e32 v5, 0xc0, v5
	v_and_b32_e32 v4, -16, v4
	v_lshlrev_b32_e32 v3, 5, v3
	v_sub_u32_e32 v2, v2, v5
	v_add_u32_e32 v4, v6, v4
	v_and_b32_e32 v3, 32, v3
	v_ashrrev_i16_sdwa v2, v244, sext(v2) dst_sel:DWORD dst_unused:UNUSED_PAD src0_sel:DWORD src1_sel:BYTE_0
	v_add_u32_sdwa v2, v3, sext(v2) dst_sel:DWORD dst_unused:UNUSED_PAD src0_sel:DWORD src1_sel:WORD_0
	v_lshlrev_b32_e32 v3, 1, v4
	v_lshrrev_b32_e32 v5, 2, v4
	v_and_b32_e32 v6, 3, v6
	v_and_b32_e32 v3, 24, v3
	v_and_b32_e32 v5, 4, v5
	v_and_or_b32 v6, v4, s3, v6
	v_or3_b32 v3, v6, v5, v3
	v_lshlrev_b32_e32 v4, s2, v4
	v_lshlrev_b32_e32 v3, s2, v3
	s_add_i32 s2, s8, s6
	s_ashr_i32 s3, s2, 31
	s_lshr_b32 s3, s3, 27
	s_add_i32 s3, s2, s3
	s_ashr_i32 s6, s3, 5
	s_and_b32 s3, s3, 0xffe0
	s_sub_i32 s2, s2, s3
	s_bfe_i32 s3, s2, 0x80000
	s_bfe_u32 s3, s3, 0x3000c
	s_add_i32 s3, s2, s3
	s_bfe_i32 s7, s3, 0x80000
	s_and_b32 s3, s3, 0xf8
	s_sub_i32 s2, s2, s3
	s_lshl_b32 s6, s6, 3
	s_sext_i32_i8 s2, s2
	s_sext_i32_i16 s7, s7
	s_add_i32 s8, s6, s2
	s_ashr_i32 s17, s78, 8
	s_lshl_b32 s56, s16, 8
	s_lshl_b32 s84, s13, 10
	s_ashr_i32 s12, s7, 3
	s_ashr_i32 s9, s8, 31
	s_and_b64 s[6:7], s[4:5], exec
	s_cselect_b32 s85, 19, 21
	s_lshl_b32 s18, s12, 8
	s_lshl_b64 s[6:7], s[8:9], s85
	s_ashr_i32 s19, s18, 31
	s_and_b64 s[22:23], s[4:5], exec
	s_cselect_b32 s9, 11, 13
	s_lshl_b64 s[18:19], s[18:19], s9
	s_add_u32 s30, s82, s18
	s_addc_u32 s31, s83, s19
	s_add_i32 s86, s84, 0
	s_add_i32 m0, s86, 0x10000
	v_add_lshl_u32 v134, v3, v2, 1
	global_load_lds_dwordx4 v0, s[30:31]
	s_add_i32 m0, s86, 0x12000
	s_add_u32 s28, s81, s6
	global_load_lds_dwordx4 v134, s[30:31]
	s_addc_u32 s29, s80, s7
	s_mov_b32 m0, s86
	s_add_i32 s87, s86, 0x2000
	v_add_lshl_u32 v132, v2, v4, 1
	global_load_lds_dwordx4 v130, s[28:29]
	s_mov_b32 m0, s87
	s_add_u32 s6, s30, s56
	global_load_lds_dwordx4 v132, s[28:29]
	s_addc_u32 s7, s31, 0
	s_add_i32 m0, s86, 0x14000
	v_mov_b32_e32 v135, v1
	global_load_lds_dwordx4 v0, s[6:7]
	s_add_i32 m0, s86, 0x16000
	v_lshl_add_u64 v[10:11], s[6:7], 0, v[0:1]
	v_lshl_add_u64 v[12:13], s[6:7], 0, v[134:135]
	global_load_lds_dwordx4 v134, s[6:7]
	s_add_u32 s6, s28, s56
	s_addc_u32 s7, s29, 0
	s_add_i32 s74, s86, 0x4000
	s_mov_b32 m0, s74
	s_add_i32 s41, s86, 0x6000
	global_load_lds_dwordx4 v130, s[6:7]
	s_mov_b32 m0, s41
	v_mov_b32_e32 v131, v1
	global_load_lds_dwordx4 v132, s[6:7]
	v_mov_b32_e32 v133, v1
	v_lshl_add_u64 v[2:3], s[30:31], 0, v[0:1]
	v_lshl_add_u64 v[4:5], s[30:31], 0, v[134:135]
	v_lshl_add_u64 v[6:7], s[28:29], 0, v[130:131]
	v_lshl_add_u64 v[8:9], s[28:29], 0, v[132:133]
	s_cmp_lg_u32 s17, 1
	s_cbranch_scc1 .LBB0_536
	s_setprio 1
	s_barrier

; #define PG8_STAGE(bufoff, gbase, voff) do { _Pragma("unroll") for (int _i = 0; _i < 2; ++_i) \
;         __builtin_amdgcn_global_load_lds((const unsigned*)((const char*)(gbase) + (voff)[_i]), (LAS unsigned*)(lds + (bufoff) + ldsw + _i * 8192), 16, 0, 0); } while (0)
; #define PG8_LDA(dst, b, h) do { _Pragma("unroll") for (int m = 0; m < 4; ++m) _Pragma("unroll") for (int k = 0; k < 2; ++k) dst[m][k] = *(const LAS bf16x8*)(lds + PG8_SA(b, h) + aoff + m * 2048 + k * 1024); } while (0)
; #define PG8_LDB(dst, b, h) do { _Pragma("unroll") for (int n = 0; n < 2; ++n) _Pragma("unroll") for (int k = 0; k < 2; ++k) dst[n][k] = *(const LAS bf16x8*)(lds + PG8_SB(b, h) + boff + n * 2048 + k * 1024); } while (0)
; #define PG8_MMA(ai, bj, At, Bt) do { __builtin_amdgcn_s_setprio(1); _Pragma("unroll") for (int m = 0; m < 4; ++m) _Pragma("unroll") for (int n = 0; n < 2; ++n) _Pragma("unroll") for (int k = 0; k < 2; ++k) \
;         acc[ai][bj][m][n] = __builtin_amdgcn_mfma_f32_16x16x32_bf16(Bt[n][k], At[m][k], acc[ai][bj][m][n], 0, 0, 0); __builtin_amdgcn_s_setprio(0); } while (0)
; #define PG8_WAIT_L(n) asm volatile("s_waitcnt lgkmcnt(" #n ")" ::: "memory")
; template <class Epi>
; DI void gemm_phase(int wv, LAS unsigned char* lds, const GemmD g, const Epi& E) {
;     ...
;         const bool has_next = S.next(ui + 1, nxt);
;         const char* nA = has_next ? (const char*)g.A + (size_t)nxt.pm * 256 * g.lda * 2 : cA; const char* nB = has_next ? (const char*)g.Bt + PG8_BROW(nxt.pn) * (size_t)g.ldb * 2 : cB;
;         for (int t = 0; t < nt; t += 2) {
;             const bool last = (t == nt - 2);
;             const char* a1 = cA + (size_t)(t + 1) * kstep;
;             const char* a2 = last ? nA : cA + (size_t)(t + 2) * kstep; const char* b2 = last ? nB : cB + (size_t)(t + 2) * kstep;
;             const char* a3 = a2 + kstep; const char* b3 = b2 + kstep;
;             PG8_LDB(B0, 0, 0); PG8_SCHED; PG8_LDA(At, 0, 0); PG8_STAGE(PG8_SA(1, 1), a1 + hstepA, voffA);
;             PG8_WAIT_L(8); PG8_BAR; PG8_WAIT_L(0); PG8_MMA(0, 0, At, B0); PG8_BAR; PG8_SCHED;
;             PG8_LDB(B1, 0, 1); PG8_STAGE(PG8_SB(0, 0), b2, voffB);
;             PG8_BAR; PG8_WAIT_L(0); PG8_MMA(0, 1, At, B1); PG8_BAR;
;             PG8_LDA(At, 0, 1); PG8_STAGE(PG8_SA(0, 0), a2, voffA);
;             PG8_BAR; PG8_WAIT_L(0); PG8_MMA(1, 0, At, B0); PG8_BAR; PG8_SCHED;
.LBB0_543:
	s_ashr_i32 s23, s22, 31
	s_lshl_b64 s[18:19], s[22:23], s85
	v_cmp_lt_i64_e32 vcc, s[24:25], v[174:175]
	s_add_u32 s24, s81, s18
	s_addc_u32 s25, s80, s19
	s_and_b64 s[18:19], vcc, exec
	s_cselect_b32 s23, s25, s29
	s_cselect_b32 s68, s24, s28
	s_lshl_b32 s18, s55, 8
	s_ashr_i32 s19, s18, 31
	s_lshl_b64 s[18:19], s[18:19], s9
	s_add_u32 s26, s82, s18
	s_addc_u32 s27, s83, s19
	s_and_b64 s[18:19], vcc, exec
	s_cselect_b32 vcc_lo, s27, s31
	s_cselect_b32 vcc_hi, s26, s30
	s_add_u32 s28, s28, 0x80
	s_addc_u32 s29, s29, 0
	s_add_u32 s37, s30, 0x100
	s_addc_u32 s18, s31, 0
	s_mov_b32 s19, 0
	s_add_i32 s95, s19, 2
	s_add_u32 s2, s28, 0x80
	s_addc_u32 s3, s29, 0
	s_add_i32 s94, 0, 0x10000
	v_add_u32_e32 v145, s94, v141
	ds_read_b128 v[146:149], v145
	ds_read_b128 v[150:153], v145 offset:1024
	ds_read_b128 v[154:157], v145 offset:2048
	ds_read_b128 v[158:161], v145 offset:3072
	s_cmp_eq_u32 s17, s19
	s_cselect_b32 s31, s23, s3
	s_cselect_b32 s30, s68, s2
	s_cselect_b32 s35, vcc_lo, s18
	s_cselect_b32 s34, vcc_hi, s37
	v_lshl_add_u64 v[200:201], s[28:29], 0, v[136:137]
	s_add_i32 m0, s86, 0xc000
	ds_read_b128 v[162:165], v144
	ds_read_b128 v[168:171], v144 offset:1024
	ds_read_b128 v[176:179], v144 offset:2048
	ds_read_b128 v[180:183], v144 offset:3072
	ds_read_b128 v[184:187], v144 offset:4096
	ds_read_b128 v[188:191], v144 offset:5120
	ds_read_b128 v[192:195], v144 offset:6144
	ds_read_b128 v[196:199], v144 offset:7168
	global_load_lds_dwordx4 v[200:201], off
	v_lshl_add_u64 v[200:201], s[28:29], 0, v[138:139]
	s_add_i32 m0, s86, 0xe000
	s_nop 0
	global_load_lds_dwordx4 v[200:201], off
	s_waitcnt lgkmcnt(8)
	s_barrier
	s_waitcnt lgkmcnt(0)
	s_waitcnt lgkmcnt(0)
	v_mfma_f32_16x16x32_bf16 v[126:129], v[146:149], v[162:165], 0
	v_mfma_f32_16x16x32_bf16 v[122:125], v[154:157], v[162:165], 0
	v_mfma_f32_16x16x32_bf16 v[118:121], v[146:149], v[176:179], 0
	v_mfma_f32_16x16x32_bf16 v[114:117], v[154:157], v[176:179], 0
	v_mfma_f32_16x16x32_bf16 v[102:105], v[146:149], v[184:187], 0
	v_mfma_f32_16x16x32_bf16 v[98:101], v[154:157], v[184:187], 0
	v_mfma_f32_16x16x32_bf16 v[86:89], v[146:149], v[192:195], 0
	v_mfma_f32_16x16x32_bf16 v[82:85], v[154:157], v[192:195], 0
	v_mfma_f32_16x16x32_bf16 v[126:129], v[150:153], v[168:171], v[126:129]
	v_mfma_f32_16x16x32_bf16 v[122:125], v[158:161], v[168:171], v[122:125]
	v_mfma_f32_16x16x32_bf16 v[118:121], v[150:153], v[180:183], v[118:121]
	v_mfma_f32_16x16x32_bf16 v[114:117], v[158:161], v[180:183], v[114:117]
	v_mfma_f32_16x16x32_bf16 v[102:105], v[150:153], v[188:191], v[102:105]
	v_mfma_f32_16x16x32_bf16 v[98:101], v[158:161], v[188:191], v[98:101]
	v_mfma_f32_16x16x32_bf16 v[86:89], v[150:153], v[196:199], v[86:89]
	v_mfma_f32_16x16x32_bf16 v[82:85], v[158:161], v[196:199], v[82:85]
	s_barrier
	s_add_i32 s2, 0, 0x14000
	s_add_i32 s3, s94, s84
	v_add_u32_e32 v145, s2, v141
	v_lshl_add_u64 v[216:217], s[34:35], 0, v[0:1]
	s_mov_b32 m0, s3
	ds_read_b128 v[200:203], v145
	ds_read_b128 v[204:207], v145 offset:1024
	ds_read_b128 v[208:211], v145 offset:2048
	ds_read_b128 v[212:215], v145 offset:3072
	global_load_lds_dwordx4 v[216:217], off
	v_lshl_add_u64 v[218:219], s[34:35], 0, v[134:135]
	s_add_i32 m0, s3, 0x2000
	s_nop 0
	global_load_lds_dwordx4 v[218:219], off
	s_barrier
	s_waitcnt lgkmcnt(0)
	s_waitcnt lgkmcnt(0)
	v_mfma_f32_16x16x32_bf16 v[110:113], v[200:203], v[162:165], 0
	v_mfma_f32_16x16x32_bf16 v[106:109], v[208:211], v[162:165], 0
	v_mfma_f32_16x16x32_bf16 v[94:97], v[200:203], v[176:179], 0
	v_mfma_f32_16x16x32_bf16 v[90:93], v[208:211], v[176:179], 0
	v_mfma_f32_16x16x32_bf16 v[78:81], v[200:203], v[184:187], 0
	v_mfma_f32_16x16x32_bf16 v[74:77], v[208:211], v[184:187], 0
	v_mfma_f32_16x16x32_bf16 v[70:73], v[200:203], v[192:195], 0
	v_mfma_f32_16x16x32_bf16 v[66:69], v[208:211], v[192:195], 0
	v_mfma_f32_16x16x32_bf16 v[110:113], v[204:207], v[168:171], v[110:113]
	v_mfma_f32_16x16x32_bf16 v[106:109], v[212:215], v[168:171], v[106:109]
	v_mfma_f32_16x16x32_bf16 v[94:97], v[204:207], v[180:183], v[94:97]
	v_mfma_f32_16x16x32_bf16 v[90:93], v[212:215], v[180:183], v[90:93]
	v_mfma_f32_16x16x32_bf16 v[78:81], v[204:207], v[188:191], v[78:81]
	v_mfma_f32_16x16x32_bf16 v[74:77], v[212:215], v[188:191], v[74:77]
	v_mfma_f32_16x16x32_bf16 v[70:73], v[204:207], v[196:199], v[70:73]
	v_mfma_f32_16x16x32_bf16 v[66:69], v[212:215], v[196:199], v[66:69]
	s_mov_b32 m0, s86
	v_lshl_add_u64 v[220:221], s[30:31], 0, v[130:131]
	s_barrier
	ds_read_b128 v[162:165], v144 offset:16384
	ds_read_b128 v[168:171], v144 offset:17408
	ds_read_b128 v[176:179], v144 offset:18432
	ds_read_b128 v[180:183], v144 offset:19456
	ds_read_b128 v[184:187], v144 offset:20480
	ds_read_b128 v[188:191], v144 offset:21504
	ds_read_b128 v[192:195], v144 offset:22528
	ds_read_b128 v[196:199], v144 offset:23552
	global_load_lds_dwordx4 v[220:221], off
	v_lshl_add_u64 v[222:223], s[30:31], 0, v[132:133]
	s_mov_b32 m0, s87
	s_nop 0
	global_load_lds_dwordx4 v[222:223], off
	s_barrier
	s_waitcnt lgkmcnt(0)
	s_waitcnt lgkmcnt(0)
	v_mfma_f32_16x16x32_bf16 v[62:65], v[146:149], v[162:165], 0
	v_mfma_f32_16x16x32_bf16 v[58:61], v[154:157], v[162:165], 0
	v_mfma_f32_16x16x32_bf16 v[54:57], v[146:149], v[176:179], 0
	v_mfma_f32_16x16x32_bf16 v[50:53], v[154:157], v[176:179], 0
	v_mfma_f32_16x16x32_bf16 v[38:41], v[146:149], v[184:187], 0
	v_mfma_f32_16x16x32_bf16 v[34:37], v[154:157], v[184:187], 0
	v_mfma_f32_16x16x32_bf16 v[22:25], v[146:149], v[192:195], 0
	v_mfma_f32_16x16x32_bf16 v[18:21], v[154:157], v[192:195], 0
	v_mfma_f32_16x16x32_bf16 v[62:65], v[150:153], v[168:171], v[62:65]
	v_mfma_f32_16x16x32_bf16 v[58:61], v[158:161], v[168:171], v[58:61]
	v_mfma_f32_16x16x32_bf16 v[54:57], v[150:153], v[180:183], v[54:57]
	v_mfma_f32_16x16x32_bf16 v[50:53], v[158:161], v[180:183], v[50:53]
	v_mfma_f32_16x16x32_bf16 v[38:41], v[150:153], v[188:191], v[38:41]
	v_mfma_f32_16x16x32_bf16 v[34:37], v[158:161], v[188:191], v[34:37]
	v_mfma_f32_16x16x32_bf16 v[22:25], v[150:153], v[196:199], v[22:25]
	v_mfma_f32_16x16x32_bf16 v[18:21], v[158:161], v[196:199], v[18:21]
	s_barrier
; #define PG8_STAGE(bufoff, gbase, voff) do { _Pragma("unroll") for (int _i = 0; _i < 2; ++_i) \
;         __builtin_amdgcn_global_load_lds((const unsigned*)((const char*)(gbase) + (voff)[_i]), (LAS unsigned*)(lds + (bufoff) + ldsw + _i * 8192), 16, 0, 0); } while (0)
; #define PG8_LDA(dst, b, h) do { _Pragma("unroll") for (int m = 0; m < 4; ++m) _Pragma("unroll") for (int k = 0; k < 2; ++k) dst[m][k] = *(const LAS bf16x8*)(lds + PG8_SA(b, h) + aoff + m * 2048 + k * 1024); } while (0)
; #define PG8_LDB(dst, b, h) do { _Pragma("unroll") for (int n = 0; n < 2; ++n) _Pragma("unroll") for (int k = 0; k < 2; ++k) dst[n][k] = *(const LAS bf16x8*)(lds + PG8_SB(b, h) + boff + n * 2048 + k * 1024); } while (0)
; #define PG8_MMA(ai, bj, At, Bt) do { __builtin_amdgcn_s_setprio(1); _Pragma("unroll") for (int m = 0; m < 4; ++m) _Pragma("unroll") for (int n = 0; n < 2; ++n) _Pragma("unroll") for (int k = 0; k < 2; ++k) \
;         acc[ai][bj][m][n] = __builtin_amdgcn_mfma_f32_16x16x32_bf16(Bt[n][k], At[m][k], acc[ai][bj][m][n], 0, 0, 0); __builtin_amdgcn_s_setprio(0); } while (0)
; #define PG8_WAIT_V(n) asm volatile("s_waitcnt vmcnt(" #n ")" ::: "memory")
; #define PG8_WAIT_L(n) asm volatile("s_waitcnt lgkmcnt(" #n ")" ::: "memory")
; #define PG8_BAR __builtin_amdgcn_s_barrier()
; #define PG8_SCHED __builtin_amdgcn_sched_barrier(0)
; template <class Epi>
; DI void gemm_phase(int wv, LAS unsigned char* lds, const GemmD g, const Epi& E) {
;     ...
;             PG8_BAR; PG8_WAIT_L(0); PG8_MMA(1, 0, At, B0); PG8_BAR; PG8_SCHED;
;             PG8_STAGE(PG8_SB(0, 1), b2 + hstepB, voffB);
;             PG8_WAIT_V(6); PG8_BAR; PG8_MMA(1, 1, At, B1); PG8_BAR;
;             PG8_LDB(B0, 1, 0); PG8_SCHED; PG8_LDA(At, 1, 0); PG8_STAGE(PG8_SA(0, 1), a2 + hstepA, voffA);
;             PG8_WAIT_L(8); PG8_BAR; PG8_WAIT_L(0); PG8_MMA(0, 0, At, B0); PG8_BAR; PG8_SCHED;
;             PG8_LDB(B1, 1, 1); PG8_STAGE(PG8_SB(1, 0), b3, voffB);
;             PG8_BAR; PG8_WAIT_L(0); PG8_MMA(0, 1, At, B1); PG8_BAR;
;             PG8_LDA(At, 1, 1); PG8_STAGE(PG8_SA(1, 0), a3, voffA);
;             PG8_BAR; PG8_WAIT_L(0); PG8_MMA(1, 0, At, B0); PG8_BAR; PG8_SCHED;
	s_add_u32 s34, s34, s56
	s_addc_u32 s35, s35, 0
	s_add_i32 s2, s2, s84
	v_lshl_add_u64 v[224:225], s[34:35], 0, v[0:1]
	s_mov_b32 m0, s2
	v_lshl_add_u64 v[226:227], s[34:35], 0, v[134:135]
	global_load_lds_dwordx4 v[224:225], off
	s_add_i32 m0, s2, 0x2000
	s_nop 0
	global_load_lds_dwordx4 v[226:227], off
	s_waitcnt vmcnt(6)
	s_barrier
	v_mfma_f32_16x16x32_bf16 v[46:49], v[200:203], v[162:165], 0
	v_mfma_f32_16x16x32_bf16 v[42:45], v[208:211], v[162:165], 0
	v_mfma_f32_16x16x32_bf16 v[30:33], v[200:203], v[176:179], 0
	v_mfma_f32_16x16x32_bf16 v[26:29], v[208:211], v[176:179], 0
	v_mfma_f32_16x16x32_bf16 v[14:17], v[200:203], v[184:187], 0
	v_mfma_f32_16x16x32_bf16 v[10:13], v[208:211], v[184:187], 0
	v_mfma_f32_16x16x32_bf16 v[6:9], v[200:203], v[192:195], 0
	v_mfma_f32_16x16x32_bf16 v[2:5], v[208:211], v[192:195], 0
	v_mfma_f32_16x16x32_bf16 v[46:49], v[204:207], v[168:171], v[46:49]
	v_mfma_f32_16x16x32_bf16 v[42:45], v[212:215], v[168:171], v[42:45]
	v_mfma_f32_16x16x32_bf16 v[30:33], v[204:207], v[180:183], v[30:33]
	v_mfma_f32_16x16x32_bf16 v[26:29], v[212:215], v[180:183], v[26:29]
	v_mfma_f32_16x16x32_bf16 v[14:17], v[204:207], v[188:191], v[14:17]
	v_mfma_f32_16x16x32_bf16 v[10:13], v[212:215], v[188:191], v[10:13]
	v_mfma_f32_16x16x32_bf16 v[6:9], v[204:207], v[196:199], v[6:9]
	v_mfma_f32_16x16x32_bf16 v[2:5], v[212:215], v[196:199], v[2:5]
	s_add_i32 s2, 0, 0x18000
	v_add_u32_e32 v145, s2, v141
	s_barrier
	ds_read_b128 v[146:149], v145
	ds_read_b128 v[150:153], v145 offset:1024
	ds_read_b128 v[154:157], v145 offset:2048
	ds_read_b128 v[158:161], v145 offset:3072
	s_add_u32 s30, s30, s56
	s_addc_u32 s31, s31, 0
	s_mov_b32 m0, s74
	v_lshl_add_u64 v[200:201], s[30:31], 0, v[130:131]
	ds_read_b128 v[162:165], v144 offset:32768
	ds_read_b128 v[168:171], v144 offset:33792
	ds_read_b128 v[176:179], v144 offset:34816
	ds_read_b128 v[180:183], v144 offset:35840
	ds_read_b128 v[184:187], v144 offset:36864
	ds_read_b128 v[188:191], v144 offset:37888
	ds_read_b128 v[192:195], v144 offset:38912
	ds_read_b128 v[196:199], v144 offset:39936
	global_load_lds_dwordx4 v[200:201], off
	v_lshl_add_u64 v[200:201], s[30:31], 0, v[132:133]
	s_mov_b32 m0, s41
	s_nop 0
	global_load_lds_dwordx4 v[200:201], off
	s_waitcnt lgkmcnt(8)
	s_barrier
	s_waitcnt lgkmcnt(0)
	s_waitcnt lgkmcnt(0)
	v_mfma_f32_16x16x32_bf16 v[126:129], v[146:149], v[162:165], v[126:129]
	v_mfma_f32_16x16x32_bf16 v[122:125], v[154:157], v[162:165], v[122:125]
	v_mfma_f32_16x16x32_bf16 v[118:121], v[146:149], v[176:179], v[118:121]
	v_mfma_f32_16x16x32_bf16 v[114:117], v[154:157], v[176:179], v[114:117]
	v_mfma_f32_16x16x32_bf16 v[102:105], v[146:149], v[184:187], v[102:105]
	v_mfma_f32_16x16x32_bf16 v[98:101], v[154:157], v[184:187], v[98:101]
	v_mfma_f32_16x16x32_bf16 v[86:89], v[146:149], v[192:195], v[86:89]
	v_mfma_f32_16x16x32_bf16 v[82:85], v[154:157], v[192:195], v[82:85]
	v_mfma_f32_16x16x32_bf16 v[126:129], v[150:153], v[168:171], v[126:129]
	v_mfma_f32_16x16x32_bf16 v[122:125], v[158:161], v[168:171], v[122:125]
	v_mfma_f32_16x16x32_bf16 v[118:121], v[150:153], v[180:183], v[118:121]
	v_mfma_f32_16x16x32_bf16 v[114:117], v[158:161], v[180:183], v[114:117]
	v_mfma_f32_16x16x32_bf16 v[102:105], v[150:153], v[188:191], v[102:105]
	v_mfma_f32_16x16x32_bf16 v[98:101], v[158:161], v[188:191], v[98:101]
	v_mfma_f32_16x16x32_bf16 v[86:89], v[150:153], v[196:199], v[86:89]
	v_mfma_f32_16x16x32_bf16 v[82:85], v[158:161], v[196:199], v[82:85]
	s_barrier
	s_add_i32 s3, 0, 0x1c000
	s_add_i32 s2, s2, s84
	v_add_u32_e32 v145, s3, v141
	v_lshl_add_u64 v[216:217], v[216:217], 0, s[58:59]
	s_mov_b32 m0, s2
	ds_read_b128 v[200:203], v145
	ds_read_b128 v[204:207], v145 offset:1024
	ds_read_b128 v[208:211], v145 offset:2048
	ds_read_b128 v[212:215], v145 offset:3072
	global_load_lds_dwordx4 v[216:217], off
	v_lshl_add_u64 v[216:217], v[218:219], 0, s[58:59]
	s_add_i32 m0, s2, 0x2000
	s_nop 0
	global_load_lds_dwordx4 v[216:217], off
	s_barrier
	s_waitcnt lgkmcnt(0)
	s_waitcnt lgkmcnt(0)
	v_mfma_f32_16x16x32_bf16 v[110:113], v[200:203], v[162:165], v[110:113]
	v_mfma_f32_16x16x32_bf16 v[106:109], v[208:211], v[162:165], v[106:109]
	v_mfma_f32_16x16x32_bf16 v[94:97], v[200:203], v[176:179], v[94:97]
	v_mfma_f32_16x16x32_bf16 v[90:93], v[208:211], v[176:179], v[90:93]
	v_mfma_f32_16x16x32_bf16 v[78:81], v[200:203], v[184:187], v[78:81]
	v_mfma_f32_16x16x32_bf16 v[74:77], v[208:211], v[184:187], v[74:77]
	v_mfma_f32_16x16x32_bf16 v[70:73], v[200:203], v[192:195], v[70:73]
	v_mfma_f32_16x16x32_bf16 v[66:69], v[208:211], v[192:195], v[66:69]
	v_mfma_f32_16x16x32_bf16 v[110:113], v[204:207], v[168:171], v[110:113]
	v_mfma_f32_16x16x32_bf16 v[106:109], v[212:215], v[168:171], v[106:109]
	v_mfma_f32_16x16x32_bf16 v[94:97], v[204:207], v[180:183], v[94:97]
	v_mfma_f32_16x16x32_bf16 v[90:93], v[212:215], v[180:183], v[90:93]
	v_mfma_f32_16x16x32_bf16 v[78:81], v[204:207], v[188:191], v[78:81]
	v_mfma_f32_16x16x32_bf16 v[74:77], v[212:215], v[188:191], v[74:77]
	v_mfma_f32_16x16x32_bf16 v[70:73], v[204:207], v[196:199], v[70:73]
	v_mfma_f32_16x16x32_bf16 v[66:69], v[212:215], v[196:199], v[66:69]
	s_mov_b32 m0, s13
	v_lshl_add_u64 v[216:217], v[220:221], 0, s[58:59]
	s_barrier
	ds_read_b128 v[162:165], v144 offset:49152
	ds_read_b128 v[168:171], v144 offset:50176
	ds_read_b128 v[176:179], v144 offset:51200
	ds_read_b128 v[180:183], v144 offset:52224
	ds_read_b128 v[184:187], v144 offset:53248
	ds_read_b128 v[188:191], v144 offset:54272
	ds_read_b128 v[192:195], v144 offset:55296
	ds_read_b128 v[196:199], v144 offset:56320
	global_load_lds_dwordx4 v[216:217], off
	v_lshl_add_u64 v[216:217], v[222:223], 0, s[58:59]
	s_mov_b32 m0, s16
	s_nop 0
	global_load_lds_dwordx4 v[216:217], off
	s_barrier
; #define PG8_STAGE(bufoff, gbase, voff) do { _Pragma("unroll") for (int _i = 0; _i < 2; ++_i) \
;         __builtin_amdgcn_global_load_lds((const unsigned*)((const char*)(gbase) + (voff)[_i]), (LAS unsigned*)(lds + (bufoff) + ldsw + _i * 8192), 16, 0, 0); } while (0)
; #define PG8_LDA(dst, b, h) do { _Pragma("unroll") for (int m = 0; m < 4; ++m) _Pragma("unroll") for (int k = 0; k < 2; ++k) dst[m][k] = *(const LAS bf16x8*)(lds + PG8_SA(b, h) + aoff + m * 2048 + k * 1024); } while (0)
; #define PG8_LDB(dst, b, h) do { _Pragma("unroll") for (int n = 0; n < 2; ++n) _Pragma("unroll") for (int k = 0; k < 2; ++k) dst[n][k] = *(const LAS bf16x8*)(lds + PG8_SB(b, h) + boff + n * 2048 + k * 1024); } while (0)
; #define PG8_MMA(ai, bj, At, Bt) do { __builtin_amdgcn_s_setprio(1); _Pragma("unroll") for (int m = 0; m < 4; ++m) _Pragma("unroll") for (int n = 0; n < 2; ++n) _Pragma("unroll") for (int k = 0; k < 2; ++k) \
;         acc[ai][bj][m][n] = __builtin_amdgcn_mfma_f32_16x16x32_bf16(Bt[n][k], At[m][k], acc[ai][bj][m][n], 0, 0, 0); __builtin_amdgcn_s_setprio(0); } while (0)
; #define PG8_WAIT_V(n) asm volatile("s_waitcnt vmcnt(" #n ")" ::: "memory")
; #define PG8_WAIT_L(n) asm volatile("s_waitcnt lgkmcnt(" #n ")" ::: "memory")
; #define PG8_BAR __builtin_amdgcn_s_barrier()
; #define PG8_SCHED __builtin_amdgcn_sched_barrier(0)
; template <class Epi>
; DI void gemm_phase(int wv, LAS unsigned char* lds, const GemmD g, const Epi& E) {
;     ...
;             PG8_LDB(B0, 0, 0); PG8_SCHED; PG8_LDA(At, 0, 0); PG8_STAGE(PG8_SA(1, 1), a1 + hstepA, voffA);
;             PG8_WAIT_L(8); PG8_BAR; PG8_WAIT_L(0); PG8_MMA(0, 0, At, B0); PG8_BAR; PG8_SCHED;
;             PG8_LDB(B1, 0, 1); PG8_STAGE(PG8_SB(0, 0), b2, voffB);
;             PG8_BAR; PG8_WAIT_L(0); PG8_MMA(0, 1, At, B1); PG8_BAR;
;     ...
;             PG8_WAIT_L(8); PG8_BAR; PG8_WAIT_L(0); PG8_MMA(0, 0, At, B0); PG8_BAR; PG8_SCHED;
;             PG8_LDB(B1, 1, 1); PG8_STAGE(PG8_SB(1, 0), b3, voffB);
;             PG8_BAR; PG8_WAIT_L(0); PG8_MMA(0, 1, At, B1); PG8_BAR;
;             PG8_LDA(At, 1, 1); PG8_STAGE(PG8_SA(1, 0), a3, voffA);
;             PG8_BAR; PG8_WAIT_L(0); PG8_MMA(1, 0, At, B0); PG8_BAR; PG8_SCHED;
;             PG8_STAGE(PG8_SB(1, 1), b3 + hstepB, voffB);
;             PG8_WAIT_V(6); PG8_BAR; PG8_MMA(1, 1, At, B1); PG8_BAR;
;         }
	s_waitcnt lgkmcnt(0)
	s_waitcnt lgkmcnt(0)
	v_mfma_f32_16x16x32_bf16 v[62:65], v[146:149], v[162:165], v[62:65]
	v_mfma_f32_16x16x32_bf16 v[58:61], v[154:157], v[162:165], v[58:61]
	v_mfma_f32_16x16x32_bf16 v[54:57], v[146:149], v[176:179], v[54:57]
	v_mfma_f32_16x16x32_bf16 v[50:53], v[154:157], v[176:179], v[50:53]
	v_mfma_f32_16x16x32_bf16 v[38:41], v[146:149], v[184:187], v[38:41]
	v_mfma_f32_16x16x32_bf16 v[34:37], v[154:157], v[184:187], v[34:37]
	v_mfma_f32_16x16x32_bf16 v[22:25], v[146:149], v[192:195], v[22:25]
	v_mfma_f32_16x16x32_bf16 v[18:21], v[154:157], v[192:195], v[18:21]
	v_mfma_f32_16x16x32_bf16 v[62:65], v[150:153], v[168:171], v[62:65]
	v_mfma_f32_16x16x32_bf16 v[58:61], v[158:161], v[168:171], v[58:61]
	v_mfma_f32_16x16x32_bf16 v[54:57], v[150:153], v[180:183], v[54:57]
	v_mfma_f32_16x16x32_bf16 v[50:53], v[158:161], v[180:183], v[50:53]
	v_mfma_f32_16x16x32_bf16 v[38:41], v[150:153], v[188:191], v[38:41]
	v_mfma_f32_16x16x32_bf16 v[34:37], v[158:161], v[188:191], v[34:37]
	v_mfma_f32_16x16x32_bf16 v[22:25], v[150:153], v[196:199], v[22:25]
	v_mfma_f32_16x16x32_bf16 v[18:21], v[158:161], v[196:199], v[18:21]
	s_barrier
	s_add_i32 s2, s3, s84
	v_lshl_add_u64 v[146:147], v[224:225], 0, s[58:59]
	s_mov_b32 m0, s2
	s_nop 0
	global_load_lds_dwordx4 v[146:147], off
	v_lshl_add_u64 v[146:147], v[226:227], 0, s[58:59]
	s_add_i32 m0, s2, 0x2000
	s_nop 0
	global_load_lds_dwordx4 v[146:147], off
	s_waitcnt vmcnt(6)
	s_barrier
	v_mfma_f32_16x16x32_bf16 v[46:49], v[200:203], v[162:165], v[46:49]
	v_mfma_f32_16x16x32_bf16 v[42:45], v[208:211], v[162:165], v[42:45]
	v_mfma_f32_16x16x32_bf16 v[30:33], v[200:203], v[176:179], v[30:33]
	v_mfma_f32_16x16x32_bf16 v[26:29], v[208:211], v[176:179], v[26:29]
	v_mfma_f32_16x16x32_bf16 v[14:17], v[200:203], v[184:187], v[14:17]
	v_mfma_f32_16x16x32_bf16 v[10:13], v[208:211], v[184:187], v[10:13]
	v_mfma_f32_16x16x32_bf16 v[6:9], v[200:203], v[192:195], v[6:9]
	v_mfma_f32_16x16x32_bf16 v[2:5], v[208:211], v[192:195], v[2:5]
	v_mfma_f32_16x16x32_bf16 v[46:49], v[204:207], v[168:171], v[46:49]
	v_mfma_f32_16x16x32_bf16 v[42:45], v[212:215], v[168:171], v[42:45]
	v_mfma_f32_16x16x32_bf16 v[30:33], v[204:207], v[180:183], v[30:33]
	v_mfma_f32_16x16x32_bf16 v[26:29], v[212:215], v[180:183], v[26:29]
	v_mfma_f32_16x16x32_bf16 v[14:17], v[204:207], v[188:191], v[14:17]
	v_mfma_f32_16x16x32_bf16 v[10:13], v[212:215], v[188:191], v[10:13]
	v_mfma_f32_16x16x32_bf16 v[6:9], v[204:207], v[196:199], v[6:9]
	v_mfma_f32_16x16x32_bf16 v[2:5], v[212:215], v[196:199], v[2:5]
	s_add_u32 s28, s28, 0x100
	s_addc_u32 s29, s29, 0
	s_add_u32 s37, s37, 0x100
	s_addc_u32 s18, s18, 0
	s_cmp_ge_u32 s95, s38
	s_mov_b32 s19, s95
	s_barrier
	s_cbranch_scc0 .LBB0_544
	s_branch .Lgemm_epi_c
.LBB0_544:
	s_add_i32 s95, s19, 2
	s_add_u32 s2, s28, 0x80
	s_addc_u32 s3, s29, 0
	s_add_i32 s94, 0, 0x10000
	v_add_u32_e32 v145, s94, v141
	ds_read_b128 v[146:149], v145
	ds_read_b128 v[150:153], v145 offset:1024
	ds_read_b128 v[154:157], v145 offset:2048
	ds_read_b128 v[158:161], v145 offset:3072
	s_cmp_eq_u32 s17, s19
	s_cselect_b32 s31, s23, s3
	s_cselect_b32 s30, s68, s2
	s_cselect_b32 s35, vcc_lo, s18
	s_cselect_b32 s34, vcc_hi, s37
	v_lshl_add_u64 v[200:201], s[28:29], 0, v[136:137]
	s_add_i32 m0, s86, 0xc000
	ds_read_b128 v[162:165], v144
	ds_read_b128 v[168:171], v144 offset:1024
	ds_read_b128 v[176:179], v144 offset:2048
	ds_read_b128 v[180:183], v144 offset:3072
	ds_read_b128 v[184:187], v144 offset:4096
	ds_read_b128 v[188:191], v144 offset:5120
	ds_read_b128 v[192:195], v144 offset:6144
	ds_read_b128 v[196:199], v144 offset:7168
	global_load_lds_dwordx4 v[200:201], off
	v_lshl_add_u64 v[200:201], s[28:29], 0, v[138:139]
	s_add_i32 m0, s86, 0xe000
	s_nop 0
	global_load_lds_dwordx4 v[200:201], off
	s_waitcnt lgkmcnt(8)
	s_barrier
	s_waitcnt lgkmcnt(0)
	s_waitcnt lgkmcnt(0)
	v_mfma_f32_16x16x32_bf16 v[126:129], v[146:149], v[162:165], v[126:129]
	v_mfma_f32_16x16x32_bf16 v[122:125], v[154:157], v[162:165], v[122:125]
	v_mfma_f32_16x16x32_bf16 v[118:121], v[146:149], v[176:179], v[118:121]
	v_mfma_f32_16x16x32_bf16 v[114:117], v[154:157], v[176:179], v[114:117]
	v_mfma_f32_16x16x32_bf16 v[102:105], v[146:149], v[184:187], v[102:105]
	v_mfma_f32_16x16x32_bf16 v[98:101], v[154:157], v[184:187], v[98:101]
	v_mfma_f32_16x16x32_bf16 v[86:89], v[146:149], v[192:195], v[86:89]
	v_mfma_f32_16x16x32_bf16 v[82:85], v[154:157], v[192:195], v[82:85]
	v_mfma_f32_16x16x32_bf16 v[126:129], v[150:153], v[168:171], v[126:129]
	v_mfma_f32_16x16x32_bf16 v[122:125], v[158:161], v[168:171], v[122:125]
	v_mfma_f32_16x16x32_bf16 v[118:121], v[150:153], v[180:183], v[118:121]
	v_mfma_f32_16x16x32_bf16 v[114:117], v[158:161], v[180:183], v[114:117]
	v_mfma_f32_16x16x32_bf16 v[102:105], v[150:153], v[188:191], v[102:105]
	v_mfma_f32_16x16x32_bf16 v[98:101], v[158:161], v[188:191], v[98:101]
	v_mfma_f32_16x16x32_bf16 v[86:89], v[150:153], v[196:199], v[86:89]
	v_mfma_f32_16x16x32_bf16 v[82:85], v[158:161], v[196:199], v[82:85]
	s_barrier
	s_add_i32 s2, 0, 0x14000
	s_add_i32 s3, s94, s84
	v_add_u32_e32 v145, s2, v141
	v_lshl_add_u64 v[216:217], s[34:35], 0, v[0:1]
	s_mov_b32 m0, s3
	ds_read_b128 v[200:203], v145
	ds_read_b128 v[204:207], v145 offset:1024
	ds_read_b128 v[208:211], v145 offset:2048
	ds_read_b128 v[212:215], v145 offset:3072
	global_load_lds_dwordx4 v[216:217], off
	v_lshl_add_u64 v[218:219], s[34:35], 0, v[134:135]
	s_add_i32 m0, s3, 0x2000
	s_nop 0
	global_load_lds_dwordx4 v[218:219], off
	s_barrier
; #define PG8_STAGE(bufoff, gbase, voff) do { _Pragma("unroll") for (int _i = 0; _i < 2; ++_i) \
;         __builtin_amdgcn_global_load_lds((const unsigned*)((const char*)(gbase) + (voff)[_i]), (LAS unsigned*)(lds + (bufoff) + ldsw + _i * 8192), 16, 0, 0); } while (0)
; #define PG8_LDA(dst, b, h) do { _Pragma("unroll") for (int m = 0; m < 4; ++m) _Pragma("unroll") for (int k = 0; k < 2; ++k) dst[m][k] = *(const LAS bf16x8*)(lds + PG8_SA(b, h) + aoff + m * 2048 + k * 1024); } while (0)
; #define PG8_LDB(dst, b, h) do { _Pragma("unroll") for (int n = 0; n < 2; ++n) _Pragma("unroll") for (int k = 0; k < 2; ++k) dst[n][k] = *(const LAS bf16x8*)(lds + PG8_SB(b, h) + boff + n * 2048 + k * 1024); } while (0)
; #define PG8_MMA(ai, bj, At, Bt) do { __builtin_amdgcn_s_setprio(1); _Pragma("unroll") for (int m = 0; m < 4; ++m) _Pragma("unroll") for (int n = 0; n < 2; ++n) _Pragma("unroll") for (int k = 0; k < 2; ++k) \
;         acc[ai][bj][m][n] = __builtin_amdgcn_mfma_f32_16x16x32_bf16(Bt[n][k], At[m][k], acc[ai][bj][m][n], 0, 0, 0); __builtin_amdgcn_s_setprio(0); } while (0)
; #define PG8_WAIT_V(n) asm volatile("s_waitcnt vmcnt(" #n ")" ::: "memory")
; #define PG8_WAIT_L(n) asm volatile("s_waitcnt lgkmcnt(" #n ")" ::: "memory")
; #define PG8_BAR __builtin_amdgcn_s_barrier()
; #define PG8_SCHED __builtin_amdgcn_sched_barrier(0)
; template <class Epi>
; DI void gemm_phase(int wv, LAS unsigned char* lds, const GemmD g, const Epi& E) {
;     ...
;             PG8_BAR; PG8_WAIT_L(0); PG8_MMA(0, 1, At, B1); PG8_BAR;
;             PG8_LDA(At, 0, 1); PG8_STAGE(PG8_SA(0, 0), a2, voffA);
;             PG8_BAR; PG8_WAIT_L(0); PG8_MMA(1, 0, At, B0); PG8_BAR; PG8_SCHED;
;             PG8_STAGE(PG8_SB(0, 1), b2 + hstepB, voffB);
;             PG8_WAIT_V(6); PG8_BAR; PG8_MMA(1, 1, At, B1); PG8_BAR;
;             PG8_LDB(B0, 1, 0); PG8_SCHED; PG8_LDA(At, 1, 0); PG8_STAGE(PG8_SA(0, 1), a2 + hstepA, voffA);
;             PG8_WAIT_L(8); PG8_BAR; PG8_WAIT_L(0); PG8_MMA(0, 0, At, B0); PG8_BAR; PG8_SCHED;
;             PG8_LDB(B1, 1, 1); PG8_STAGE(PG8_SB(1, 0), b3, voffB);
;             PG8_BAR; PG8_WAIT_L(0); PG8_MMA(0, 1, At, B1); PG8_BAR;
;             PG8_LDA(At, 1, 1); PG8_STAGE(PG8_SA(1, 0), a3, voffA);
	s_waitcnt lgkmcnt(0)
	s_waitcnt lgkmcnt(0)
	v_mfma_f32_16x16x32_bf16 v[110:113], v[200:203], v[162:165], v[110:113]
	v_mfma_f32_16x16x32_bf16 v[106:109], v[208:211], v[162:165], v[106:109]
	v_mfma_f32_16x16x32_bf16 v[94:97], v[200:203], v[176:179], v[94:97]
	v_mfma_f32_16x16x32_bf16 v[90:93], v[208:211], v[176:179], v[90:93]
	v_mfma_f32_16x16x32_bf16 v[78:81], v[200:203], v[184:187], v[78:81]
	v_mfma_f32_16x16x32_bf16 v[74:77], v[208:211], v[184:187], v[74:77]
	v_mfma_f32_16x16x32_bf16 v[70:73], v[200:203], v[192:195], v[70:73]
	v_mfma_f32_16x16x32_bf16 v[66:69], v[208:211], v[192:195], v[66:69]
	v_mfma_f32_16x16x32_bf16 v[110:113], v[204:207], v[168:171], v[110:113]
	v_mfma_f32_16x16x32_bf16 v[106:109], v[212:215], v[168:171], v[106:109]
	v_mfma_f32_16x16x32_bf16 v[94:97], v[204:207], v[180:183], v[94:97]
	v_mfma_f32_16x16x32_bf16 v[90:93], v[212:215], v[180:183], v[90:93]
	v_mfma_f32_16x16x32_bf16 v[78:81], v[204:207], v[188:191], v[78:81]
	v_mfma_f32_16x16x32_bf16 v[74:77], v[212:215], v[188:191], v[74:77]
	v_mfma_f32_16x16x32_bf16 v[70:73], v[204:207], v[196:199], v[70:73]
	v_mfma_f32_16x16x32_bf16 v[66:69], v[212:215], v[196:199], v[66:69]
	s_mov_b32 m0, s86
	v_lshl_add_u64 v[220:221], s[30:31], 0, v[130:131]
	s_barrier
	ds_read_b128 v[162:165], v144 offset:16384
	ds_read_b128 v[168:171], v144 offset:17408
	ds_read_b128 v[176:179], v144 offset:18432
	ds_read_b128 v[180:183], v144 offset:19456
	ds_read_b128 v[184:187], v144 offset:20480
	ds_read_b128 v[188:191], v144 offset:21504
	ds_read_b128 v[192:195], v144 offset:22528
	ds_read_b128 v[196:199], v144 offset:23552
	global_load_lds_dwordx4 v[220:221], off
	v_lshl_add_u64 v[222:223], s[30:31], 0, v[132:133]
	s_mov_b32 m0, s87
	s_nop 0
	global_load_lds_dwordx4 v[222:223], off
	s_barrier
	s_waitcnt lgkmcnt(0)
	s_waitcnt lgkmcnt(0)
	v_mfma_f32_16x16x32_bf16 v[62:65], v[146:149], v[162:165], v[62:65]
	v_mfma_f32_16x16x32_bf16 v[58:61], v[154:157], v[162:165], v[58:61]
	v_mfma_f32_16x16x32_bf16 v[54:57], v[146:149], v[176:179], v[54:57]
	v_mfma_f32_16x16x32_bf16 v[50:53], v[154:157], v[176:179], v[50:53]
	v_mfma_f32_16x16x32_bf16 v[38:41], v[146:149], v[184:187], v[38:41]
	v_mfma_f32_16x16x32_bf16 v[34:37], v[154:157], v[184:187], v[34:37]
	v_mfma_f32_16x16x32_bf16 v[22:25], v[146:149], v[192:195], v[22:25]
	v_mfma_f32_16x16x32_bf16 v[18:21], v[154:157], v[192:195], v[18:21]
	v_mfma_f32_16x16x32_bf16 v[62:65], v[150:153], v[168:171], v[62:65]
	v_mfma_f32_16x16x32_bf16 v[58:61], v[158:161], v[168:171], v[58:61]
	v_mfma_f32_16x16x32_bf16 v[54:57], v[150:153], v[180:183], v[54:57]
	v_mfma_f32_16x16x32_bf16 v[50:53], v[158:161], v[180:183], v[50:53]
	v_mfma_f32_16x16x32_bf16 v[38:41], v[150:153], v[188:191], v[38:41]
	v_mfma_f32_16x16x32_bf16 v[34:37], v[158:161], v[188:191], v[34:37]
	v_mfma_f32_16x16x32_bf16 v[22:25], v[150:153], v[196:199], v[22:25]
	v_mfma_f32_16x16x32_bf16 v[18:21], v[158:161], v[196:199], v[18:21]
	s_barrier
	s_add_u32 s34, s34, s56
	s_addc_u32 s35, s35, 0
	s_add_i32 s2, s2, s84
	v_lshl_add_u64 v[224:225], s[34:35], 0, v[0:1]
	s_mov_b32 m0, s2
	v_lshl_add_u64 v[226:227], s[34:35], 0, v[134:135]
	global_load_lds_dwordx4 v[224:225], off
	s_add_i32 m0, s2, 0x2000
	s_nop 0
	global_load_lds_dwordx4 v[226:227], off
	s_waitcnt vmcnt(6)
	s_barrier
	v_mfma_f32_16x16x32_bf16 v[46:49], v[200:203], v[162:165], v[46:49]
	v_mfma_f32_16x16x32_bf16 v[42:45], v[208:211], v[162:165], v[42:45]
	v_mfma_f32_16x16x32_bf16 v[30:33], v[200:203], v[176:179], v[30:33]
	v_mfma_f32_16x16x32_bf16 v[26:29], v[208:211], v[176:179], v[26:29]
	v_mfma_f32_16x16x32_bf16 v[14:17], v[200:203], v[184:187], v[14:17]
	v_mfma_f32_16x16x32_bf16 v[10:13], v[208:211], v[184:187], v[10:13]
	v_mfma_f32_16x16x32_bf16 v[6:9], v[200:203], v[192:195], v[6:9]
	v_mfma_f32_16x16x32_bf16 v[2:5], v[208:211], v[192:195], v[2:5]
	v_mfma_f32_16x16x32_bf16 v[46:49], v[204:207], v[168:171], v[46:49]
	v_mfma_f32_16x16x32_bf16 v[42:45], v[212:215], v[168:171], v[42:45]
	v_mfma_f32_16x16x32_bf16 v[30:33], v[204:207], v[180:183], v[30:33]
	v_mfma_f32_16x16x32_bf16 v[26:29], v[212:215], v[180:183], v[26:29]
	v_mfma_f32_16x16x32_bf16 v[14:17], v[204:207], v[188:191], v[14:17]
	v_mfma_f32_16x16x32_bf16 v[10:13], v[212:215], v[188:191], v[10:13]
	v_mfma_f32_16x16x32_bf16 v[6:9], v[204:207], v[196:199], v[6:9]
	v_mfma_f32_16x16x32_bf16 v[2:5], v[212:215], v[196:199], v[2:5]
	s_add_i32 s2, 0, 0x18000
	v_add_u32_e32 v145, s2, v141
	s_barrier
	ds_read_b128 v[146:149], v145
	ds_read_b128 v[150:153], v145 offset:1024
	ds_read_b128 v[154:157], v145 offset:2048
	ds_read_b128 v[158:161], v145 offset:3072
	s_add_u32 s30, s30, s56
	s_addc_u32 s31, s31, 0
	s_mov_b32 m0, s74
	v_lshl_add_u64 v[200:201], s[30:31], 0, v[130:131]
	ds_read_b128 v[162:165], v144 offset:32768
	ds_read_b128 v[168:171], v144 offset:33792
	ds_read_b128 v[176:179], v144 offset:34816
	ds_read_b128 v[180:183], v144 offset:35840
	ds_read_b128 v[184:187], v144 offset:36864
	ds_read_b128 v[188:191], v144 offset:37888
	ds_read_b128 v[192:195], v144 offset:38912
	ds_read_b128 v[196:199], v144 offset:39936
	global_load_lds_dwordx4 v[200:201], off
	v_lshl_add_u64 v[200:201], s[30:31], 0, v[132:133]
	s_mov_b32 m0, s41
	s_nop 0
	global_load_lds_dwordx4 v[200:201], off
	s_waitcnt lgkmcnt(8)
	s_barrier
; #define PG8_STAGE(bufoff, gbase, voff) do { _Pragma("unroll") for (int _i = 0; _i < 2; ++_i) \
;         __builtin_amdgcn_global_load_lds((const unsigned*)((const char*)(gbase) + (voff)[_i]), (LAS unsigned*)(lds + (bufoff) + ldsw + _i * 8192), 16, 0, 0); } while (0)
; #define PG8_LDA(dst, b, h) do { _Pragma("unroll") for (int m = 0; m < 4; ++m) _Pragma("unroll") for (int k = 0; k < 2; ++k) dst[m][k] = *(const LAS bf16x8*)(lds + PG8_SA(b, h) + aoff + m * 2048 + k * 1024); } while (0)
; #define PG8_LDB(dst, b, h) do { _Pragma("unroll") for (int n = 0; n < 2; ++n) _Pragma("unroll") for (int k = 0; k < 2; ++k) dst[n][k] = *(const LAS bf16x8*)(lds + PG8_SB(b, h) + boff + n * 2048 + k * 1024); } while (0)
; #define PG8_MMA(ai, bj, At, Bt) do { __builtin_amdgcn_s_setprio(1); _Pragma("unroll") for (int m = 0; m < 4; ++m) _Pragma("unroll") for (int n = 0; n < 2; ++n) _Pragma("unroll") for (int k = 0; k < 2; ++k) \
;         acc[ai][bj][m][n] = __builtin_amdgcn_mfma_f32_16x16x32_bf16(Bt[n][k], At[m][k], acc[ai][bj][m][n], 0, 0, 0); __builtin_amdgcn_s_setprio(0); } while (0)
; #define PG8_WAIT_V(n) asm volatile("s_waitcnt vmcnt(" #n ")" ::: "memory")
; #define PG8_WAIT_L(n) asm volatile("s_waitcnt lgkmcnt(" #n ")" ::: "memory")
; #define PG8_BAR __builtin_amdgcn_s_barrier()
; #define PG8_SCHED __builtin_amdgcn_sched_barrier(0)
; template <class Epi>
; DI void gemm_phase(int wv, LAS unsigned char* lds, const GemmD g, const Epi& E) {
;     ...
;             PG8_WAIT_L(8); PG8_BAR; PG8_WAIT_L(0); PG8_MMA(0, 0, At, B0); PG8_BAR; PG8_SCHED;
;             PG8_LDB(B1, 1, 1); PG8_STAGE(PG8_SB(1, 0), b3, voffB);
;             PG8_BAR; PG8_WAIT_L(0); PG8_MMA(0, 1, At, B1); PG8_BAR;
;             PG8_LDA(At, 1, 1); PG8_STAGE(PG8_SA(1, 0), a3, voffA);
;             PG8_BAR; PG8_WAIT_L(0); PG8_MMA(1, 0, At, B0); PG8_BAR; PG8_SCHED;
;             PG8_STAGE(PG8_SB(1, 1), b3 + hstepB, voffB);
;             PG8_WAIT_V(6); PG8_BAR; PG8_MMA(1, 1, At, B1); PG8_BAR;
	s_waitcnt lgkmcnt(0)
	s_waitcnt lgkmcnt(0)
	v_mfma_f32_16x16x32_bf16 v[126:129], v[146:149], v[162:165], v[126:129]
	v_mfma_f32_16x16x32_bf16 v[122:125], v[154:157], v[162:165], v[122:125]
	v_mfma_f32_16x16x32_bf16 v[118:121], v[146:149], v[176:179], v[118:121]
	v_mfma_f32_16x16x32_bf16 v[114:117], v[154:157], v[176:179], v[114:117]
	v_mfma_f32_16x16x32_bf16 v[102:105], v[146:149], v[184:187], v[102:105]
	v_mfma_f32_16x16x32_bf16 v[98:101], v[154:157], v[184:187], v[98:101]
	v_mfma_f32_16x16x32_bf16 v[86:89], v[146:149], v[192:195], v[86:89]
	v_mfma_f32_16x16x32_bf16 v[82:85], v[154:157], v[192:195], v[82:85]
	v_mfma_f32_16x16x32_bf16 v[126:129], v[150:153], v[168:171], v[126:129]
	v_mfma_f32_16x16x32_bf16 v[122:125], v[158:161], v[168:171], v[122:125]
	v_mfma_f32_16x16x32_bf16 v[118:121], v[150:153], v[180:183], v[118:121]
	v_mfma_f32_16x16x32_bf16 v[114:117], v[158:161], v[180:183], v[114:117]
	v_mfma_f32_16x16x32_bf16 v[102:105], v[150:153], v[188:191], v[102:105]
	v_mfma_f32_16x16x32_bf16 v[98:101], v[158:161], v[188:191], v[98:101]
	v_mfma_f32_16x16x32_bf16 v[86:89], v[150:153], v[196:199], v[86:89]
	v_mfma_f32_16x16x32_bf16 v[82:85], v[158:161], v[196:199], v[82:85]
	s_barrier
	s_add_i32 s3, 0, 0x1c000
	s_add_i32 s2, s2, s84
	v_add_u32_e32 v145, s3, v141
	v_lshl_add_u64 v[216:217], v[216:217], 0, s[58:59]
	s_mov_b32 m0, s2
	ds_read_b128 v[200:203], v145
	ds_read_b128 v[204:207], v145 offset:1024
	ds_read_b128 v[208:211], v145 offset:2048
	ds_read_b128 v[212:215], v145 offset:3072
	global_load_lds_dwordx4 v[216:217], off
	v_lshl_add_u64 v[216:217], v[218:219], 0, s[58:59]
	s_add_i32 m0, s2, 0x2000
	s_nop 0
	global_load_lds_dwordx4 v[216:217], off
	s_barrier
	s_waitcnt lgkmcnt(0)
	s_waitcnt lgkmcnt(0)
	v_mfma_f32_16x16x32_bf16 v[110:113], v[200:203], v[162:165], v[110:113]
	v_mfma_f32_16x16x32_bf16 v[106:109], v[208:211], v[162:165], v[106:109]
	v_mfma_f32_16x16x32_bf16 v[94:97], v[200:203], v[176:179], v[94:97]
	v_mfma_f32_16x16x32_bf16 v[90:93], v[208:211], v[176:179], v[90:93]
	v_mfma_f32_16x16x32_bf16 v[78:81], v[200:203], v[184:187], v[78:81]
	v_mfma_f32_16x16x32_bf16 v[74:77], v[208:211], v[184:187], v[74:77]
	v_mfma_f32_16x16x32_bf16 v[70:73], v[200:203], v[192:195], v[70:73]
	v_mfma_f32_16x16x32_bf16 v[66:69], v[208:211], v[192:195], v[66:69]
	v_mfma_f32_16x16x32_bf16 v[110:113], v[204:207], v[168:171], v[110:113]
	v_mfma_f32_16x16x32_bf16 v[106:109], v[212:215], v[168:171], v[106:109]
	v_mfma_f32_16x16x32_bf16 v[94:97], v[204:207], v[180:183], v[94:97]
	v_mfma_f32_16x16x32_bf16 v[90:93], v[212:215], v[180:183], v[90:93]
	v_mfma_f32_16x16x32_bf16 v[78:81], v[204:207], v[188:191], v[78:81]
	v_mfma_f32_16x16x32_bf16 v[74:77], v[212:215], v[188:191], v[74:77]
	v_mfma_f32_16x16x32_bf16 v[70:73], v[204:207], v[196:199], v[70:73]
	v_mfma_f32_16x16x32_bf16 v[66:69], v[212:215], v[196:199], v[66:69]
	s_mov_b32 m0, s13
	v_lshl_add_u64 v[216:217], v[220:221], 0, s[58:59]
	s_barrier
	ds_read_b128 v[162:165], v144 offset:49152
	ds_read_b128 v[168:171], v144 offset:50176
	ds_read_b128 v[176:179], v144 offset:51200
	ds_read_b128 v[180:183], v144 offset:52224
	ds_read_b128 v[184:187], v144 offset:53248
	ds_read_b128 v[188:191], v144 offset:54272
	ds_read_b128 v[192:195], v144 offset:55296
	ds_read_b128 v[196:199], v144 offset:56320
	global_load_lds_dwordx4 v[216:217], off
	v_lshl_add_u64 v[216:217], v[222:223], 0, s[58:59]
	s_mov_b32 m0, s16
	s_nop 0
	global_load_lds_dwordx4 v[216:217], off
	s_barrier
	s_waitcnt lgkmcnt(0)
	s_waitcnt lgkmcnt(0)
	v_mfma_f32_16x16x32_bf16 v[62:65], v[146:149], v[162:165], v[62:65]
	v_mfma_f32_16x16x32_bf16 v[58:61], v[154:157], v[162:165], v[58:61]
	v_mfma_f32_16x16x32_bf16 v[54:57], v[146:149], v[176:179], v[54:57]
	v_mfma_f32_16x16x32_bf16 v[50:53], v[154:157], v[176:179], v[50:53]
	v_mfma_f32_16x16x32_bf16 v[38:41], v[146:149], v[184:187], v[38:41]
	v_mfma_f32_16x16x32_bf16 v[34:37], v[154:157], v[184:187], v[34:37]
	v_mfma_f32_16x16x32_bf16 v[22:25], v[146:149], v[192:195], v[22:25]
	v_mfma_f32_16x16x32_bf16 v[18:21], v[154:157], v[192:195], v[18:21]
	v_mfma_f32_16x16x32_bf16 v[62:65], v[150:153], v[168:171], v[62:65]
	v_mfma_f32_16x16x32_bf16 v[58:61], v[158:161], v[168:171], v[58:61]
	v_mfma_f32_16x16x32_bf16 v[54:57], v[150:153], v[180:183], v[54:57]
	v_mfma_f32_16x16x32_bf16 v[50:53], v[158:161], v[180:183], v[50:53]
	v_mfma_f32_16x16x32_bf16 v[38:41], v[150:153], v[188:191], v[38:41]
	v_mfma_f32_16x16x32_bf16 v[34:37], v[158:161], v[188:191], v[34:37]
	v_mfma_f32_16x16x32_bf16 v[22:25], v[150:153], v[196:199], v[22:25]
	v_mfma_f32_16x16x32_bf16 v[18:21], v[158:161], v[196:199], v[18:21]
	s_barrier
	s_add_i32 s2, s3, s84
	v_lshl_add_u64 v[146:147], v[224:225], 0, s[58:59]
	s_mov_b32 m0, s2
	s_nop 0
	global_load_lds_dwordx4 v[146:147], off
	v_lshl_add_u64 v[146:147], v[226:227], 0, s[58:59]
	s_add_i32 m0, s2, 0x2000
	s_nop 0
	global_load_lds_dwordx4 v[146:147], off
	s_waitcnt vmcnt(6)
	s_barrier
	v_mfma_f32_16x16x32_bf16 v[46:49], v[200:203], v[162:165], v[46:49]
	v_mfma_f32_16x16x32_bf16 v[42:45], v[208:211], v[162:165], v[42:45]
	v_mfma_f32_16x16x32_bf16 v[30:33], v[200:203], v[176:179], v[30:33]
	v_mfma_f32_16x16x32_bf16 v[26:29], v[208:211], v[176:179], v[26:29]
	v_mfma_f32_16x16x32_bf16 v[14:17], v[200:203], v[184:187], v[14:17]
	v_mfma_f32_16x16x32_bf16 v[10:13], v[208:211], v[184:187], v[10:13]
	v_mfma_f32_16x16x32_bf16 v[6:9], v[200:203], v[192:195], v[6:9]
	v_mfma_f32_16x16x32_bf16 v[2:5], v[208:211], v[192:195], v[2:5]
	v_mfma_f32_16x16x32_bf16 v[46:49], v[204:207], v[168:171], v[46:49]
	v_mfma_f32_16x16x32_bf16 v[42:45], v[212:215], v[168:171], v[42:45]
	v_mfma_f32_16x16x32_bf16 v[30:33], v[204:207], v[180:183], v[30:33]
	v_mfma_f32_16x16x32_bf16 v[26:29], v[212:215], v[180:183], v[26:29]
	v_mfma_f32_16x16x32_bf16 v[14:17], v[204:207], v[188:191], v[14:17]
	v_mfma_f32_16x16x32_bf16 v[10:13], v[212:215], v[188:191], v[10:13]
	v_mfma_f32_16x16x32_bf16 v[6:9], v[204:207], v[196:199], v[6:9]
	v_mfma_f32_16x16x32_bf16 v[2:5], v[212:215], v[196:199], v[2:5]
	s_add_u32 s28, s28, 0x100
	s_addc_u32 s29, s29, 0
	s_add_u32 s37, s37, 0x100
	s_addc_u32 s18, s18, 0
	s_cmp_ge_u32 s95, s38
	s_mov_b32 s19, s95
	s_barrier
	s_cbranch_scc0 .LBB0_544
; DI unsigned pk2(float lo, float hi) { f32x2 f = {lo, hi}; bf2_t v = __builtin_convertvector(f, bf2_t); return __builtin_bit_cast(unsigned, v); }
; #define PG8_WAIT_V(n) asm volatile("s_waitcnt vmcnt(" #n ")" ::: "memory")
; #define PG8_BAR __builtin_amdgcn_s_barrier()
;     DI void operator()(const f32x4 (&acc)[2][2][4][2], const Unit& u, int wr, int wc, int fr, int fq) const {
;         const int row0 = u.pm * BM + wr * 64 + fr; const int col0 = u.pn * BM + wc * 32 + 8 * fq;
; #pragma unroll
;         for (int ai = 0; ai < 2; ++ai)
; #pragma unroll
;             for (int m = 0; m < 4; ++m) { bf16_t* rowp = O + (size_t)(row0 + ai * HALF + m * 16) * ldc + col0;
; #pragma unroll
;                 for (int bj = 0; bj < 2; ++bj) { f32x4 v0 = acc[ai][bj][m][0], v1 = acc[ai][bj][m][1];
;                     if (ACT == 1) {
; #pragma unroll
;                         for (int j = 0; j < 4; ++j) { float a = fmaxf(v0[j], 0.f), b = fmaxf(v1[j], 0.f); v0[j] = a * a; v1[j] = b * b; } }
;                     u32x4 w; w.x = pk2(v0[0], v0[1]); w.y = pk2(v0[2], v0[3]); w.z = pk2(v1[0], v1[1]); w.w = pk2(v1[2], v1[3]);
;                     *(u32x4*)(rowp + bj * HALF) = w; } }
; template <class Epi>
; DI void gemm_phase(int wv, LAS unsigned char* lds, const GemmD g, const Epi& E) {
;     ...
;         E(acc, cur, wr, wc, fr, fq);
;         if (!has_next) break;
; #pragma unroll
;         for (int a = 0; a < 2; ++a)
; #pragma unroll
;             for (int b = 0; b < 2; ++b)
; #pragma unroll
;                 for (int m = 0; m < 4; ++m)
; #pragma unroll
;                     for (int n = 0; n < 2; ++n) acc[a][b][m][n] = (f32x4){0.f, 0.f, 0.f, 0.f};
;         cur = nxt; cA = nA; cB = nB; ++ui;
;     }
;     PG8_WAIT_V(0);
;     if (wr == 0) PG8_BAR;
;     PG8_BAR;
.Lgemm_epi_c:
	v_lshl_add_u32 v146, s8, 8, v140
	v_lshl_or_b32 v148, s12, 8, v143
	v_ashrrev_i32_e32 v147, 31, v146
	v_ashrrev_i32_e32 v149, 31, v148
	v_lshlrev_b64 v[150:151], 11, v[146:147]
	v_lshl_add_u64 v[150:151], s[6:7], 0, v[150:151]
	v_lshlrev_b64 v[148:149], 1, v[148:149]
	v_lshl_add_u64 v[150:151], v[150:151], 0, v[148:149]
	s_mov_b32 s94, 0x40000
	s_mov_b64 s[18:19], 0x40000
	v_cvt_pk_bf16_f32 v62, v62, v63
	v_cvt_pk_bf16_f32 v63, v64, v65
	v_cvt_pk_bf16_f32 v64, v58, v59
	v_add_co_u32_e32 v58, vcc, s94, v150
	v_cvt_pk_bf16_f32 v70, v70, v71
	v_cvt_pk_bf16_f32 v71, v72, v73
	v_cvt_pk_bf16_f32 v72, v66, v67
	v_lshl_add_u64 v[66:67], v[150:151], 0, s[18:19]
	v_addc_co_u32_e32 v59, vcc, 0, v151, vcc
	v_cvt_pk_bf16_f32 v46, v46, v47
	v_cvt_pk_bf16_f32 v47, v48, v49
	v_cvt_pk_bf16_f32 v48, v42, v43
	v_cvt_pk_bf16_f32 v49, v44, v45
	s_mov_b32 s2, 0x48000
	v_cvt_pk_bf16_f32 v110, v110, v111
	v_cvt_pk_bf16_f32 v111, v112, v113
	v_cvt_pk_bf16_f32 v112, v106, v107
	v_or_b32_e32 v106, 16, v146
	global_store_dwordx4 v[66:67], v[46:49], off offset:256
	s_mov_b64 s[18:19], 0x48000
	v_ashrrev_i32_e32 v107, 31, v106
	v_add_co_u32_e32 v48, vcc, s2, v150
	v_cvt_pk_bf16_f32 v94, v94, v95
	v_cvt_pk_bf16_f32 v95, v96, v97
	v_cvt_pk_bf16_f32 v96, v90, v91
	v_or_b32_e32 v90, 32, v146
	v_lshl_add_u64 v[46:47], v[150:151], 0, s[18:19]
	v_addc_co_u32_e32 v49, vcc, 0, v151, vcc
	v_cvt_pk_bf16_f32 v30, v30, v31
	v_cvt_pk_bf16_f32 v31, v32, v33
	v_cvt_pk_bf16_f32 v32, v26, v27
	v_cvt_pk_bf16_f32 v33, v28, v29
	s_mov_b32 s2, 0x50000
	v_lshlrev_b64 v[106:107], 11, v[106:107]
	v_ashrrev_i32_e32 v91, 31, v90
	v_cvt_pk_bf16_f32 v78, v78, v79
	v_cvt_pk_bf16_f32 v79, v80, v81
	v_cvt_pk_bf16_f32 v80, v74, v75
	v_or_b32_e32 v74, 48, v146
	global_store_dwordx4 v[46:47], v[30:33], off offset:256
	s_mov_b64 s[18:19], 0x50000
	v_cvt_pk_bf16_f32 v113, v108, v109
	v_add_co_u32_e32 v32, vcc, s2, v150
	v_lshl_add_u64 v[106:107], s[6:7], 0, v[106:107]
	v_lshlrev_b64 v[90:91], 11, v[90:91]
	v_ashrrev_i32_e32 v75, 31, v74
	v_lshl_add_u64 v[30:31], v[150:151], 0, s[18:19]
	v_addc_co_u32_e32 v33, vcc, 0, v151, vcc
	v_cvt_pk_bf16_f32 v14, v14, v15
	v_cvt_pk_bf16_f32 v15, v16, v17
	v_cvt_pk_bf16_f32 v16, v10, v11
	v_cvt_pk_bf16_f32 v17, v12, v13
	s_mov_b32 s2, 0x58000
	global_store_dwordx4 v[150:151], v[110:113], off offset:256
	v_cvt_pk_bf16_f32 v97, v92, v93
	v_lshl_add_u64 v[90:91], s[6:7], 0, v[90:91]
	v_lshl_add_u64 v[110:111], v[106:107], 0, v[148:149]
	v_lshlrev_b64 v[74:75], 11, v[74:75]
	global_store_dwordx4 v[30:31], v[14:17], off offset:256
	global_store_dwordx4 v[110:111], v[94:97], off offset:256
	v_cvt_pk_bf16_f32 v81, v76, v77
	v_add_co_u32_e32 v16, vcc, s2, v150
	v_lshl_add_u64 v[94:95], v[90:91], 0, v[148:149]
	v_lshl_add_u64 v[74:75], s[6:7], 0, v[74:75]
	s_mov_b64 s[18:19], 0x58000
	v_addc_co_u32_e32 v17, vcc, 0, v151, vcc
	v_cvt_pk_bf16_f32 v126, v126, v127
	v_cvt_pk_bf16_f32 v127, v128, v129
	v_cvt_pk_bf16_f32 v128, v122, v123
	v_cvt_pk_bf16_f32 v129, v124, v125
	v_cvt_pk_bf16_f32 v106, v118, v119
	v_cvt_pk_bf16_f32 v107, v120, v121
	v_cvt_pk_bf16_f32 v108, v114, v115
	v_cvt_pk_bf16_f32 v109, v116, v117
	v_cvt_pk_bf16_f32 v90, v102, v103
	v_cvt_pk_bf16_f32 v91, v104, v105
	v_cvt_pk_bf16_f32 v92, v98, v99
	v_cvt_pk_bf16_f32 v93, v100, v101
	global_store_dwordx4 v[94:95], v[78:81], off offset:256
	v_cvt_pk_bf16_f32 v76, v82, v83
	v_cvt_pk_bf16_f32 v77, v84, v85
	v_lshl_add_u64 v[78:79], v[74:75], 0, v[148:149]
	v_cvt_pk_bf16_f32 v74, v86, v87
	v_cvt_pk_bf16_f32 v75, v88, v89
	v_cvt_pk_bf16_f32 v73, v68, v69
	v_cvt_pk_bf16_f32 v65, v60, v61
	v_cvt_pk_bf16_f32 v42, v54, v55
	v_cvt_pk_bf16_f32 v43, v56, v57
	v_cvt_pk_bf16_f32 v44, v50, v51
	v_cvt_pk_bf16_f32 v45, v52, v53
	v_cvt_pk_bf16_f32 v26, v38, v39
	v_cvt_pk_bf16_f32 v27, v40, v41
	v_cvt_pk_bf16_f32 v28, v34, v35
	v_cvt_pk_bf16_f32 v29, v36, v37
	v_lshl_add_u64 v[14:15], v[150:151], 0, s[18:19]
	v_cvt_pk_bf16_f32 v10, v22, v23
	v_cvt_pk_bf16_f32 v11, v24, v25
	v_cvt_pk_bf16_f32 v12, v18, v19
	v_cvt_pk_bf16_f32 v13, v20, v21
	v_cvt_pk_bf16_f32 v6, v6, v7
	v_cvt_pk_bf16_f32 v7, v8, v9
	v_cvt_pk_bf16_f32 v8, v2, v3
	v_cvt_pk_bf16_f32 v9, v4, v5
	s_and_b64 vcc, exec, s[0:1]
	s_mov_b32 s12, s55
	s_mov_b32 s8, s22
	s_mov_b64 s[30:31], s[26:27]
	s_mov_b64 s[28:29], s[24:25]
	global_store_dwordx4 v[150:151], v[126:129], off
	global_store_dwordx4 v[110:111], v[106:109], off
	global_store_dwordx4 v[94:95], v[90:93], off
	global_store_dwordx4 v[78:79], v[74:77], off
	global_store_dwordx4 v[78:79], v[70:73], off offset:256
	global_store_dwordx4 v[58:59], v[62:65], off
	global_store_dwordx4 v[48:49], v[42:45], off
	global_store_dwordx4 v[32:33], v[26:29], off
	global_store_dwordx4 v[16:17], v[10:13], off
	global_store_dwordx4 v[14:15], v[6:9], off offset:256
	s_cbranch_vccz .LBB0_537
	s_waitcnt vmcnt(0)
	s_setprio 0
	s_cmpk_gt_u32 s78, 0xff
	s_cbranch_scc1 .LBB0_548
	s_barrier
